# v55 + waves 0-3 wait for their LDS-DMA slices after the MFMA block (one barrier interval later)
# speedup vs baseline: 1.1518x; 1.0007x over previous
.LBB0_250:
	s_lshr_b32 s0, s75, 1
	s_lshl_b32 s42, s75, 3
	v_writelane_b32 v254, s0, 27
	s_and_b32 s0, s75, 1
	s_cmp_eq_u32 s0, 0
	s_cselect_b64 s[4:5], -1, 0
	v_writelane_b32 v254, s4, 16
	s_cmp_eq_u32 s0, 1
	s_cselect_b64 s[0:1], -1, 0
	v_writelane_b32 v254, s5, 17
	v_writelane_b32 v254, s0, 24
	s_nop 1
	v_writelane_b32 v254, s1, 25
	s_or_b32 s0, s42, 4
	v_readlane_b32 s4, v254, 1
	v_readlane_b32 s5, v254, 2
	s_mov_b64 s[8:9], s[4:5]
	s_cmp_le_i32 s8, s0
	v_readlane_b32 s6, v254, 3
	v_readlane_b32 s7, v254, 4
	s_cselect_b64 s[4:5], -1, 0
	s_cmp_lt_i32 s0, s9
	s_cselect_b64 s[6:7], -1, 0
	s_and_b64 s[4:5], s[4:5], s[6:7]
	s_andn2_b64 vcc, exec, s[4:5]
	s_cbranch_vccnz .LBB0_312
	v_mov_b32_e32 v1, v0
	s_mov_b32 s4, 19
	s_ashr_i32 s5, s4, 31
	s_lshl_b64 s[4:5], s[4:5], 3
	v_readlane_b32 s0, v254, 7
	v_readlane_b32 s1, v254, 8
	s_add_u32 s4, s0, s4
	s_addc_u32 s5, s1, s5
	s_load_dwordx2 s[6:7], s[4:5], 0x0
	v_readlane_b32 s0, v254, 24
	v_readlane_b32 s1, v254, 25
	s_mov_b64 s[4:5], -1
	s_waitcnt lgkmcnt(0)
	s_add_u32 s79, s6, 0x1b000000
	s_addc_u32 s28, s7, 0
	s_add_u32 s52, s6, 0x23000000
	s_addc_u32 s53, s7, 0
	s_and_b64 vcc, exec, s[0:1]
	s_cbranch_vccz .LBB0_275
	v_readlane_b32 s0, v254, 29
	v_readlane_b32 s1, v254, 30
	s_andn2_b64 vcc, exec, s[0:1]
	v_readfirstlane_b32 s38, v1
	s_cbranch_vccnz .LBB0_274
	v_lshlrev_b32_e32 v13, 4, v1
	v_add_u32_e32 v2, 0x2000, v13
	v_ashrrev_i32_e32 v3, 31, v2
	v_lshrrev_b32_e32 v3, 22, v3
	v_add_u32_e32 v3, v2, v3
	v_ashrrev_i32_e32 v10, 10, v3
	v_mul_i32_i24_e32 v4, 0x400, v10
	v_sub_u32_e32 v2, v2, v4
	v_lshrrev_b32_e32 v4, 4, v2
	v_bitop3_b32 v2, v4, v2, 32 bitop3:0x6c
	v_ashrrev_i32_e32 v4, 31, v2
	v_lshrrev_b32_e32 v4, 26, v4
	v_add_u32_e32 v4, v2, v4
	v_ashrrev_i32_e32 v11, 6, v4
	v_and_b32_e32 v4, 0xc0, v4
	v_sub_u32_e32 v2, v2, v4
	v_lshlrev_b32_e32 v3, 5, v10
	v_ashrrev_i16_sdwa v2, v233, sext(v2) dst_sel:DWORD dst_unused:UNUSED_PAD src0_sel:DWORD src1_sel:BYTE_0
	v_and_b32_e32 v3, 32, v3
	v_bfe_i32 v12, v2, 0, 16
	v_add_u32_e32 v2, v3, v12
	v_lshlrev_b32_e32 v3, 3, v10
	v_and_b32_e32 v3, 0xffff0, v3
	v_add_lshl_u32 v3, v11, v3, 12
	v_lshl_add_u32 v130, v2, 1, v3
	v_bfe_i32 v3, v1, 27, 1
	v_lshrrev_b32_e32 v3, 22, v3
	v_add_u32_e32 v3, v13, v3
	v_and_b32_e32 v3, 0xfffffc00, v3
	v_sub_u32_e32 v3, v13, v3
	v_lshrrev_b32_e32 v4, 4, v3
	v_bitop3_b32 v3, v4, v3, 32 bitop3:0x6c
	v_readlane_b32 s1, v254, 27
	v_ashrrev_i32_e32 v4, 31, v3
	s_mul_hi_u32 s0, s1, 0x1800000
	s_mul_i32 s1, s1, 0x1800000
	v_lshrrev_b32_e32 v4, 26, v4
	s_add_u32 s1, s6, s1
	v_ashrrev_i32_e32 v2, 31, v1
	v_add_u32_e32 v4, v3, v4
	s_addc_u32 s0, s7, s0
	v_lshrrev_b32_e32 v2, 26, v2
	v_ashrrev_i32_e32 v15, 6, v4
	v_and_b32_e32 v4, 0xc0, v4
	s_add_u32 s8, s1, 0x6800000
	v_add_u32_e32 v2, v1, v2
	v_sub_u32_e32 v3, v3, v4
	s_addc_u32 s9, s0, 0
	s_ashr_i32 s33, s38, 6
	v_ashrrev_i32_e32 v14, 6, v2
	v_ashrrev_i16_sdwa v3, v233, sext(v3) dst_sel:DWORD dst_unused:UNUSED_PAD src0_sel:DWORD src1_sel:BYTE_0
	s_ashr_i32 s36, s38, 8
	s_ashr_i32 s98, s38, 8
	s_lshl_b32 s20, s33, 10
	v_lshlrev_b32_e32 v2, 5, v14
	v_bfe_i32 v16, v3, 0, 16
	v_lshlrev_b32_e32 v3, 3, v14
	v_readlane_b32 s0, v254, 56
	v_and_b32_e32 v2, 32, v2
	v_and_b32_e32 v3, 0xffff0, v3
	v_readlane_b32 s1, v254, 57
	s_add_u32 s84, s8, s0
	v_add_u32_e32 v2, v2, v16
	v_add_lshl_u32 v3, v15, v3, 12
	s_addc_u32 s85, s9, s1
	s_add_i32 s21, s20, 0
	v_lshl_add_u32 v132, v2, 1, v3
	s_add_i32 m0, s21, 0x10000
	v_readlane_b32 s0, v254, 54
	global_load_lds_dwordx4 v132, s[84:85]
	s_add_i32 m0, s21, 0x12000
	s_add_u32 s4, s84, 0x80000
	global_load_lds_dwordx4 v130, s[84:85]
	s_addc_u32 s5, s85, 0
	s_add_i32 m0, s21, 0x14000
	v_readlane_b32 s1, v254, 55
	global_load_lds_dwordx4 v132, s[4:5]
	s_add_i32 m0, s21, 0x16000
	s_add_u32 s76, s79, s0
	s_addc_u32 s77, s28, s1
	s_add_i32 s26, s21, 0x2000
	global_load_lds_dwordx4 v130, s[4:5]
	s_mov_b32 m0, s21
	s_add_u32 s4, s76, 0x80000
	global_load_lds_dwordx4 v132, s[76:77]
	s_mov_b32 m0, s26
	s_addc_u32 s5, s77, 0
	s_add_i32 s27, s21, 0x4000
	global_load_lds_dwordx4 v130, s[76:77]
	s_mov_b32 m0, s27
	s_add_i32 s29, s21, 0x6000
	global_load_lds_dwordx4 v132, s[4:5]
	s_mov_b32 m0, s29
	v_mov_b32_e32 v133, v195
	global_load_lds_dwordx4 v130, s[4:5]
	v_mov_b32_e32 v131, v195
	s_cmp_eq_u32 s36, 1
	v_lshl_add_u64 v[8:9], s[84:85], 0, v[132:133]
	v_lshl_add_u64 v[6:7], s[84:85], 0, v[130:131]
	v_lshl_add_u64 v[2:3], s[76:77], 0, v[132:133]
	s_cselect_b64 s[10:11], -1, 0
	s_cmp_lg_u32 s36, 1
	v_lshl_add_u64 v[4:5], s[76:77], 0, v[130:131]
	s_cbranch_scc1 .LBB0_255
	s_barrier

.Lpeel_disp_ine:
	s_cmp_lg_u32 s65, -2
	s_cbranch_scc1 .Llw_main_ine
	s_cmp_eq_u32 s98, 0
	s_cbranch_scc1 .Llw_p0_ine
	s_add_u32 s0, s76, 0xfff80080
	s_addc_u32 s1, s77, -1
	s_and_b64 s[84:85], s[84:85], exec
	s_cselect_b32 vcc_hi, s22, s1
	s_cselect_b32 vcc_lo, s23, s0
	s_cselect_b32 s85, s49, s58
	s_cselect_b32 s84, s57, s51
	s_add_i32 s0, 0, 0x10000
	s_add_i32 s1, 0, 0x14000
	v_add_u32_e32 v158, s0, v176
	v_add_u32_e32 v174, s1, v176
	ds_read_b128 v[146:149], v158
	ds_read_b128 v[150:153], v158 offset:1024
	ds_read_b128 v[154:157], v158 offset:2048
	ds_read_b128 v[158:161], v158 offset:3072
	ds_read_b128 v[162:165], v174
	ds_read_b128 v[166:169], v174 offset:1024
	ds_read_b128 v[170:173], v174 offset:2048
	ds_read_b128 v[178:181], v174 offset:3072
	s_add_i32 m0, s21, 0xc000
	ds_read_b128 v[182:185], v177
	ds_read_b128 v[186:189], v177 offset:1024
	ds_read_b128 v[190:193], v177 offset:2048
	ds_read_b128 v[204:207], v177 offset:3072
	ds_read_b128 v[208:211], v177 offset:4096
	ds_read_b128 v[212:215], v177 offset:5120
	ds_read_b128 v[216:219], v177 offset:6144
	ds_read_b128 v[220:223], v177 offset:7168
	global_load_lds_dwordx4 v138, s[76:77]
	s_add_i32 m0, s21, 0xe000
	s_nop 0
	global_load_lds_dwordx4 v140, s[76:77]
	s_waitcnt vmcnt(8)
	s_waitcnt lgkmcnt(0)
	s_barrier
	s_waitcnt lgkmcnt(0)
	v_mfma_f32_16x16x32_bf16 v[126:129], v[146:149], v[182:185], 0
	v_mfma_f32_16x16x32_bf16 v[126:129], v[150:153], v[186:189], v[126:129]
	v_mfma_f32_16x16x32_bf16 v[122:125], v[158:161], v[186:189], 0
	v_mfma_f32_16x16x32_bf16 v[122:125], v[154:157], v[182:185], v[122:125]
	v_mfma_f32_16x16x32_bf16 v[118:121], v[162:165], v[182:185], 0
	v_mfma_f32_16x16x32_bf16 v[118:121], v[166:169], v[186:189], v[118:121]
	v_mfma_f32_16x16x32_bf16 v[114:117], v[178:181], v[186:189], 0
	v_mfma_f32_16x16x32_bf16 v[114:117], v[170:173], v[182:185], v[114:117]
	v_mfma_f32_16x16x32_bf16 v[98:101], v[170:173], v[190:193], 0
	v_mfma_f32_16x16x32_bf16 v[98:101], v[178:181], v[204:207], v[98:101]
	v_mfma_f32_16x16x32_bf16 v[102:105], v[166:169], v[204:207], 0
	v_mfma_f32_16x16x32_bf16 v[102:105], v[162:165], v[190:193], v[102:105]
	v_mfma_f32_16x16x32_bf16 v[106:109], v[154:157], v[190:193], 0
	v_mfma_f32_16x16x32_bf16 v[106:109], v[158:161], v[204:207], v[106:109]
	v_mfma_f32_16x16x32_bf16 v[110:113], v[150:153], v[204:207], 0
	v_mfma_f32_16x16x32_bf16 v[110:113], v[146:149], v[190:193], v[110:113]
	v_mfma_f32_16x16x32_bf16 v[94:97], v[146:149], v[208:211], 0
	v_mfma_f32_16x16x32_bf16 v[94:97], v[150:153], v[212:215], v[94:97]
	v_mfma_f32_16x16x32_bf16 v[90:93], v[158:161], v[212:215], 0
	v_mfma_f32_16x16x32_bf16 v[90:93], v[154:157], v[208:211], v[90:93]
	v_mfma_f32_16x16x32_bf16 v[86:89], v[162:165], v[208:211], 0
	v_mfma_f32_16x16x32_bf16 v[86:89], v[166:169], v[212:215], v[86:89]
	v_mfma_f32_16x16x32_bf16 v[82:85], v[178:181], v[212:215], 0
	v_mfma_f32_16x16x32_bf16 v[82:85], v[170:173], v[208:211], v[82:85]
	v_mfma_f32_16x16x32_bf16 v[66:69], v[170:173], v[216:219], 0
	v_mfma_f32_16x16x32_bf16 v[66:69], v[178:181], v[220:223], v[66:69]
	v_mfma_f32_16x16x32_bf16 v[70:73], v[166:169], v[220:223], 0
	v_mfma_f32_16x16x32_bf16 v[70:73], v[162:165], v[216:219], v[70:73]
	v_mfma_f32_16x16x32_bf16 v[74:77], v[154:157], v[216:219], 0
	v_mfma_f32_16x16x32_bf16 v[74:77], v[158:161], v[220:223], v[74:77]
	v_mfma_f32_16x16x32_bf16 v[78:81], v[150:153], v[220:223], 0
	v_mfma_f32_16x16x32_bf16 v[78:81], v[146:149], v[216:219], v[78:81]
	s_barrier
	s_add_i32 s0, s0, s20
	s_mov_b32 m0, s0
	ds_read_b128 v[182:185], v177 offset:16384
	ds_read_b128 v[186:189], v177 offset:17408
	ds_read_b128 v[190:193], v177 offset:18432
	ds_read_b128 v[204:207], v177 offset:19456
	ds_read_b128 v[208:211], v177 offset:20480
	ds_read_b128 v[212:215], v177 offset:21504
	ds_read_b128 v[216:219], v177 offset:22528
	ds_read_b128 v[220:223], v177 offset:23552
	global_load_lds_dwordx4 v132, s[84:85]
	s_add_i32 m0, s0, 0x2000
	s_add_u32 s94, s84, 0x80000
	s_addc_u32 s95, s85, 0
	s_add_i32 s0, s1, s20
	global_load_lds_dwordx4 v130, s[84:85]
	s_mov_b32 m0, s0
	s_nop 0
	global_load_lds_dwordx4 v132, s[94:95]
	s_add_i32 m0, s0, 0x2000
	s_nop 0
	global_load_lds_dwordx4 v130, s[94:95]
	s_mov_b32 m0, s21
	s_nop 0
	global_load_lds_dwordx4 v132, vcc
	s_mov_b32 m0, s26
	s_nop 0
	global_load_lds_dwordx4 v130, vcc
	s_waitcnt vmcnt(8)
	s_waitcnt lgkmcnt(0)
	s_barrier
	s_waitcnt lgkmcnt(0)
	v_mfma_f32_16x16x32_bf16 v[62:65], v[146:149], v[182:185], 0
	v_mfma_f32_16x16x32_bf16 v[62:65], v[150:153], v[186:189], v[62:65]
	v_mfma_f32_16x16x32_bf16 v[58:61], v[158:161], v[186:189], 0
	v_mfma_f32_16x16x32_bf16 v[58:61], v[154:157], v[182:185], v[58:61]
	v_mfma_f32_16x16x32_bf16 v[54:57], v[162:165], v[182:185], 0
	v_mfma_f32_16x16x32_bf16 v[54:57], v[166:169], v[186:189], v[54:57]
	v_mfma_f32_16x16x32_bf16 v[50:53], v[178:181], v[186:189], 0
	v_mfma_f32_16x16x32_bf16 v[50:53], v[170:173], v[182:185], v[50:53]
	v_mfma_f32_16x16x32_bf16 v[34:37], v[170:173], v[190:193], 0
	v_mfma_f32_16x16x32_bf16 v[34:37], v[178:181], v[204:207], v[34:37]
	v_mfma_f32_16x16x32_bf16 v[38:41], v[166:169], v[204:207], 0
	v_mfma_f32_16x16x32_bf16 v[38:41], v[162:165], v[190:193], v[38:41]
	v_mfma_f32_16x16x32_bf16 v[42:45], v[154:157], v[190:193], 0
	v_mfma_f32_16x16x32_bf16 v[42:45], v[158:161], v[204:207], v[42:45]
	v_mfma_f32_16x16x32_bf16 v[46:49], v[150:153], v[204:207], 0
	v_mfma_f32_16x16x32_bf16 v[46:49], v[146:149], v[190:193], v[46:49]
	v_mfma_f32_16x16x32_bf16 v[30:33], v[146:149], v[208:211], 0
	v_mfma_f32_16x16x32_bf16 v[30:33], v[150:153], v[212:215], v[30:33]
	v_mfma_f32_16x16x32_bf16 v[26:29], v[158:161], v[212:215], 0
	v_mfma_f32_16x16x32_bf16 v[26:29], v[154:157], v[208:211], v[26:29]
	v_mfma_f32_16x16x32_bf16 v[22:25], v[162:165], v[208:211], 0
	v_mfma_f32_16x16x32_bf16 v[22:25], v[166:169], v[212:215], v[22:25]
	v_mfma_f32_16x16x32_bf16 v[18:21], v[178:181], v[212:215], 0
	v_mfma_f32_16x16x32_bf16 v[18:21], v[170:173], v[208:211], v[18:21]
	v_mfma_f32_16x16x32_bf16 v[2:5], v[170:173], v[216:219], 0
	v_mfma_f32_16x16x32_bf16 v[2:5], v[178:181], v[220:223], v[2:5]
	v_mfma_f32_16x16x32_bf16 v[6:9], v[166:169], v[220:223], 0
	v_mfma_f32_16x16x32_bf16 v[6:9], v[162:165], v[216:219], v[6:9]
	v_mfma_f32_16x16x32_bf16 v[10:13], v[154:157], v[216:219], 0
	v_mfma_f32_16x16x32_bf16 v[10:13], v[158:161], v[220:223], v[10:13]
	v_mfma_f32_16x16x32_bf16 v[14:17], v[150:153], v[220:223], 0
	v_mfma_f32_16x16x32_bf16 v[14:17], v[146:149], v[216:219], v[14:17]
	s_barrier
	s_add_i32 s0, 0, 0x18000
	s_add_i32 s1, 0, 0x1c000
	v_add_u32_e32 v158, s0, v176
	v_add_u32_e32 v178, s1, v176
	ds_read_b128 v[146:149], v158
	ds_read_b128 v[150:153], v158 offset:1024
	ds_read_b128 v[154:157], v158 offset:2048
	ds_read_b128 v[158:161], v158 offset:3072
	ds_read_b128 v[162:165], v178
	ds_read_b128 v[166:169], v178 offset:1024
	ds_read_b128 v[170:173], v178 offset:2048
	ds_read_b128 v[178:181], v178 offset:3072
	s_add_u32 s94, vcc_lo, 0x80000
	s_addc_u32 s95, vcc_hi, 0
	s_mov_b32 m0, s27
	ds_read_b128 v[182:185], v177 offset:32768
	ds_read_b128 v[186:189], v177 offset:33792
	ds_read_b128 v[190:193], v177 offset:34816
	ds_read_b128 v[204:207], v177 offset:35840
	ds_read_b128 v[208:211], v177 offset:36864
	ds_read_b128 v[212:215], v177 offset:37888
	ds_read_b128 v[216:219], v177 offset:38912
	ds_read_b128 v[220:223], v177 offset:39936
	global_load_lds_dwordx4 v132, s[94:95]
	s_mov_b32 m0, s29
	s_nop 0
	global_load_lds_dwordx4 v130, s[94:95]
	s_waitcnt vmcnt(8)
	s_waitcnt lgkmcnt(0)
	s_barrier
	s_waitcnt lgkmcnt(0)
	v_mfma_f32_16x16x32_bf16 v[126:129], v[146:149], v[182:185], v[126:129]
	v_mfma_f32_16x16x32_bf16 v[126:129], v[150:153], v[186:189], v[126:129]
	v_mfma_f32_16x16x32_bf16 v[122:125], v[158:161], v[186:189], v[122:125]
	v_mfma_f32_16x16x32_bf16 v[122:125], v[154:157], v[182:185], v[122:125]
	v_mfma_f32_16x16x32_bf16 v[118:121], v[162:165], v[182:185], v[118:121]
	v_mfma_f32_16x16x32_bf16 v[118:121], v[166:169], v[186:189], v[118:121]
	v_mfma_f32_16x16x32_bf16 v[114:117], v[178:181], v[186:189], v[114:117]
	v_mfma_f32_16x16x32_bf16 v[114:117], v[170:173], v[182:185], v[114:117]
	v_mfma_f32_16x16x32_bf16 v[98:101], v[170:173], v[190:193], v[98:101]
	v_mfma_f32_16x16x32_bf16 v[98:101], v[178:181], v[204:207], v[98:101]
	v_mfma_f32_16x16x32_bf16 v[102:105], v[166:169], v[204:207], v[102:105]
	v_mfma_f32_16x16x32_bf16 v[102:105], v[162:165], v[190:193], v[102:105]
	v_mfma_f32_16x16x32_bf16 v[106:109], v[154:157], v[190:193], v[106:109]
	v_mfma_f32_16x16x32_bf16 v[106:109], v[158:161], v[204:207], v[106:109]
	v_mfma_f32_16x16x32_bf16 v[110:113], v[150:153], v[204:207], v[110:113]
	v_mfma_f32_16x16x32_bf16 v[110:113], v[146:149], v[190:193], v[110:113]
	v_mfma_f32_16x16x32_bf16 v[94:97], v[146:149], v[208:211], v[94:97]
	v_mfma_f32_16x16x32_bf16 v[94:97], v[150:153], v[212:215], v[94:97]
	v_mfma_f32_16x16x32_bf16 v[90:93], v[158:161], v[212:215], v[90:93]
	v_mfma_f32_16x16x32_bf16 v[90:93], v[154:157], v[208:211], v[90:93]
	v_mfma_f32_16x16x32_bf16 v[86:89], v[162:165], v[208:211], v[86:89]
	v_mfma_f32_16x16x32_bf16 v[86:89], v[166:169], v[212:215], v[86:89]
	v_mfma_f32_16x16x32_bf16 v[82:85], v[178:181], v[212:215], v[82:85]
	v_mfma_f32_16x16x32_bf16 v[82:85], v[170:173], v[208:211], v[82:85]
	v_mfma_f32_16x16x32_bf16 v[66:69], v[170:173], v[216:219], v[66:69]
	v_mfma_f32_16x16x32_bf16 v[66:69], v[178:181], v[220:223], v[66:69]
	v_mfma_f32_16x16x32_bf16 v[70:73], v[166:169], v[220:223], v[70:73]
	v_mfma_f32_16x16x32_bf16 v[70:73], v[162:165], v[216:219], v[70:73]
	v_mfma_f32_16x16x32_bf16 v[74:77], v[154:157], v[216:219], v[74:77]
	v_mfma_f32_16x16x32_bf16 v[74:77], v[158:161], v[220:223], v[74:77]
	v_mfma_f32_16x16x32_bf16 v[78:81], v[150:153], v[220:223], v[78:81]
	v_mfma_f32_16x16x32_bf16 v[78:81], v[146:149], v[216:219], v[78:81]
	s_barrier
	s_add_u32 s98, s84, 0x80
	s_addc_u32 s99, s85, 0
	s_add_u32 s100, vcc_lo, 0x80
	s_addc_u32 s101, vcc_hi, 0
	s_add_i32 s0, s0, s20
	s_mov_b32 m0, s0
	ds_read_b128 v[182:185], v177 offset:49152
	ds_read_b128 v[186:189], v177 offset:50176
	ds_read_b128 v[190:193], v177 offset:51200
	ds_read_b128 v[204:207], v177 offset:52224
	ds_read_b128 v[208:211], v177 offset:53248
	ds_read_b128 v[212:215], v177 offset:54272
	ds_read_b128 v[216:219], v177 offset:55296
	ds_read_b128 v[220:223], v177 offset:56320
	global_load_lds_dwordx4 v132, s[98:99]
	s_add_i32 m0, s0, 0x2000
	s_add_u32 s84, s84, 0x80080
	s_addc_u32 s85, s85, 0
	s_add_i32 s0, s1, s20
	global_load_lds_dwordx4 v130, s[98:99]
	s_mov_b32 m0, s0
	s_nop 0
	global_load_lds_dwordx4 v132, s[84:85]
	s_add_i32 m0, s0, 0x2000
	s_nop 0
	global_load_lds_dwordx4 v130, s[84:85]
	s_mov_b32 m0, s40
	s_nop 0
	global_load_lds_dwordx4 v132, s[100:101]
	s_mov_b32 m0, s41
	s_nop 0
	global_load_lds_dwordx4 v130, s[100:101]
	s_waitcnt vmcnt(8)
	s_waitcnt lgkmcnt(0)
	s_barrier
	s_waitcnt lgkmcnt(0)
	v_mfma_f32_16x16x32_bf16 v[62:65], v[146:149], v[182:185], v[62:65]
	v_mfma_f32_16x16x32_bf16 v[62:65], v[150:153], v[186:189], v[62:65]
	v_mfma_f32_16x16x32_bf16 v[58:61], v[158:161], v[186:189], v[58:61]
	v_mfma_f32_16x16x32_bf16 v[58:61], v[154:157], v[182:185], v[58:61]
	v_mfma_f32_16x16x32_bf16 v[54:57], v[162:165], v[182:185], v[54:57]
	v_mfma_f32_16x16x32_bf16 v[54:57], v[166:169], v[186:189], v[54:57]
	v_mfma_f32_16x16x32_bf16 v[50:53], v[178:181], v[186:189], v[50:53]
	v_mfma_f32_16x16x32_bf16 v[50:53], v[170:173], v[182:185], v[50:53]
	v_mfma_f32_16x16x32_bf16 v[34:37], v[170:173], v[190:193], v[34:37]
	v_mfma_f32_16x16x32_bf16 v[34:37], v[178:181], v[204:207], v[34:37]
	v_mfma_f32_16x16x32_bf16 v[38:41], v[166:169], v[204:207], v[38:41]
	v_mfma_f32_16x16x32_bf16 v[38:41], v[162:165], v[190:193], v[38:41]
	v_mfma_f32_16x16x32_bf16 v[42:45], v[154:157], v[190:193], v[42:45]
	v_mfma_f32_16x16x32_bf16 v[42:45], v[158:161], v[204:207], v[42:45]
	v_mfma_f32_16x16x32_bf16 v[46:49], v[150:153], v[204:207], v[46:49]
	v_mfma_f32_16x16x32_bf16 v[46:49], v[146:149], v[190:193], v[46:49]
	v_mfma_f32_16x16x32_bf16 v[30:33], v[146:149], v[208:211], v[30:33]
	v_mfma_f32_16x16x32_bf16 v[30:33], v[150:153], v[212:215], v[30:33]
	v_mfma_f32_16x16x32_bf16 v[26:29], v[158:161], v[212:215], v[26:29]
	v_mfma_f32_16x16x32_bf16 v[26:29], v[154:157], v[208:211], v[26:29]
	v_mfma_f32_16x16x32_bf16 v[22:25], v[162:165], v[208:211], v[22:25]
	v_mfma_f32_16x16x32_bf16 v[22:25], v[166:169], v[212:215], v[22:25]
	v_mfma_f32_16x16x32_bf16 v[18:21], v[178:181], v[212:215], v[18:21]
	v_mfma_f32_16x16x32_bf16 v[18:21], v[170:173], v[208:211], v[18:21]
	v_mfma_f32_16x16x32_bf16 v[2:5], v[170:173], v[216:219], v[2:5]
	v_mfma_f32_16x16x32_bf16 v[2:5], v[178:181], v[220:223], v[2:5]
	v_mfma_f32_16x16x32_bf16 v[6:9], v[166:169], v[220:223], v[6:9]
	v_mfma_f32_16x16x32_bf16 v[6:9], v[162:165], v[216:219], v[6:9]
	v_mfma_f32_16x16x32_bf16 v[10:13], v[154:157], v[216:219], v[10:13]
	v_mfma_f32_16x16x32_bf16 v[10:13], v[158:161], v[220:223], v[10:13]
	v_mfma_f32_16x16x32_bf16 v[14:17], v[150:153], v[220:223], v[14:17]
	v_mfma_f32_16x16x32_bf16 v[14:17], v[146:149], v[216:219], v[14:17]
	s_barrier
	s_add_i32 s65, s65, 2
	s_add_u32 s76, s76, 0x100
	s_addc_u32 s77, s77, 0
	s_add_u32 s51, s51, 0x100
	s_addc_u32 s58, s58, 0
	s_cmp_gt_u32 s65, 29
	s_cbranch_scc1 .LBB0_264
	s_branch .LBB0_262
.Llw_p0_ine:
	s_add_u32 s0, s76, 0xfff80080
	s_addc_u32 s1, s77, -1
	s_and_b64 s[84:85], s[84:85], exec
	s_cselect_b32 vcc_hi, s22, s1
	s_cselect_b32 vcc_lo, s23, s0
	s_cselect_b32 s85, s49, s58
	s_cselect_b32 s84, s57, s51
	s_add_i32 s0, 0, 0x10000
	s_add_i32 s1, 0, 0x14000
	v_add_u32_e32 v158, s0, v176
	v_add_u32_e32 v174, s1, v176
	ds_read_b128 v[146:149], v158
	ds_read_b128 v[150:153], v158 offset:1024
	ds_read_b128 v[154:157], v158 offset:2048
	ds_read_b128 v[158:161], v158 offset:3072
	ds_read_b128 v[162:165], v174
	ds_read_b128 v[166:169], v174 offset:1024
	ds_read_b128 v[170:173], v174 offset:2048
	ds_read_b128 v[178:181], v174 offset:3072
	s_add_i32 m0, s21, 0xc000
	ds_read_b128 v[182:185], v177
	ds_read_b128 v[186:189], v177 offset:1024
	ds_read_b128 v[190:193], v177 offset:2048
	ds_read_b128 v[204:207], v177 offset:3072
	ds_read_b128 v[208:211], v177 offset:4096
	ds_read_b128 v[212:215], v177 offset:5120
	ds_read_b128 v[216:219], v177 offset:6144
	ds_read_b128 v[220:223], v177 offset:7168
	global_load_lds_dwordx4 v138, s[76:77]
	s_add_i32 m0, s21, 0xe000
	s_nop 0
	global_load_lds_dwordx4 v140, s[76:77]
	s_waitcnt lgkmcnt(0)
	s_barrier
	s_waitcnt lgkmcnt(0)
	v_mfma_f32_16x16x32_bf16 v[126:129], v[146:149], v[182:185], 0
	v_mfma_f32_16x16x32_bf16 v[126:129], v[150:153], v[186:189], v[126:129]
	v_mfma_f32_16x16x32_bf16 v[122:125], v[158:161], v[186:189], 0
	v_mfma_f32_16x16x32_bf16 v[122:125], v[154:157], v[182:185], v[122:125]
	v_mfma_f32_16x16x32_bf16 v[118:121], v[162:165], v[182:185], 0
	v_mfma_f32_16x16x32_bf16 v[118:121], v[166:169], v[186:189], v[118:121]
	v_mfma_f32_16x16x32_bf16 v[114:117], v[178:181], v[186:189], 0
	v_mfma_f32_16x16x32_bf16 v[114:117], v[170:173], v[182:185], v[114:117]
	v_mfma_f32_16x16x32_bf16 v[98:101], v[170:173], v[190:193], 0
	v_mfma_f32_16x16x32_bf16 v[98:101], v[178:181], v[204:207], v[98:101]
	v_mfma_f32_16x16x32_bf16 v[102:105], v[166:169], v[204:207], 0
	v_mfma_f32_16x16x32_bf16 v[102:105], v[162:165], v[190:193], v[102:105]
	v_mfma_f32_16x16x32_bf16 v[106:109], v[154:157], v[190:193], 0
	v_mfma_f32_16x16x32_bf16 v[106:109], v[158:161], v[204:207], v[106:109]
	v_mfma_f32_16x16x32_bf16 v[110:113], v[150:153], v[204:207], 0
	v_mfma_f32_16x16x32_bf16 v[110:113], v[146:149], v[190:193], v[110:113]
	v_mfma_f32_16x16x32_bf16 v[94:97], v[146:149], v[208:211], 0
	v_mfma_f32_16x16x32_bf16 v[94:97], v[150:153], v[212:215], v[94:97]
	v_mfma_f32_16x16x32_bf16 v[90:93], v[158:161], v[212:215], 0
	v_mfma_f32_16x16x32_bf16 v[90:93], v[154:157], v[208:211], v[90:93]
	v_mfma_f32_16x16x32_bf16 v[86:89], v[162:165], v[208:211], 0
	v_mfma_f32_16x16x32_bf16 v[86:89], v[166:169], v[212:215], v[86:89]
	v_mfma_f32_16x16x32_bf16 v[82:85], v[178:181], v[212:215], 0
	v_mfma_f32_16x16x32_bf16 v[82:85], v[170:173], v[208:211], v[82:85]
	v_mfma_f32_16x16x32_bf16 v[66:69], v[170:173], v[216:219], 0
	v_mfma_f32_16x16x32_bf16 v[66:69], v[178:181], v[220:223], v[66:69]
	v_mfma_f32_16x16x32_bf16 v[70:73], v[166:169], v[220:223], 0
	v_mfma_f32_16x16x32_bf16 v[70:73], v[162:165], v[216:219], v[70:73]
	v_mfma_f32_16x16x32_bf16 v[74:77], v[154:157], v[216:219], 0
	v_mfma_f32_16x16x32_bf16 v[74:77], v[158:161], v[220:223], v[74:77]
	v_mfma_f32_16x16x32_bf16 v[78:81], v[150:153], v[220:223], 0
	v_mfma_f32_16x16x32_bf16 v[78:81], v[146:149], v[216:219], v[78:81]
	s_waitcnt vmcnt(8)
	s_barrier
	s_add_i32 s0, s0, s20
	s_mov_b32 m0, s0
	ds_read_b128 v[182:185], v177 offset:16384
	ds_read_b128 v[186:189], v177 offset:17408
	ds_read_b128 v[190:193], v177 offset:18432
	ds_read_b128 v[204:207], v177 offset:19456
	ds_read_b128 v[208:211], v177 offset:20480
	ds_read_b128 v[212:215], v177 offset:21504
	ds_read_b128 v[216:219], v177 offset:22528
	ds_read_b128 v[220:223], v177 offset:23552
	global_load_lds_dwordx4 v132, s[84:85]
	s_add_i32 m0, s0, 0x2000
	s_add_u32 s94, s84, 0x80000
	s_addc_u32 s95, s85, 0
	s_add_i32 s0, s1, s20
	global_load_lds_dwordx4 v130, s[84:85]
	s_mov_b32 m0, s0
	s_nop 0
	global_load_lds_dwordx4 v132, s[94:95]
	s_add_i32 m0, s0, 0x2000
	s_nop 0
	global_load_lds_dwordx4 v130, s[94:95]
	s_mov_b32 m0, s21
	s_nop 0
	global_load_lds_dwordx4 v132, vcc
	s_mov_b32 m0, s26
	s_nop 0
	global_load_lds_dwordx4 v130, vcc
	s_waitcnt lgkmcnt(0)
	s_barrier
	s_waitcnt lgkmcnt(0)
	v_mfma_f32_16x16x32_bf16 v[62:65], v[146:149], v[182:185], 0
	v_mfma_f32_16x16x32_bf16 v[62:65], v[150:153], v[186:189], v[62:65]
	v_mfma_f32_16x16x32_bf16 v[58:61], v[158:161], v[186:189], 0
	v_mfma_f32_16x16x32_bf16 v[58:61], v[154:157], v[182:185], v[58:61]
	v_mfma_f32_16x16x32_bf16 v[54:57], v[162:165], v[182:185], 0
	v_mfma_f32_16x16x32_bf16 v[54:57], v[166:169], v[186:189], v[54:57]
	v_mfma_f32_16x16x32_bf16 v[50:53], v[178:181], v[186:189], 0
	v_mfma_f32_16x16x32_bf16 v[50:53], v[170:173], v[182:185], v[50:53]
	v_mfma_f32_16x16x32_bf16 v[34:37], v[170:173], v[190:193], 0
	v_mfma_f32_16x16x32_bf16 v[34:37], v[178:181], v[204:207], v[34:37]
	v_mfma_f32_16x16x32_bf16 v[38:41], v[166:169], v[204:207], 0
	v_mfma_f32_16x16x32_bf16 v[38:41], v[162:165], v[190:193], v[38:41]
	v_mfma_f32_16x16x32_bf16 v[42:45], v[154:157], v[190:193], 0
	v_mfma_f32_16x16x32_bf16 v[42:45], v[158:161], v[204:207], v[42:45]
	v_mfma_f32_16x16x32_bf16 v[46:49], v[150:153], v[204:207], 0
	v_mfma_f32_16x16x32_bf16 v[46:49], v[146:149], v[190:193], v[46:49]
	v_mfma_f32_16x16x32_bf16 v[30:33], v[146:149], v[208:211], 0
	v_mfma_f32_16x16x32_bf16 v[30:33], v[150:153], v[212:215], v[30:33]
	v_mfma_f32_16x16x32_bf16 v[26:29], v[158:161], v[212:215], 0
	v_mfma_f32_16x16x32_bf16 v[26:29], v[154:157], v[208:211], v[26:29]
	v_mfma_f32_16x16x32_bf16 v[22:25], v[162:165], v[208:211], 0
	v_mfma_f32_16x16x32_bf16 v[22:25], v[166:169], v[212:215], v[22:25]
	v_mfma_f32_16x16x32_bf16 v[18:21], v[178:181], v[212:215], 0
	v_mfma_f32_16x16x32_bf16 v[18:21], v[170:173], v[208:211], v[18:21]
	v_mfma_f32_16x16x32_bf16 v[2:5], v[170:173], v[216:219], 0
	v_mfma_f32_16x16x32_bf16 v[2:5], v[178:181], v[220:223], v[2:5]
	v_mfma_f32_16x16x32_bf16 v[6:9], v[166:169], v[220:223], 0
	v_mfma_f32_16x16x32_bf16 v[6:9], v[162:165], v[216:219], v[6:9]
	v_mfma_f32_16x16x32_bf16 v[10:13], v[154:157], v[216:219], 0
	v_mfma_f32_16x16x32_bf16 v[10:13], v[158:161], v[220:223], v[10:13]
	v_mfma_f32_16x16x32_bf16 v[14:17], v[150:153], v[220:223], 0
	v_mfma_f32_16x16x32_bf16 v[14:17], v[146:149], v[216:219], v[14:17]
	s_waitcnt vmcnt(8)
	s_barrier
	s_add_i32 s0, 0, 0x18000
	s_add_i32 s1, 0, 0x1c000
	v_add_u32_e32 v158, s0, v176
	v_add_u32_e32 v178, s1, v176
	ds_read_b128 v[146:149], v158
	ds_read_b128 v[150:153], v158 offset:1024
	ds_read_b128 v[154:157], v158 offset:2048
	ds_read_b128 v[158:161], v158 offset:3072
	ds_read_b128 v[162:165], v178
	ds_read_b128 v[166:169], v178 offset:1024
	ds_read_b128 v[170:173], v178 offset:2048
	ds_read_b128 v[178:181], v178 offset:3072
	s_add_u32 s94, vcc_lo, 0x80000
	s_addc_u32 s95, vcc_hi, 0
	s_mov_b32 m0, s27
	ds_read_b128 v[182:185], v177 offset:32768
	ds_read_b128 v[186:189], v177 offset:33792
	ds_read_b128 v[190:193], v177 offset:34816
	ds_read_b128 v[204:207], v177 offset:35840
	ds_read_b128 v[208:211], v177 offset:36864
	ds_read_b128 v[212:215], v177 offset:37888
	ds_read_b128 v[216:219], v177 offset:38912
	ds_read_b128 v[220:223], v177 offset:39936
	global_load_lds_dwordx4 v132, s[94:95]
	s_mov_b32 m0, s29
	s_nop 0
	global_load_lds_dwordx4 v130, s[94:95]
	s_waitcnt lgkmcnt(0)
	s_barrier
	s_waitcnt lgkmcnt(0)
	v_mfma_f32_16x16x32_bf16 v[126:129], v[146:149], v[182:185], v[126:129]
	v_mfma_f32_16x16x32_bf16 v[126:129], v[150:153], v[186:189], v[126:129]
	v_mfma_f32_16x16x32_bf16 v[122:125], v[158:161], v[186:189], v[122:125]
	v_mfma_f32_16x16x32_bf16 v[122:125], v[154:157], v[182:185], v[122:125]
	v_mfma_f32_16x16x32_bf16 v[118:121], v[162:165], v[182:185], v[118:121]
	v_mfma_f32_16x16x32_bf16 v[118:121], v[166:169], v[186:189], v[118:121]
	v_mfma_f32_16x16x32_bf16 v[114:117], v[178:181], v[186:189], v[114:117]
	v_mfma_f32_16x16x32_bf16 v[114:117], v[170:173], v[182:185], v[114:117]
	v_mfma_f32_16x16x32_bf16 v[98:101], v[170:173], v[190:193], v[98:101]
	v_mfma_f32_16x16x32_bf16 v[98:101], v[178:181], v[204:207], v[98:101]
	v_mfma_f32_16x16x32_bf16 v[102:105], v[166:169], v[204:207], v[102:105]
	v_mfma_f32_16x16x32_bf16 v[102:105], v[162:165], v[190:193], v[102:105]
	v_mfma_f32_16x16x32_bf16 v[106:109], v[154:157], v[190:193], v[106:109]
	v_mfma_f32_16x16x32_bf16 v[106:109], v[158:161], v[204:207], v[106:109]
	v_mfma_f32_16x16x32_bf16 v[110:113], v[150:153], v[204:207], v[110:113]
	v_mfma_f32_16x16x32_bf16 v[110:113], v[146:149], v[190:193], v[110:113]
	v_mfma_f32_16x16x32_bf16 v[94:97], v[146:149], v[208:211], v[94:97]
	v_mfma_f32_16x16x32_bf16 v[94:97], v[150:153], v[212:215], v[94:97]
	v_mfma_f32_16x16x32_bf16 v[90:93], v[158:161], v[212:215], v[90:93]
	v_mfma_f32_16x16x32_bf16 v[90:93], v[154:157], v[208:211], v[90:93]
	v_mfma_f32_16x16x32_bf16 v[86:89], v[162:165], v[208:211], v[86:89]
	v_mfma_f32_16x16x32_bf16 v[86:89], v[166:169], v[212:215], v[86:89]
	v_mfma_f32_16x16x32_bf16 v[82:85], v[178:181], v[212:215], v[82:85]
	v_mfma_f32_16x16x32_bf16 v[82:85], v[170:173], v[208:211], v[82:85]
	v_mfma_f32_16x16x32_bf16 v[66:69], v[170:173], v[216:219], v[66:69]
	v_mfma_f32_16x16x32_bf16 v[66:69], v[178:181], v[220:223], v[66:69]
	v_mfma_f32_16x16x32_bf16 v[70:73], v[166:169], v[220:223], v[70:73]
	v_mfma_f32_16x16x32_bf16 v[70:73], v[162:165], v[216:219], v[70:73]
	v_mfma_f32_16x16x32_bf16 v[74:77], v[154:157], v[216:219], v[74:77]
	v_mfma_f32_16x16x32_bf16 v[74:77], v[158:161], v[220:223], v[74:77]
	v_mfma_f32_16x16x32_bf16 v[78:81], v[150:153], v[220:223], v[78:81]
	v_mfma_f32_16x16x32_bf16 v[78:81], v[146:149], v[216:219], v[78:81]
	s_waitcnt vmcnt(8)
	s_barrier
	s_add_u32 s98, s84, 0x80
	s_addc_u32 s99, s85, 0
	s_add_u32 s100, vcc_lo, 0x80
	s_addc_u32 s101, vcc_hi, 0
	s_add_i32 s0, s0, s20
	s_mov_b32 m0, s0
	ds_read_b128 v[182:185], v177 offset:49152
	ds_read_b128 v[186:189], v177 offset:50176
	ds_read_b128 v[190:193], v177 offset:51200
	ds_read_b128 v[204:207], v177 offset:52224
	ds_read_b128 v[208:211], v177 offset:53248
	ds_read_b128 v[212:215], v177 offset:54272
	ds_read_b128 v[216:219], v177 offset:55296
	ds_read_b128 v[220:223], v177 offset:56320
	global_load_lds_dwordx4 v132, s[98:99]
	s_add_i32 m0, s0, 0x2000
	s_add_u32 s84, s84, 0x80080
	s_addc_u32 s85, s85, 0
	s_add_i32 s0, s1, s20
	global_load_lds_dwordx4 v130, s[98:99]
	s_mov_b32 m0, s0
	s_nop 0
	global_load_lds_dwordx4 v132, s[84:85]
	s_add_i32 m0, s0, 0x2000
	s_nop 0
	global_load_lds_dwordx4 v130, s[84:85]
	s_mov_b32 m0, s40
	s_nop 0
	global_load_lds_dwordx4 v132, s[100:101]
	s_mov_b32 m0, s41
	s_nop 0
	global_load_lds_dwordx4 v130, s[100:101]
	s_waitcnt lgkmcnt(0)
	s_barrier
	s_waitcnt lgkmcnt(0)
	v_mfma_f32_16x16x32_bf16 v[62:65], v[146:149], v[182:185], v[62:65]
	v_mfma_f32_16x16x32_bf16 v[62:65], v[150:153], v[186:189], v[62:65]
	v_mfma_f32_16x16x32_bf16 v[58:61], v[158:161], v[186:189], v[58:61]
	v_mfma_f32_16x16x32_bf16 v[58:61], v[154:157], v[182:185], v[58:61]
	v_mfma_f32_16x16x32_bf16 v[54:57], v[162:165], v[182:185], v[54:57]
	v_mfma_f32_16x16x32_bf16 v[54:57], v[166:169], v[186:189], v[54:57]
	v_mfma_f32_16x16x32_bf16 v[50:53], v[178:181], v[186:189], v[50:53]
	v_mfma_f32_16x16x32_bf16 v[50:53], v[170:173], v[182:185], v[50:53]
	v_mfma_f32_16x16x32_bf16 v[34:37], v[170:173], v[190:193], v[34:37]
	v_mfma_f32_16x16x32_bf16 v[34:37], v[178:181], v[204:207], v[34:37]
	v_mfma_f32_16x16x32_bf16 v[38:41], v[166:169], v[204:207], v[38:41]
	v_mfma_f32_16x16x32_bf16 v[38:41], v[162:165], v[190:193], v[38:41]
	v_mfma_f32_16x16x32_bf16 v[42:45], v[154:157], v[190:193], v[42:45]
	v_mfma_f32_16x16x32_bf16 v[42:45], v[158:161], v[204:207], v[42:45]
	v_mfma_f32_16x16x32_bf16 v[46:49], v[150:153], v[204:207], v[46:49]
	v_mfma_f32_16x16x32_bf16 v[46:49], v[146:149], v[190:193], v[46:49]
	v_mfma_f32_16x16x32_bf16 v[30:33], v[146:149], v[208:211], v[30:33]
	v_mfma_f32_16x16x32_bf16 v[30:33], v[150:153], v[212:215], v[30:33]
	v_mfma_f32_16x16x32_bf16 v[26:29], v[158:161], v[212:215], v[26:29]
	v_mfma_f32_16x16x32_bf16 v[26:29], v[154:157], v[208:211], v[26:29]
	v_mfma_f32_16x16x32_bf16 v[22:25], v[162:165], v[208:211], v[22:25]
	v_mfma_f32_16x16x32_bf16 v[22:25], v[166:169], v[212:215], v[22:25]
	v_mfma_f32_16x16x32_bf16 v[18:21], v[178:181], v[212:215], v[18:21]
	v_mfma_f32_16x16x32_bf16 v[18:21], v[170:173], v[208:211], v[18:21]
	v_mfma_f32_16x16x32_bf16 v[2:5], v[170:173], v[216:219], v[2:5]
	v_mfma_f32_16x16x32_bf16 v[2:5], v[178:181], v[220:223], v[2:5]
	v_mfma_f32_16x16x32_bf16 v[6:9], v[166:169], v[220:223], v[6:9]
	v_mfma_f32_16x16x32_bf16 v[6:9], v[162:165], v[216:219], v[6:9]
	v_mfma_f32_16x16x32_bf16 v[10:13], v[154:157], v[216:219], v[10:13]
	v_mfma_f32_16x16x32_bf16 v[10:13], v[158:161], v[220:223], v[10:13]
	v_mfma_f32_16x16x32_bf16 v[14:17], v[150:153], v[220:223], v[14:17]
	v_mfma_f32_16x16x32_bf16 v[14:17], v[146:149], v[216:219], v[14:17]
	s_waitcnt vmcnt(8)
	s_barrier
	s_add_i32 s65, s65, 2
	s_add_u32 s76, s76, 0x100
	s_addc_u32 s77, s77, 0
	s_add_u32 s51, s51, 0x100
	s_addc_u32 s58, s58, 0
	s_cmp_gt_u32 s65, 29
	s_cbranch_scc1 .LBB0_264
	s_branch .LBB0_262
.Llw_main_ine:
	s_cmp_eq_u32 s98, 0
	s_cbranch_scc0 .LBB0_261
	s_add_u32 s0, s76, 0xfff80080
	s_addc_u32 s1, s77, -1
	s_and_b64 s[84:85], s[84:85], exec
	s_cselect_b32 vcc_hi, s22, s1
	s_cselect_b32 vcc_lo, s23, s0
	s_cselect_b32 s85, s49, s58
	s_cselect_b32 s84, s57, s51
	s_add_i32 s0, 0, 0x10000
	s_add_i32 s1, 0, 0x14000
	v_add_u32_e32 v158, s0, v176
	v_add_u32_e32 v174, s1, v176
	ds_read_b128 v[146:149], v158
	ds_read_b128 v[150:153], v158 offset:1024
	ds_read_b128 v[154:157], v158 offset:2048
	ds_read_b128 v[158:161], v158 offset:3072
	ds_read_b128 v[162:165], v174
	ds_read_b128 v[166:169], v174 offset:1024
	ds_read_b128 v[170:173], v174 offset:2048
	ds_read_b128 v[178:181], v174 offset:3072
	s_add_i32 m0, s21, 0xc000
	ds_read_b128 v[182:185], v177
	ds_read_b128 v[186:189], v177 offset:1024
	ds_read_b128 v[190:193], v177 offset:2048
	ds_read_b128 v[204:207], v177 offset:3072
	ds_read_b128 v[208:211], v177 offset:4096
	ds_read_b128 v[212:215], v177 offset:5120
	ds_read_b128 v[216:219], v177 offset:6144
	ds_read_b128 v[220:223], v177 offset:7168
	global_load_lds_dwordx4 v138, s[76:77]
	s_add_i32 m0, s21, 0xe000
	s_nop 0
	global_load_lds_dwordx4 v140, s[76:77]
	s_waitcnt lgkmcnt(0)
	s_barrier
	s_waitcnt lgkmcnt(0)
	v_mfma_f32_16x16x32_bf16 v[126:129], v[146:149], v[182:185], v[126:129]
	v_mfma_f32_16x16x32_bf16 v[126:129], v[150:153], v[186:189], v[126:129]
	v_mfma_f32_16x16x32_bf16 v[122:125], v[158:161], v[186:189], v[122:125]
	v_mfma_f32_16x16x32_bf16 v[122:125], v[154:157], v[182:185], v[122:125]
	v_mfma_f32_16x16x32_bf16 v[118:121], v[162:165], v[182:185], v[118:121]
	v_mfma_f32_16x16x32_bf16 v[118:121], v[166:169], v[186:189], v[118:121]
	v_mfma_f32_16x16x32_bf16 v[114:117], v[178:181], v[186:189], v[114:117]
	v_mfma_f32_16x16x32_bf16 v[114:117], v[170:173], v[182:185], v[114:117]
	v_mfma_f32_16x16x32_bf16 v[98:101], v[170:173], v[190:193], v[98:101]
	v_mfma_f32_16x16x32_bf16 v[98:101], v[178:181], v[204:207], v[98:101]
	v_mfma_f32_16x16x32_bf16 v[102:105], v[166:169], v[204:207], v[102:105]
	v_mfma_f32_16x16x32_bf16 v[102:105], v[162:165], v[190:193], v[102:105]
	v_mfma_f32_16x16x32_bf16 v[106:109], v[154:157], v[190:193], v[106:109]
	v_mfma_f32_16x16x32_bf16 v[106:109], v[158:161], v[204:207], v[106:109]
	v_mfma_f32_16x16x32_bf16 v[110:113], v[150:153], v[204:207], v[110:113]
	v_mfma_f32_16x16x32_bf16 v[110:113], v[146:149], v[190:193], v[110:113]
	v_mfma_f32_16x16x32_bf16 v[94:97], v[146:149], v[208:211], v[94:97]
	v_mfma_f32_16x16x32_bf16 v[94:97], v[150:153], v[212:215], v[94:97]
	v_mfma_f32_16x16x32_bf16 v[90:93], v[158:161], v[212:215], v[90:93]
	v_mfma_f32_16x16x32_bf16 v[90:93], v[154:157], v[208:211], v[90:93]
	v_mfma_f32_16x16x32_bf16 v[86:89], v[162:165], v[208:211], v[86:89]
	v_mfma_f32_16x16x32_bf16 v[86:89], v[166:169], v[212:215], v[86:89]
	v_mfma_f32_16x16x32_bf16 v[82:85], v[178:181], v[212:215], v[82:85]
	v_mfma_f32_16x16x32_bf16 v[82:85], v[170:173], v[208:211], v[82:85]
	v_mfma_f32_16x16x32_bf16 v[66:69], v[170:173], v[216:219], v[66:69]
	v_mfma_f32_16x16x32_bf16 v[66:69], v[178:181], v[220:223], v[66:69]
	v_mfma_f32_16x16x32_bf16 v[70:73], v[166:169], v[220:223], v[70:73]
	v_mfma_f32_16x16x32_bf16 v[70:73], v[162:165], v[216:219], v[70:73]
	v_mfma_f32_16x16x32_bf16 v[74:77], v[154:157], v[216:219], v[74:77]
	v_mfma_f32_16x16x32_bf16 v[74:77], v[158:161], v[220:223], v[74:77]
	v_mfma_f32_16x16x32_bf16 v[78:81], v[150:153], v[220:223], v[78:81]
	v_mfma_f32_16x16x32_bf16 v[78:81], v[146:149], v[216:219], v[78:81]
	s_waitcnt vmcnt(8)
	s_barrier
	s_add_i32 s0, s0, s20
	s_mov_b32 m0, s0
	ds_read_b128 v[182:185], v177 offset:16384
	ds_read_b128 v[186:189], v177 offset:17408
	ds_read_b128 v[190:193], v177 offset:18432
	ds_read_b128 v[204:207], v177 offset:19456
	ds_read_b128 v[208:211], v177 offset:20480
	ds_read_b128 v[212:215], v177 offset:21504
	ds_read_b128 v[216:219], v177 offset:22528
	ds_read_b128 v[220:223], v177 offset:23552
	global_load_lds_dwordx4 v132, s[84:85]
	s_add_i32 m0, s0, 0x2000
	s_add_u32 s94, s84, 0x80000
	s_addc_u32 s95, s85, 0
	s_add_i32 s0, s1, s20
	global_load_lds_dwordx4 v130, s[84:85]
	s_mov_b32 m0, s0
	s_nop 0
	global_load_lds_dwordx4 v132, s[94:95]
	s_add_i32 m0, s0, 0x2000
	s_nop 0
	global_load_lds_dwordx4 v130, s[94:95]
	s_mov_b32 m0, s21
	s_nop 0
	global_load_lds_dwordx4 v132, vcc
	s_mov_b32 m0, s26
	s_nop 0
	global_load_lds_dwordx4 v130, vcc
	s_waitcnt lgkmcnt(0)
	s_barrier
	s_waitcnt lgkmcnt(0)
	v_mfma_f32_16x16x32_bf16 v[62:65], v[146:149], v[182:185], v[62:65]
	v_mfma_f32_16x16x32_bf16 v[62:65], v[150:153], v[186:189], v[62:65]
	v_mfma_f32_16x16x32_bf16 v[58:61], v[158:161], v[186:189], v[58:61]
	v_mfma_f32_16x16x32_bf16 v[58:61], v[154:157], v[182:185], v[58:61]
	v_mfma_f32_16x16x32_bf16 v[54:57], v[162:165], v[182:185], v[54:57]
	v_mfma_f32_16x16x32_bf16 v[54:57], v[166:169], v[186:189], v[54:57]
	v_mfma_f32_16x16x32_bf16 v[50:53], v[178:181], v[186:189], v[50:53]
	v_mfma_f32_16x16x32_bf16 v[50:53], v[170:173], v[182:185], v[50:53]
	v_mfma_f32_16x16x32_bf16 v[34:37], v[170:173], v[190:193], v[34:37]
	v_mfma_f32_16x16x32_bf16 v[34:37], v[178:181], v[204:207], v[34:37]
	v_mfma_f32_16x16x32_bf16 v[38:41], v[166:169], v[204:207], v[38:41]
	v_mfma_f32_16x16x32_bf16 v[38:41], v[162:165], v[190:193], v[38:41]
	v_mfma_f32_16x16x32_bf16 v[42:45], v[154:157], v[190:193], v[42:45]
	v_mfma_f32_16x16x32_bf16 v[42:45], v[158:161], v[204:207], v[42:45]
	v_mfma_f32_16x16x32_bf16 v[46:49], v[150:153], v[204:207], v[46:49]
	v_mfma_f32_16x16x32_bf16 v[46:49], v[146:149], v[190:193], v[46:49]
	v_mfma_f32_16x16x32_bf16 v[30:33], v[146:149], v[208:211], v[30:33]
	v_mfma_f32_16x16x32_bf16 v[30:33], v[150:153], v[212:215], v[30:33]
	v_mfma_f32_16x16x32_bf16 v[26:29], v[158:161], v[212:215], v[26:29]
	v_mfma_f32_16x16x32_bf16 v[26:29], v[154:157], v[208:211], v[26:29]
	v_mfma_f32_16x16x32_bf16 v[22:25], v[162:165], v[208:211], v[22:25]
	v_mfma_f32_16x16x32_bf16 v[22:25], v[166:169], v[212:215], v[22:25]
	v_mfma_f32_16x16x32_bf16 v[18:21], v[178:181], v[212:215], v[18:21]
	v_mfma_f32_16x16x32_bf16 v[18:21], v[170:173], v[208:211], v[18:21]
	v_mfma_f32_16x16x32_bf16 v[2:5], v[170:173], v[216:219], v[2:5]
	v_mfma_f32_16x16x32_bf16 v[2:5], v[178:181], v[220:223], v[2:5]
	v_mfma_f32_16x16x32_bf16 v[6:9], v[166:169], v[220:223], v[6:9]
	v_mfma_f32_16x16x32_bf16 v[6:9], v[162:165], v[216:219], v[6:9]
	v_mfma_f32_16x16x32_bf16 v[10:13], v[154:157], v[216:219], v[10:13]
	v_mfma_f32_16x16x32_bf16 v[10:13], v[158:161], v[220:223], v[10:13]
	v_mfma_f32_16x16x32_bf16 v[14:17], v[150:153], v[220:223], v[14:17]
	v_mfma_f32_16x16x32_bf16 v[14:17], v[146:149], v[216:219], v[14:17]
	s_waitcnt vmcnt(8)
	s_barrier
	s_add_i32 s0, 0, 0x18000
	s_add_i32 s1, 0, 0x1c000
	v_add_u32_e32 v158, s0, v176
	v_add_u32_e32 v178, s1, v176
	ds_read_b128 v[146:149], v158
	ds_read_b128 v[150:153], v158 offset:1024
	ds_read_b128 v[154:157], v158 offset:2048
	ds_read_b128 v[158:161], v158 offset:3072
	ds_read_b128 v[162:165], v178
	ds_read_b128 v[166:169], v178 offset:1024
	ds_read_b128 v[170:173], v178 offset:2048
	ds_read_b128 v[178:181], v178 offset:3072
	s_add_u32 s94, vcc_lo, 0x80000
	s_addc_u32 s95, vcc_hi, 0
	s_mov_b32 m0, s27
	ds_read_b128 v[182:185], v177 offset:32768
	ds_read_b128 v[186:189], v177 offset:33792
	ds_read_b128 v[190:193], v177 offset:34816
	ds_read_b128 v[204:207], v177 offset:35840
	ds_read_b128 v[208:211], v177 offset:36864
	ds_read_b128 v[212:215], v177 offset:37888
	ds_read_b128 v[216:219], v177 offset:38912
	ds_read_b128 v[220:223], v177 offset:39936
	global_load_lds_dwordx4 v132, s[94:95]
	s_mov_b32 m0, s29
	s_nop 0
	global_load_lds_dwordx4 v130, s[94:95]
	s_waitcnt lgkmcnt(0)
	s_barrier
	s_waitcnt lgkmcnt(0)
	v_mfma_f32_16x16x32_bf16 v[126:129], v[146:149], v[182:185], v[126:129]
	v_mfma_f32_16x16x32_bf16 v[126:129], v[150:153], v[186:189], v[126:129]
	v_mfma_f32_16x16x32_bf16 v[122:125], v[158:161], v[186:189], v[122:125]
	v_mfma_f32_16x16x32_bf16 v[122:125], v[154:157], v[182:185], v[122:125]
	v_mfma_f32_16x16x32_bf16 v[118:121], v[162:165], v[182:185], v[118:121]
	v_mfma_f32_16x16x32_bf16 v[118:121], v[166:169], v[186:189], v[118:121]
	v_mfma_f32_16x16x32_bf16 v[114:117], v[178:181], v[186:189], v[114:117]
	v_mfma_f32_16x16x32_bf16 v[114:117], v[170:173], v[182:185], v[114:117]
	v_mfma_f32_16x16x32_bf16 v[98:101], v[170:173], v[190:193], v[98:101]
	v_mfma_f32_16x16x32_bf16 v[98:101], v[178:181], v[204:207], v[98:101]
	v_mfma_f32_16x16x32_bf16 v[102:105], v[166:169], v[204:207], v[102:105]
	v_mfma_f32_16x16x32_bf16 v[102:105], v[162:165], v[190:193], v[102:105]
	v_mfma_f32_16x16x32_bf16 v[106:109], v[154:157], v[190:193], v[106:109]
	v_mfma_f32_16x16x32_bf16 v[106:109], v[158:161], v[204:207], v[106:109]
	v_mfma_f32_16x16x32_bf16 v[110:113], v[150:153], v[204:207], v[110:113]
	v_mfma_f32_16x16x32_bf16 v[110:113], v[146:149], v[190:193], v[110:113]
	v_mfma_f32_16x16x32_bf16 v[94:97], v[146:149], v[208:211], v[94:97]
	v_mfma_f32_16x16x32_bf16 v[94:97], v[150:153], v[212:215], v[94:97]
	v_mfma_f32_16x16x32_bf16 v[90:93], v[158:161], v[212:215], v[90:93]
	v_mfma_f32_16x16x32_bf16 v[90:93], v[154:157], v[208:211], v[90:93]
	v_mfma_f32_16x16x32_bf16 v[86:89], v[162:165], v[208:211], v[86:89]
	v_mfma_f32_16x16x32_bf16 v[86:89], v[166:169], v[212:215], v[86:89]
	v_mfma_f32_16x16x32_bf16 v[82:85], v[178:181], v[212:215], v[82:85]
	v_mfma_f32_16x16x32_bf16 v[82:85], v[170:173], v[208:211], v[82:85]
	v_mfma_f32_16x16x32_bf16 v[66:69], v[170:173], v[216:219], v[66:69]
	v_mfma_f32_16x16x32_bf16 v[66:69], v[178:181], v[220:223], v[66:69]
	v_mfma_f32_16x16x32_bf16 v[70:73], v[166:169], v[220:223], v[70:73]
	v_mfma_f32_16x16x32_bf16 v[70:73], v[162:165], v[216:219], v[70:73]
	v_mfma_f32_16x16x32_bf16 v[74:77], v[154:157], v[216:219], v[74:77]
	v_mfma_f32_16x16x32_bf16 v[74:77], v[158:161], v[220:223], v[74:77]
	v_mfma_f32_16x16x32_bf16 v[78:81], v[150:153], v[220:223], v[78:81]
	v_mfma_f32_16x16x32_bf16 v[78:81], v[146:149], v[216:219], v[78:81]
	s_waitcnt vmcnt(8)
	s_barrier
	s_add_u32 s98, s84, 0x80
	s_addc_u32 s99, s85, 0
	s_add_u32 s100, vcc_lo, 0x80
	s_addc_u32 s101, vcc_hi, 0
	s_add_i32 s0, s0, s20
	s_mov_b32 m0, s0
	ds_read_b128 v[182:185], v177 offset:49152
	ds_read_b128 v[186:189], v177 offset:50176
	ds_read_b128 v[190:193], v177 offset:51200
	ds_read_b128 v[204:207], v177 offset:52224
	ds_read_b128 v[208:211], v177 offset:53248
	ds_read_b128 v[212:215], v177 offset:54272
	ds_read_b128 v[216:219], v177 offset:55296
	ds_read_b128 v[220:223], v177 offset:56320
	global_load_lds_dwordx4 v132, s[98:99]
	s_add_i32 m0, s0, 0x2000
	s_add_u32 s84, s84, 0x80080
	s_addc_u32 s85, s85, 0
	s_add_i32 s0, s1, s20
	global_load_lds_dwordx4 v130, s[98:99]
	s_mov_b32 m0, s0
	s_nop 0
	global_load_lds_dwordx4 v132, s[84:85]
	s_add_i32 m0, s0, 0x2000
	s_nop 0
	global_load_lds_dwordx4 v130, s[84:85]
	s_mov_b32 m0, s40
	s_nop 0
	global_load_lds_dwordx4 v132, s[100:101]
	s_mov_b32 m0, s41
	s_nop 0
	global_load_lds_dwordx4 v130, s[100:101]
	s_waitcnt lgkmcnt(0)
	s_barrier
	s_waitcnt lgkmcnt(0)
	v_mfma_f32_16x16x32_bf16 v[62:65], v[146:149], v[182:185], v[62:65]
	v_mfma_f32_16x16x32_bf16 v[62:65], v[150:153], v[186:189], v[62:65]
	v_mfma_f32_16x16x32_bf16 v[58:61], v[158:161], v[186:189], v[58:61]
	v_mfma_f32_16x16x32_bf16 v[58:61], v[154:157], v[182:185], v[58:61]
	v_mfma_f32_16x16x32_bf16 v[54:57], v[162:165], v[182:185], v[54:57]
	v_mfma_f32_16x16x32_bf16 v[54:57], v[166:169], v[186:189], v[54:57]
	v_mfma_f32_16x16x32_bf16 v[50:53], v[178:181], v[186:189], v[50:53]
	v_mfma_f32_16x16x32_bf16 v[50:53], v[170:173], v[182:185], v[50:53]
	v_mfma_f32_16x16x32_bf16 v[34:37], v[170:173], v[190:193], v[34:37]
	v_mfma_f32_16x16x32_bf16 v[34:37], v[178:181], v[204:207], v[34:37]
	v_mfma_f32_16x16x32_bf16 v[38:41], v[166:169], v[204:207], v[38:41]
	v_mfma_f32_16x16x32_bf16 v[38:41], v[162:165], v[190:193], v[38:41]
	v_mfma_f32_16x16x32_bf16 v[42:45], v[154:157], v[190:193], v[42:45]
	v_mfma_f32_16x16x32_bf16 v[42:45], v[158:161], v[204:207], v[42:45]
	v_mfma_f32_16x16x32_bf16 v[46:49], v[150:153], v[204:207], v[46:49]
	v_mfma_f32_16x16x32_bf16 v[46:49], v[146:149], v[190:193], v[46:49]
	v_mfma_f32_16x16x32_bf16 v[30:33], v[146:149], v[208:211], v[30:33]
	v_mfma_f32_16x16x32_bf16 v[30:33], v[150:153], v[212:215], v[30:33]
	v_mfma_f32_16x16x32_bf16 v[26:29], v[158:161], v[212:215], v[26:29]
	v_mfma_f32_16x16x32_bf16 v[26:29], v[154:157], v[208:211], v[26:29]
	v_mfma_f32_16x16x32_bf16 v[22:25], v[162:165], v[208:211], v[22:25]
	v_mfma_f32_16x16x32_bf16 v[22:25], v[166:169], v[212:215], v[22:25]
	v_mfma_f32_16x16x32_bf16 v[18:21], v[178:181], v[212:215], v[18:21]
	v_mfma_f32_16x16x32_bf16 v[18:21], v[170:173], v[208:211], v[18:21]
	v_mfma_f32_16x16x32_bf16 v[2:5], v[170:173], v[216:219], v[2:5]
	v_mfma_f32_16x16x32_bf16 v[2:5], v[178:181], v[220:223], v[2:5]
	v_mfma_f32_16x16x32_bf16 v[6:9], v[166:169], v[220:223], v[6:9]
	v_mfma_f32_16x16x32_bf16 v[6:9], v[162:165], v[216:219], v[6:9]
	v_mfma_f32_16x16x32_bf16 v[10:13], v[154:157], v[216:219], v[10:13]
	v_mfma_f32_16x16x32_bf16 v[10:13], v[158:161], v[220:223], v[10:13]
	v_mfma_f32_16x16x32_bf16 v[14:17], v[150:153], v[220:223], v[14:17]
	v_mfma_f32_16x16x32_bf16 v[14:17], v[146:149], v[216:219], v[14:17]
	s_waitcnt vmcnt(8)
	s_barrier
	s_add_i32 s65, s65, 2
	s_add_u32 s76, s76, 0x100
	s_addc_u32 s77, s77, 0
	s_add_u32 s51, s51, 0x100
	s_addc_u32 s58, s58, 0
	s_cmp_gt_u32 s65, 29
	s_cbranch_scc1 .LBB0_264
	s_branch .LBB0_262

.LBB0_275:
	s_andn2_b64 vcc, exec, s[4:5]
	s_cbranch_vccnz .LBB0_312
	v_readlane_b32 s0, v254, 31
	v_readlane_b32 s1, v254, 32
	s_andn2_b64 vcc, exec, s[0:1]
	v_readfirstlane_b32 s4, v1
	s_cbranch_vccnz .LBB0_312
	v_lshlrev_b32_e32 v13, 4, v1
	v_add_u32_e32 v2, 0x2000, v13
	v_ashrrev_i32_e32 v3, 31, v2
	v_lshrrev_b32_e32 v3, 22, v3
	v_add_u32_e32 v3, v2, v3
	v_ashrrev_i32_e32 v10, 10, v3
	v_mul_i32_i24_e32 v4, 0x400, v10
	v_sub_u32_e32 v2, v2, v4
	v_lshrrev_b32_e32 v4, 4, v2
	v_bitop3_b32 v2, v4, v2, 32 bitop3:0x6c
	v_ashrrev_i32_e32 v4, 31, v2
	v_lshrrev_b32_e32 v4, 26, v4
	v_add_u32_e32 v4, v2, v4
	v_ashrrev_i32_e32 v11, 6, v4
	v_and_b32_e32 v4, 0xc0, v4
	v_sub_u32_e32 v2, v2, v4
	v_lshlrev_b32_e32 v3, 5, v10
	v_ashrrev_i16_sdwa v2, v233, sext(v2) dst_sel:DWORD dst_unused:UNUSED_PAD src0_sel:DWORD src1_sel:BYTE_0
	v_and_b32_e32 v3, 32, v3
	v_bfe_i32 v12, v2, 0, 16
	v_add_u32_e32 v2, v3, v12
	v_lshlrev_b32_e32 v3, 3, v10
	v_and_b32_e32 v3, 0xffff0, v3
	v_add_lshl_u32 v3, v11, v3, 12
	v_lshl_add_u32 v162, v2, 1, v3
	v_bfe_i32 v3, v1, 27, 1
	v_lshrrev_b32_e32 v3, 22, v3
	v_add_u32_e32 v3, v13, v3
	v_and_b32_e32 v3, 0xfffffc00, v3
	v_sub_u32_e32 v3, v13, v3
	v_lshrrev_b32_e32 v4, 4, v3
	v_bitop3_b32 v3, v4, v3, 32 bitop3:0x6c
	v_readlane_b32 s1, v254, 27
	v_ashrrev_i32_e32 v4, 31, v3
	s_mul_hi_u32 s0, s1, 0x1600000
	s_mul_i32 s1, s1, 0x1600000
	v_lshrrev_b32_e32 v4, 26, v4
	s_add_u32 s1, s6, s1
	v_ashrrev_i32_e32 v2, 31, v1
	v_add_u32_e32 v4, v3, v4
	s_addc_u32 s0, s7, s0
	v_lshrrev_b32_e32 v2, 26, v2
	v_ashrrev_i32_e32 v15, 6, v4
	v_and_b32_e32 v4, 0xc0, v4
	s_add_u32 s29, s1, 0x2c00000
	v_add_u32_e32 v2, v1, v2
	v_sub_u32_e32 v3, v3, v4
	s_addc_u32 s31, s0, 0
	s_ashr_i32 s10, s4, 6
	v_ashrrev_i32_e32 v14, 6, v2
	v_ashrrev_i16_sdwa v3, v233, sext(v3) dst_sel:DWORD dst_unused:UNUSED_PAD src0_sel:DWORD src1_sel:BYTE_0
	s_ashr_i32 s5, s4, 8
	s_ashr_i32 s98, s4, 8
	s_lshl_b32 s54, s10, 10
	v_lshlrev_b32_e32 v2, 5, v14
	v_bfe_i32 v16, v3, 0, 16
	v_lshlrev_b32_e32 v3, 3, v14
	v_readlane_b32 s0, v255, 6
	v_and_b32_e32 v2, 32, v2
	v_and_b32_e32 v3, 0xffff0, v3
	v_readlane_b32 s1, v255, 7
	s_add_u32 s70, s29, s0
	v_add_u32_e32 v2, v2, v16
	v_add_lshl_u32 v3, v15, v3, 12
	s_addc_u32 s71, s31, s1
	s_add_i32 s67, s54, 0
	v_lshl_add_u32 v164, v2, 1, v3
	s_add_i32 m0, s67, 0x10000
	v_readlane_b32 s0, v255, 4
	global_load_lds_dwordx4 v164, s[70:71]
	s_add_i32 m0, s67, 0x12000
	s_add_u32 s8, s70, 0x80000
	global_load_lds_dwordx4 v162, s[70:71]
	s_addc_u32 s9, s71, 0
	s_add_i32 m0, s67, 0x14000
	v_readlane_b32 s1, v255, 5
	global_load_lds_dwordx4 v164, s[8:9]
	s_add_i32 m0, s67, 0x16000
	s_add_u32 s76, s79, s0
	s_addc_u32 s77, s28, s1
	s_add_i32 s68, s67, 0x2000
	global_load_lds_dwordx4 v162, s[8:9]
	s_mov_b32 m0, s67
	s_add_u32 s12, s76, 0x80000
	global_load_lds_dwordx4 v164, s[76:77]
	s_mov_b32 m0, s68
	s_addc_u32 s13, s77, 0
	s_add_i32 s8, s67, 0x4000
	global_load_lds_dwordx4 v162, s[76:77]
	s_mov_b32 m0, s8
	s_add_i32 s9, s67, 0x6000
	global_load_lds_dwordx4 v164, s[12:13]
	s_mov_b32 m0, s9
	v_mov_b32_e32 v165, v195
	global_load_lds_dwordx4 v162, s[12:13]
	v_mov_b32_e32 v163, v195
	s_cmp_eq_u32 s5, 1
	v_lshl_add_u64 v[8:9], s[70:71], 0, v[164:165]
	v_lshl_add_u64 v[6:7], s[70:71], 0, v[162:163]
	v_lshl_add_u64 v[2:3], s[76:77], 0, v[164:165]
	s_cselect_b64 s[84:85], -1, 0
	s_cmp_lg_u32 s5, 1
	v_lshl_add_u64 v[4:5], s[76:77], 0, v[162:163]
	s_cbranch_scc1 .LBB0_279
	s_barrier

.Lpeel_disp_ino:
	s_cmp_lg_u32 s43, -2
	s_cbranch_scc1 .Llw_main_ino
	s_cmp_eq_u32 s98, 0
	s_cbranch_scc1 .Llw_p0_ino
	s_add_u32 s0, s76, 0xfff80080
	s_addc_u32 s1, s77, -1
	s_and_b64 s[70:71], s[70:71], exec
	s_cselect_b32 vcc_hi, s21, s1
	s_cselect_b32 vcc_lo, s22, s0
	s_cselect_b32 s71, s23, s41
	s_cselect_b32 s70, s39, s7
	s_add_i32 s0, 0, 0x10000
	s_add_i32 s1, 0, 0x14000
	v_add_u32_e32 v146, s0, v1
	v_add_u32_e32 v174, s1, v1
	ds_read_b128 v[134:137], v146
	ds_read_b128 v[138:141], v146 offset:1024
	ds_read_b128 v[142:145], v146 offset:2048
	ds_read_b128 v[146:149], v146 offset:3072
	ds_read_b128 v[150:153], v174
	ds_read_b128 v[154:157], v174 offset:1024
	ds_read_b128 v[158:161], v174 offset:2048
	ds_read_b128 v[174:177], v174 offset:3072
	s_add_i32 m0, s67, 0xc000
	ds_read_b128 v[178:181], v222
	ds_read_b128 v[182:185], v222 offset:1024
	ds_read_b128 v[186:189], v222 offset:2048
	ds_read_b128 v[190:193], v222 offset:3072
	ds_read_b128 v[204:207], v222 offset:4096
	ds_read_b128 v[208:211], v222 offset:5120
	ds_read_b128 v[212:215], v222 offset:6144
	ds_read_b128 v[216:219], v222 offset:7168
	global_load_lds_dwordx4 v170, s[76:77]
	s_add_i32 m0, s67, 0xe000
	s_nop 0
	global_load_lds_dwordx4 v172, s[76:77]
	s_waitcnt vmcnt(8)
	s_waitcnt lgkmcnt(0)
	s_barrier
	s_waitcnt lgkmcnt(0)
	v_mfma_f32_16x16x32_bf16 v[126:129], v[134:137], v[178:181], 0
	v_mfma_f32_16x16x32_bf16 v[126:129], v[138:141], v[182:185], v[126:129]
	v_mfma_f32_16x16x32_bf16 v[122:125], v[146:149], v[182:185], 0
	v_mfma_f32_16x16x32_bf16 v[122:125], v[142:145], v[178:181], v[122:125]
	v_mfma_f32_16x16x32_bf16 v[118:121], v[150:153], v[178:181], 0
	v_mfma_f32_16x16x32_bf16 v[118:121], v[154:157], v[182:185], v[118:121]
	v_mfma_f32_16x16x32_bf16 v[114:117], v[174:177], v[182:185], 0
	v_mfma_f32_16x16x32_bf16 v[114:117], v[158:161], v[178:181], v[114:117]
	v_mfma_f32_16x16x32_bf16 v[98:101], v[158:161], v[186:189], 0
	v_mfma_f32_16x16x32_bf16 v[98:101], v[174:177], v[190:193], v[98:101]
	v_mfma_f32_16x16x32_bf16 v[102:105], v[154:157], v[190:193], 0
	v_mfma_f32_16x16x32_bf16 v[102:105], v[150:153], v[186:189], v[102:105]
	v_mfma_f32_16x16x32_bf16 v[106:109], v[142:145], v[186:189], 0
	v_mfma_f32_16x16x32_bf16 v[106:109], v[146:149], v[190:193], v[106:109]
	v_mfma_f32_16x16x32_bf16 v[110:113], v[138:141], v[190:193], 0
	v_mfma_f32_16x16x32_bf16 v[110:113], v[134:137], v[186:189], v[110:113]
	v_mfma_f32_16x16x32_bf16 v[94:97], v[134:137], v[204:207], 0
	v_mfma_f32_16x16x32_bf16 v[94:97], v[138:141], v[208:211], v[94:97]
	v_mfma_f32_16x16x32_bf16 v[90:93], v[146:149], v[208:211], 0
	v_mfma_f32_16x16x32_bf16 v[90:93], v[142:145], v[204:207], v[90:93]
	v_mfma_f32_16x16x32_bf16 v[86:89], v[150:153], v[204:207], 0
	v_mfma_f32_16x16x32_bf16 v[86:89], v[154:157], v[208:211], v[86:89]
	v_mfma_f32_16x16x32_bf16 v[82:85], v[174:177], v[208:211], 0
	v_mfma_f32_16x16x32_bf16 v[82:85], v[158:161], v[204:207], v[82:85]
	v_mfma_f32_16x16x32_bf16 v[66:69], v[158:161], v[212:215], 0
	v_mfma_f32_16x16x32_bf16 v[66:69], v[174:177], v[216:219], v[66:69]
	v_mfma_f32_16x16x32_bf16 v[70:73], v[154:157], v[216:219], 0
	v_mfma_f32_16x16x32_bf16 v[70:73], v[150:153], v[212:215], v[70:73]
	v_mfma_f32_16x16x32_bf16 v[74:77], v[142:145], v[212:215], 0
	v_mfma_f32_16x16x32_bf16 v[74:77], v[146:149], v[216:219], v[74:77]
	v_mfma_f32_16x16x32_bf16 v[78:81], v[138:141], v[216:219], 0
	v_mfma_f32_16x16x32_bf16 v[78:81], v[134:137], v[212:215], v[78:81]
	s_barrier
	s_add_i32 s0, s0, s54
	s_mov_b32 m0, s0
	ds_read_b128 v[178:181], v222 offset:16384
	ds_read_b128 v[182:185], v222 offset:17408
	ds_read_b128 v[186:189], v222 offset:18432
	ds_read_b128 v[190:193], v222 offset:19456
	ds_read_b128 v[204:207], v222 offset:20480
	ds_read_b128 v[208:211], v222 offset:21504
	ds_read_b128 v[212:215], v222 offset:22528
	ds_read_b128 v[216:219], v222 offset:23552
	global_load_lds_dwordx4 v164, s[70:71]
	s_add_i32 m0, s0, 0x2000
	s_add_u32 s44, s70, 0x80000
	s_addc_u32 s45, s71, 0
	s_add_i32 s0, s1, s54
	global_load_lds_dwordx4 v162, s[70:71]
	s_mov_b32 m0, s0
	s_nop 0
	global_load_lds_dwordx4 v164, s[44:45]
	s_add_i32 m0, s0, 0x2000
	s_nop 0
	global_load_lds_dwordx4 v162, s[44:45]
	s_mov_b32 m0, s67
	s_nop 0
	global_load_lds_dwordx4 v164, vcc
	s_mov_b32 m0, s68
	s_nop 0
	global_load_lds_dwordx4 v162, vcc
	s_waitcnt vmcnt(8)
	s_waitcnt lgkmcnt(0)
	s_barrier
	s_waitcnt lgkmcnt(0)
	v_mfma_f32_16x16x32_bf16 v[62:65], v[134:137], v[178:181], 0
	v_mfma_f32_16x16x32_bf16 v[62:65], v[138:141], v[182:185], v[62:65]
	v_mfma_f32_16x16x32_bf16 v[58:61], v[146:149], v[182:185], 0
	v_mfma_f32_16x16x32_bf16 v[58:61], v[142:145], v[178:181], v[58:61]
	v_mfma_f32_16x16x32_bf16 v[54:57], v[150:153], v[178:181], 0
	v_mfma_f32_16x16x32_bf16 v[54:57], v[154:157], v[182:185], v[54:57]
	v_mfma_f32_16x16x32_bf16 v[50:53], v[174:177], v[182:185], 0
	v_mfma_f32_16x16x32_bf16 v[50:53], v[158:161], v[178:181], v[50:53]
	v_mfma_f32_16x16x32_bf16 v[34:37], v[158:161], v[186:189], 0
	v_mfma_f32_16x16x32_bf16 v[34:37], v[174:177], v[190:193], v[34:37]
	v_mfma_f32_16x16x32_bf16 v[38:41], v[154:157], v[190:193], 0
	v_mfma_f32_16x16x32_bf16 v[38:41], v[150:153], v[186:189], v[38:41]
	v_mfma_f32_16x16x32_bf16 v[42:45], v[142:145], v[186:189], 0
	v_mfma_f32_16x16x32_bf16 v[42:45], v[146:149], v[190:193], v[42:45]
	v_mfma_f32_16x16x32_bf16 v[46:49], v[138:141], v[190:193], 0
	v_mfma_f32_16x16x32_bf16 v[46:49], v[134:137], v[186:189], v[46:49]
	v_mfma_f32_16x16x32_bf16 v[30:33], v[134:137], v[204:207], 0
	v_mfma_f32_16x16x32_bf16 v[30:33], v[138:141], v[208:211], v[30:33]
	v_mfma_f32_16x16x32_bf16 v[26:29], v[146:149], v[208:211], 0
	v_mfma_f32_16x16x32_bf16 v[26:29], v[142:145], v[204:207], v[26:29]
	v_mfma_f32_16x16x32_bf16 v[22:25], v[150:153], v[204:207], 0
	v_mfma_f32_16x16x32_bf16 v[22:25], v[154:157], v[208:211], v[22:25]
	v_mfma_f32_16x16x32_bf16 v[18:21], v[174:177], v[208:211], 0
	v_mfma_f32_16x16x32_bf16 v[18:21], v[158:161], v[204:207], v[18:21]
	v_mfma_f32_16x16x32_bf16 v[2:5], v[158:161], v[212:215], 0
	v_mfma_f32_16x16x32_bf16 v[2:5], v[174:177], v[216:219], v[2:5]
	v_mfma_f32_16x16x32_bf16 v[6:9], v[154:157], v[216:219], 0
	v_mfma_f32_16x16x32_bf16 v[6:9], v[150:153], v[212:215], v[6:9]
	v_mfma_f32_16x16x32_bf16 v[10:13], v[142:145], v[212:215], 0
	v_mfma_f32_16x16x32_bf16 v[10:13], v[146:149], v[216:219], v[10:13]
	v_mfma_f32_16x16x32_bf16 v[14:17], v[138:141], v[216:219], 0
	v_mfma_f32_16x16x32_bf16 v[14:17], v[134:137], v[212:215], v[14:17]
	s_barrier
	s_add_i32 s0, 0, 0x18000
	s_add_i32 s1, 0, 0x1c000
	v_add_u32_e32 v146, s0, v1
	v_add_u32_e32 v174, s1, v1
	ds_read_b128 v[134:137], v146
	ds_read_b128 v[138:141], v146 offset:1024
	ds_read_b128 v[142:145], v146 offset:2048
	ds_read_b128 v[146:149], v146 offset:3072
	ds_read_b128 v[150:153], v174
	ds_read_b128 v[154:157], v174 offset:1024
	ds_read_b128 v[158:161], v174 offset:2048
	ds_read_b128 v[174:177], v174 offset:3072
	s_add_u32 s44, vcc_lo, 0x80000
	s_addc_u32 s45, vcc_hi, 0
	s_mov_b32 m0, s8
	ds_read_b128 v[178:181], v222 offset:32768
	ds_read_b128 v[182:185], v222 offset:33792
	ds_read_b128 v[186:189], v222 offset:34816
	ds_read_b128 v[190:193], v222 offset:35840
	ds_read_b128 v[204:207], v222 offset:36864
	ds_read_b128 v[208:211], v222 offset:37888
	ds_read_b128 v[212:215], v222 offset:38912
	ds_read_b128 v[216:219], v222 offset:39936
	global_load_lds_dwordx4 v164, s[44:45]
	s_mov_b32 m0, s9
	s_nop 0
	global_load_lds_dwordx4 v162, s[44:45]
	s_waitcnt vmcnt(8)
	s_waitcnt lgkmcnt(0)
	s_barrier
	s_waitcnt lgkmcnt(0)
	v_mfma_f32_16x16x32_bf16 v[126:129], v[134:137], v[178:181], v[126:129]
	v_mfma_f32_16x16x32_bf16 v[126:129], v[138:141], v[182:185], v[126:129]
	v_mfma_f32_16x16x32_bf16 v[122:125], v[146:149], v[182:185], v[122:125]
	v_mfma_f32_16x16x32_bf16 v[122:125], v[142:145], v[178:181], v[122:125]
	v_mfma_f32_16x16x32_bf16 v[118:121], v[150:153], v[178:181], v[118:121]
	v_mfma_f32_16x16x32_bf16 v[118:121], v[154:157], v[182:185], v[118:121]
	v_mfma_f32_16x16x32_bf16 v[114:117], v[174:177], v[182:185], v[114:117]
	v_mfma_f32_16x16x32_bf16 v[114:117], v[158:161], v[178:181], v[114:117]
	v_mfma_f32_16x16x32_bf16 v[98:101], v[158:161], v[186:189], v[98:101]
	v_mfma_f32_16x16x32_bf16 v[98:101], v[174:177], v[190:193], v[98:101]
	v_mfma_f32_16x16x32_bf16 v[102:105], v[154:157], v[190:193], v[102:105]
	v_mfma_f32_16x16x32_bf16 v[102:105], v[150:153], v[186:189], v[102:105]
	v_mfma_f32_16x16x32_bf16 v[106:109], v[142:145], v[186:189], v[106:109]
	v_mfma_f32_16x16x32_bf16 v[106:109], v[146:149], v[190:193], v[106:109]
	v_mfma_f32_16x16x32_bf16 v[110:113], v[138:141], v[190:193], v[110:113]
	v_mfma_f32_16x16x32_bf16 v[110:113], v[134:137], v[186:189], v[110:113]
	v_mfma_f32_16x16x32_bf16 v[94:97], v[134:137], v[204:207], v[94:97]
	v_mfma_f32_16x16x32_bf16 v[94:97], v[138:141], v[208:211], v[94:97]
	v_mfma_f32_16x16x32_bf16 v[90:93], v[146:149], v[208:211], v[90:93]
	v_mfma_f32_16x16x32_bf16 v[90:93], v[142:145], v[204:207], v[90:93]
	v_mfma_f32_16x16x32_bf16 v[86:89], v[150:153], v[204:207], v[86:89]
	v_mfma_f32_16x16x32_bf16 v[86:89], v[154:157], v[208:211], v[86:89]
	v_mfma_f32_16x16x32_bf16 v[82:85], v[174:177], v[208:211], v[82:85]
	v_mfma_f32_16x16x32_bf16 v[82:85], v[158:161], v[204:207], v[82:85]
	v_mfma_f32_16x16x32_bf16 v[66:69], v[158:161], v[212:215], v[66:69]
	v_mfma_f32_16x16x32_bf16 v[66:69], v[174:177], v[216:219], v[66:69]
	v_mfma_f32_16x16x32_bf16 v[70:73], v[154:157], v[216:219], v[70:73]
	v_mfma_f32_16x16x32_bf16 v[70:73], v[150:153], v[212:215], v[70:73]
	v_mfma_f32_16x16x32_bf16 v[74:77], v[142:145], v[212:215], v[74:77]
	v_mfma_f32_16x16x32_bf16 v[74:77], v[146:149], v[216:219], v[74:77]
	v_mfma_f32_16x16x32_bf16 v[78:81], v[138:141], v[216:219], v[78:81]
	v_mfma_f32_16x16x32_bf16 v[78:81], v[134:137], v[212:215], v[78:81]
	s_barrier
	s_add_u32 s98, s70, 0x80
	s_addc_u32 s99, s71, 0
	s_add_u32 s100, vcc_lo, 0x80
	s_addc_u32 s101, vcc_hi, 0
	s_add_i32 s0, s0, s54
	s_mov_b32 m0, s0
	ds_read_b128 v[178:181], v222 offset:49152
	ds_read_b128 v[182:185], v222 offset:50176
	ds_read_b128 v[186:189], v222 offset:51200
	ds_read_b128 v[190:193], v222 offset:52224
	ds_read_b128 v[204:207], v222 offset:53248
	ds_read_b128 v[208:211], v222 offset:54272
	ds_read_b128 v[212:215], v222 offset:55296
	ds_read_b128 v[216:219], v222 offset:56320
	global_load_lds_dwordx4 v164, s[98:99]
	s_add_i32 m0, s0, 0x2000
	s_add_u32 s44, s70, 0x80080
	s_addc_u32 s45, s71, 0
	s_add_i32 s0, s1, s54
	global_load_lds_dwordx4 v162, s[98:99]
	s_mov_b32 m0, s0
	s_nop 0
	global_load_lds_dwordx4 v164, s[44:45]
	s_add_i32 m0, s0, 0x2000
	s_nop 0
	global_load_lds_dwordx4 v162, s[44:45]
	s_mov_b32 m0, s27
	s_nop 0
	global_load_lds_dwordx4 v164, s[100:101]
	s_mov_b32 m0, s26
	s_nop 0
	global_load_lds_dwordx4 v162, s[100:101]
	s_waitcnt vmcnt(8)
	s_waitcnt lgkmcnt(0)
	s_barrier
	s_waitcnt lgkmcnt(0)
	v_mfma_f32_16x16x32_bf16 v[62:65], v[134:137], v[178:181], v[62:65]
	v_mfma_f32_16x16x32_bf16 v[62:65], v[138:141], v[182:185], v[62:65]
	v_mfma_f32_16x16x32_bf16 v[58:61], v[146:149], v[182:185], v[58:61]
	v_mfma_f32_16x16x32_bf16 v[58:61], v[142:145], v[178:181], v[58:61]
	v_mfma_f32_16x16x32_bf16 v[54:57], v[150:153], v[178:181], v[54:57]
	v_mfma_f32_16x16x32_bf16 v[54:57], v[154:157], v[182:185], v[54:57]
	v_mfma_f32_16x16x32_bf16 v[50:53], v[174:177], v[182:185], v[50:53]
	v_mfma_f32_16x16x32_bf16 v[50:53], v[158:161], v[178:181], v[50:53]
	v_mfma_f32_16x16x32_bf16 v[34:37], v[158:161], v[186:189], v[34:37]
	v_mfma_f32_16x16x32_bf16 v[34:37], v[174:177], v[190:193], v[34:37]
	v_mfma_f32_16x16x32_bf16 v[38:41], v[154:157], v[190:193], v[38:41]
	v_mfma_f32_16x16x32_bf16 v[38:41], v[150:153], v[186:189], v[38:41]
	v_mfma_f32_16x16x32_bf16 v[42:45], v[142:145], v[186:189], v[42:45]
	v_mfma_f32_16x16x32_bf16 v[42:45], v[146:149], v[190:193], v[42:45]
	v_mfma_f32_16x16x32_bf16 v[46:49], v[138:141], v[190:193], v[46:49]
	v_mfma_f32_16x16x32_bf16 v[46:49], v[134:137], v[186:189], v[46:49]
	v_mfma_f32_16x16x32_bf16 v[30:33], v[134:137], v[204:207], v[30:33]
	v_mfma_f32_16x16x32_bf16 v[30:33], v[138:141], v[208:211], v[30:33]
	v_mfma_f32_16x16x32_bf16 v[26:29], v[146:149], v[208:211], v[26:29]
	v_mfma_f32_16x16x32_bf16 v[26:29], v[142:145], v[204:207], v[26:29]
	v_mfma_f32_16x16x32_bf16 v[22:25], v[150:153], v[204:207], v[22:25]
	v_mfma_f32_16x16x32_bf16 v[22:25], v[154:157], v[208:211], v[22:25]
	v_mfma_f32_16x16x32_bf16 v[18:21], v[174:177], v[208:211], v[18:21]
	v_mfma_f32_16x16x32_bf16 v[18:21], v[158:161], v[204:207], v[18:21]
	v_mfma_f32_16x16x32_bf16 v[2:5], v[158:161], v[212:215], v[2:5]
	v_mfma_f32_16x16x32_bf16 v[2:5], v[174:177], v[216:219], v[2:5]
	v_mfma_f32_16x16x32_bf16 v[6:9], v[154:157], v[216:219], v[6:9]
	v_mfma_f32_16x16x32_bf16 v[6:9], v[150:153], v[212:215], v[6:9]
	v_mfma_f32_16x16x32_bf16 v[10:13], v[142:145], v[212:215], v[10:13]
	v_mfma_f32_16x16x32_bf16 v[10:13], v[146:149], v[216:219], v[10:13]
	v_mfma_f32_16x16x32_bf16 v[14:17], v[138:141], v[216:219], v[14:17]
	v_mfma_f32_16x16x32_bf16 v[14:17], v[134:137], v[212:215], v[14:17]
	s_barrier
	s_add_i32 s43, s43, 2
	s_add_u32 s76, s76, 0x100
	s_addc_u32 s77, s77, 0
	s_add_u32 s7, s7, 0x100
	s_addc_u32 s41, s41, 0
	s_cmp_gt_u32 s43, 29
	s_cbranch_scc1 .LBB0_288
	s_branch .LBB0_286
.Llw_p0_ino:
	s_add_u32 s0, s76, 0xfff80080
	s_addc_u32 s1, s77, -1
	s_and_b64 s[70:71], s[70:71], exec
	s_cselect_b32 vcc_hi, s21, s1
	s_cselect_b32 vcc_lo, s22, s0
	s_cselect_b32 s71, s23, s41
	s_cselect_b32 s70, s39, s7
	s_add_i32 s0, 0, 0x10000
	s_add_i32 s1, 0, 0x14000
	v_add_u32_e32 v146, s0, v1
	v_add_u32_e32 v174, s1, v1
	ds_read_b128 v[134:137], v146
	ds_read_b128 v[138:141], v146 offset:1024
	ds_read_b128 v[142:145], v146 offset:2048
	ds_read_b128 v[146:149], v146 offset:3072
	ds_read_b128 v[150:153], v174
	ds_read_b128 v[154:157], v174 offset:1024
	ds_read_b128 v[158:161], v174 offset:2048
	ds_read_b128 v[174:177], v174 offset:3072
	s_add_i32 m0, s67, 0xc000
	ds_read_b128 v[178:181], v222
	ds_read_b128 v[182:185], v222 offset:1024
	ds_read_b128 v[186:189], v222 offset:2048
	ds_read_b128 v[190:193], v222 offset:3072
	ds_read_b128 v[204:207], v222 offset:4096
	ds_read_b128 v[208:211], v222 offset:5120
	ds_read_b128 v[212:215], v222 offset:6144
	ds_read_b128 v[216:219], v222 offset:7168
	global_load_lds_dwordx4 v170, s[76:77]
	s_add_i32 m0, s67, 0xe000
	s_nop 0
	global_load_lds_dwordx4 v172, s[76:77]
	s_waitcnt lgkmcnt(0)
	s_barrier
	s_waitcnt lgkmcnt(0)
	v_mfma_f32_16x16x32_bf16 v[126:129], v[134:137], v[178:181], 0
	v_mfma_f32_16x16x32_bf16 v[126:129], v[138:141], v[182:185], v[126:129]
	v_mfma_f32_16x16x32_bf16 v[122:125], v[146:149], v[182:185], 0
	v_mfma_f32_16x16x32_bf16 v[122:125], v[142:145], v[178:181], v[122:125]
	v_mfma_f32_16x16x32_bf16 v[118:121], v[150:153], v[178:181], 0
	v_mfma_f32_16x16x32_bf16 v[118:121], v[154:157], v[182:185], v[118:121]
	v_mfma_f32_16x16x32_bf16 v[114:117], v[174:177], v[182:185], 0
	v_mfma_f32_16x16x32_bf16 v[114:117], v[158:161], v[178:181], v[114:117]
	v_mfma_f32_16x16x32_bf16 v[98:101], v[158:161], v[186:189], 0
	v_mfma_f32_16x16x32_bf16 v[98:101], v[174:177], v[190:193], v[98:101]
	v_mfma_f32_16x16x32_bf16 v[102:105], v[154:157], v[190:193], 0
	v_mfma_f32_16x16x32_bf16 v[102:105], v[150:153], v[186:189], v[102:105]
	v_mfma_f32_16x16x32_bf16 v[106:109], v[142:145], v[186:189], 0
	v_mfma_f32_16x16x32_bf16 v[106:109], v[146:149], v[190:193], v[106:109]
	v_mfma_f32_16x16x32_bf16 v[110:113], v[138:141], v[190:193], 0
	v_mfma_f32_16x16x32_bf16 v[110:113], v[134:137], v[186:189], v[110:113]
	v_mfma_f32_16x16x32_bf16 v[94:97], v[134:137], v[204:207], 0
	v_mfma_f32_16x16x32_bf16 v[94:97], v[138:141], v[208:211], v[94:97]
	v_mfma_f32_16x16x32_bf16 v[90:93], v[146:149], v[208:211], 0
	v_mfma_f32_16x16x32_bf16 v[90:93], v[142:145], v[204:207], v[90:93]
	v_mfma_f32_16x16x32_bf16 v[86:89], v[150:153], v[204:207], 0
	v_mfma_f32_16x16x32_bf16 v[86:89], v[154:157], v[208:211], v[86:89]
	v_mfma_f32_16x16x32_bf16 v[82:85], v[174:177], v[208:211], 0
	v_mfma_f32_16x16x32_bf16 v[82:85], v[158:161], v[204:207], v[82:85]
	v_mfma_f32_16x16x32_bf16 v[66:69], v[158:161], v[212:215], 0
	v_mfma_f32_16x16x32_bf16 v[66:69], v[174:177], v[216:219], v[66:69]
	v_mfma_f32_16x16x32_bf16 v[70:73], v[154:157], v[216:219], 0
	v_mfma_f32_16x16x32_bf16 v[70:73], v[150:153], v[212:215], v[70:73]
	v_mfma_f32_16x16x32_bf16 v[74:77], v[142:145], v[212:215], 0
	v_mfma_f32_16x16x32_bf16 v[74:77], v[146:149], v[216:219], v[74:77]
	v_mfma_f32_16x16x32_bf16 v[78:81], v[138:141], v[216:219], 0
	v_mfma_f32_16x16x32_bf16 v[78:81], v[134:137], v[212:215], v[78:81]
	s_waitcnt vmcnt(8)
	s_barrier
	s_add_i32 s0, s0, s54
	s_mov_b32 m0, s0
	ds_read_b128 v[178:181], v222 offset:16384
	ds_read_b128 v[182:185], v222 offset:17408
	ds_read_b128 v[186:189], v222 offset:18432
	ds_read_b128 v[190:193], v222 offset:19456
	ds_read_b128 v[204:207], v222 offset:20480
	ds_read_b128 v[208:211], v222 offset:21504
	ds_read_b128 v[212:215], v222 offset:22528
	ds_read_b128 v[216:219], v222 offset:23552
	global_load_lds_dwordx4 v164, s[70:71]
	s_add_i32 m0, s0, 0x2000
	s_add_u32 s44, s70, 0x80000
	s_addc_u32 s45, s71, 0
	s_add_i32 s0, s1, s54
	global_load_lds_dwordx4 v162, s[70:71]
	s_mov_b32 m0, s0
	s_nop 0
	global_load_lds_dwordx4 v164, s[44:45]
	s_add_i32 m0, s0, 0x2000
	s_nop 0
	global_load_lds_dwordx4 v162, s[44:45]
	s_mov_b32 m0, s67
	s_nop 0
	global_load_lds_dwordx4 v164, vcc
	s_mov_b32 m0, s68
	s_nop 0
	global_load_lds_dwordx4 v162, vcc
	s_waitcnt lgkmcnt(0)
	s_barrier
	s_waitcnt lgkmcnt(0)
	v_mfma_f32_16x16x32_bf16 v[62:65], v[134:137], v[178:181], 0
	v_mfma_f32_16x16x32_bf16 v[62:65], v[138:141], v[182:185], v[62:65]
	v_mfma_f32_16x16x32_bf16 v[58:61], v[146:149], v[182:185], 0
	v_mfma_f32_16x16x32_bf16 v[58:61], v[142:145], v[178:181], v[58:61]
	v_mfma_f32_16x16x32_bf16 v[54:57], v[150:153], v[178:181], 0
	v_mfma_f32_16x16x32_bf16 v[54:57], v[154:157], v[182:185], v[54:57]
	v_mfma_f32_16x16x32_bf16 v[50:53], v[174:177], v[182:185], 0
	v_mfma_f32_16x16x32_bf16 v[50:53], v[158:161], v[178:181], v[50:53]
	v_mfma_f32_16x16x32_bf16 v[34:37], v[158:161], v[186:189], 0
	v_mfma_f32_16x16x32_bf16 v[34:37], v[174:177], v[190:193], v[34:37]
	v_mfma_f32_16x16x32_bf16 v[38:41], v[154:157], v[190:193], 0
	v_mfma_f32_16x16x32_bf16 v[38:41], v[150:153], v[186:189], v[38:41]
	v_mfma_f32_16x16x32_bf16 v[42:45], v[142:145], v[186:189], 0
	v_mfma_f32_16x16x32_bf16 v[42:45], v[146:149], v[190:193], v[42:45]
	v_mfma_f32_16x16x32_bf16 v[46:49], v[138:141], v[190:193], 0
	v_mfma_f32_16x16x32_bf16 v[46:49], v[134:137], v[186:189], v[46:49]
	v_mfma_f32_16x16x32_bf16 v[30:33], v[134:137], v[204:207], 0
	v_mfma_f32_16x16x32_bf16 v[30:33], v[138:141], v[208:211], v[30:33]
	v_mfma_f32_16x16x32_bf16 v[26:29], v[146:149], v[208:211], 0
	v_mfma_f32_16x16x32_bf16 v[26:29], v[142:145], v[204:207], v[26:29]
	v_mfma_f32_16x16x32_bf16 v[22:25], v[150:153], v[204:207], 0
	v_mfma_f32_16x16x32_bf16 v[22:25], v[154:157], v[208:211], v[22:25]
	v_mfma_f32_16x16x32_bf16 v[18:21], v[174:177], v[208:211], 0
	v_mfma_f32_16x16x32_bf16 v[18:21], v[158:161], v[204:207], v[18:21]
	v_mfma_f32_16x16x32_bf16 v[2:5], v[158:161], v[212:215], 0
	v_mfma_f32_16x16x32_bf16 v[2:5], v[174:177], v[216:219], v[2:5]
	v_mfma_f32_16x16x32_bf16 v[6:9], v[154:157], v[216:219], 0
	v_mfma_f32_16x16x32_bf16 v[6:9], v[150:153], v[212:215], v[6:9]
	v_mfma_f32_16x16x32_bf16 v[10:13], v[142:145], v[212:215], 0
	v_mfma_f32_16x16x32_bf16 v[10:13], v[146:149], v[216:219], v[10:13]
	v_mfma_f32_16x16x32_bf16 v[14:17], v[138:141], v[216:219], 0
	v_mfma_f32_16x16x32_bf16 v[14:17], v[134:137], v[212:215], v[14:17]
	s_waitcnt vmcnt(8)
	s_barrier
	s_add_i32 s0, 0, 0x18000
	s_add_i32 s1, 0, 0x1c000
	v_add_u32_e32 v146, s0, v1
	v_add_u32_e32 v174, s1, v1
	ds_read_b128 v[134:137], v146
	ds_read_b128 v[138:141], v146 offset:1024
	ds_read_b128 v[142:145], v146 offset:2048
	ds_read_b128 v[146:149], v146 offset:3072
	ds_read_b128 v[150:153], v174
	ds_read_b128 v[154:157], v174 offset:1024
	ds_read_b128 v[158:161], v174 offset:2048
	ds_read_b128 v[174:177], v174 offset:3072
	s_add_u32 s44, vcc_lo, 0x80000
	s_addc_u32 s45, vcc_hi, 0
	s_mov_b32 m0, s8
	ds_read_b128 v[178:181], v222 offset:32768
	ds_read_b128 v[182:185], v222 offset:33792
	ds_read_b128 v[186:189], v222 offset:34816
	ds_read_b128 v[190:193], v222 offset:35840
	ds_read_b128 v[204:207], v222 offset:36864
	ds_read_b128 v[208:211], v222 offset:37888
	ds_read_b128 v[212:215], v222 offset:38912
	ds_read_b128 v[216:219], v222 offset:39936
	global_load_lds_dwordx4 v164, s[44:45]
	s_mov_b32 m0, s9
	s_nop 0
	global_load_lds_dwordx4 v162, s[44:45]
	s_waitcnt lgkmcnt(0)
	s_barrier
	s_waitcnt lgkmcnt(0)
	v_mfma_f32_16x16x32_bf16 v[126:129], v[134:137], v[178:181], v[126:129]
	v_mfma_f32_16x16x32_bf16 v[126:129], v[138:141], v[182:185], v[126:129]
	v_mfma_f32_16x16x32_bf16 v[122:125], v[146:149], v[182:185], v[122:125]
	v_mfma_f32_16x16x32_bf16 v[122:125], v[142:145], v[178:181], v[122:125]
	v_mfma_f32_16x16x32_bf16 v[118:121], v[150:153], v[178:181], v[118:121]
	v_mfma_f32_16x16x32_bf16 v[118:121], v[154:157], v[182:185], v[118:121]
	v_mfma_f32_16x16x32_bf16 v[114:117], v[174:177], v[182:185], v[114:117]
	v_mfma_f32_16x16x32_bf16 v[114:117], v[158:161], v[178:181], v[114:117]
	v_mfma_f32_16x16x32_bf16 v[98:101], v[158:161], v[186:189], v[98:101]
	v_mfma_f32_16x16x32_bf16 v[98:101], v[174:177], v[190:193], v[98:101]
	v_mfma_f32_16x16x32_bf16 v[102:105], v[154:157], v[190:193], v[102:105]
	v_mfma_f32_16x16x32_bf16 v[102:105], v[150:153], v[186:189], v[102:105]
	v_mfma_f32_16x16x32_bf16 v[106:109], v[142:145], v[186:189], v[106:109]
	v_mfma_f32_16x16x32_bf16 v[106:109], v[146:149], v[190:193], v[106:109]
	v_mfma_f32_16x16x32_bf16 v[110:113], v[138:141], v[190:193], v[110:113]
	v_mfma_f32_16x16x32_bf16 v[110:113], v[134:137], v[186:189], v[110:113]
	v_mfma_f32_16x16x32_bf16 v[94:97], v[134:137], v[204:207], v[94:97]
	v_mfma_f32_16x16x32_bf16 v[94:97], v[138:141], v[208:211], v[94:97]
	v_mfma_f32_16x16x32_bf16 v[90:93], v[146:149], v[208:211], v[90:93]
	v_mfma_f32_16x16x32_bf16 v[90:93], v[142:145], v[204:207], v[90:93]
	v_mfma_f32_16x16x32_bf16 v[86:89], v[150:153], v[204:207], v[86:89]
	v_mfma_f32_16x16x32_bf16 v[86:89], v[154:157], v[208:211], v[86:89]
	v_mfma_f32_16x16x32_bf16 v[82:85], v[174:177], v[208:211], v[82:85]
	v_mfma_f32_16x16x32_bf16 v[82:85], v[158:161], v[204:207], v[82:85]
	v_mfma_f32_16x16x32_bf16 v[66:69], v[158:161], v[212:215], v[66:69]
	v_mfma_f32_16x16x32_bf16 v[66:69], v[174:177], v[216:219], v[66:69]
	v_mfma_f32_16x16x32_bf16 v[70:73], v[154:157], v[216:219], v[70:73]
	v_mfma_f32_16x16x32_bf16 v[70:73], v[150:153], v[212:215], v[70:73]
	v_mfma_f32_16x16x32_bf16 v[74:77], v[142:145], v[212:215], v[74:77]
	v_mfma_f32_16x16x32_bf16 v[74:77], v[146:149], v[216:219], v[74:77]
	v_mfma_f32_16x16x32_bf16 v[78:81], v[138:141], v[216:219], v[78:81]
	v_mfma_f32_16x16x32_bf16 v[78:81], v[134:137], v[212:215], v[78:81]
	s_waitcnt vmcnt(8)
	s_barrier
	s_add_u32 s98, s70, 0x80
	s_addc_u32 s99, s71, 0
	s_add_u32 s100, vcc_lo, 0x80
	s_addc_u32 s101, vcc_hi, 0
	s_add_i32 s0, s0, s54
	s_mov_b32 m0, s0
	ds_read_b128 v[178:181], v222 offset:49152
	ds_read_b128 v[182:185], v222 offset:50176
	ds_read_b128 v[186:189], v222 offset:51200
	ds_read_b128 v[190:193], v222 offset:52224
	ds_read_b128 v[204:207], v222 offset:53248
	ds_read_b128 v[208:211], v222 offset:54272
	ds_read_b128 v[212:215], v222 offset:55296
	ds_read_b128 v[216:219], v222 offset:56320
	global_load_lds_dwordx4 v164, s[98:99]
	s_add_i32 m0, s0, 0x2000
	s_add_u32 s44, s70, 0x80080
	s_addc_u32 s45, s71, 0
	s_add_i32 s0, s1, s54
	global_load_lds_dwordx4 v162, s[98:99]
	s_mov_b32 m0, s0
	s_nop 0
	global_load_lds_dwordx4 v164, s[44:45]
	s_add_i32 m0, s0, 0x2000
	s_nop 0
	global_load_lds_dwordx4 v162, s[44:45]
	s_mov_b32 m0, s27
	s_nop 0
	global_load_lds_dwordx4 v164, s[100:101]
	s_mov_b32 m0, s26
	s_nop 0
	global_load_lds_dwordx4 v162, s[100:101]
	s_waitcnt lgkmcnt(0)
	s_barrier
	s_waitcnt lgkmcnt(0)
	v_mfma_f32_16x16x32_bf16 v[62:65], v[134:137], v[178:181], v[62:65]
	v_mfma_f32_16x16x32_bf16 v[62:65], v[138:141], v[182:185], v[62:65]
	v_mfma_f32_16x16x32_bf16 v[58:61], v[146:149], v[182:185], v[58:61]
	v_mfma_f32_16x16x32_bf16 v[58:61], v[142:145], v[178:181], v[58:61]
	v_mfma_f32_16x16x32_bf16 v[54:57], v[150:153], v[178:181], v[54:57]
	v_mfma_f32_16x16x32_bf16 v[54:57], v[154:157], v[182:185], v[54:57]
	v_mfma_f32_16x16x32_bf16 v[50:53], v[174:177], v[182:185], v[50:53]
	v_mfma_f32_16x16x32_bf16 v[50:53], v[158:161], v[178:181], v[50:53]
	v_mfma_f32_16x16x32_bf16 v[34:37], v[158:161], v[186:189], v[34:37]
	v_mfma_f32_16x16x32_bf16 v[34:37], v[174:177], v[190:193], v[34:37]
	v_mfma_f32_16x16x32_bf16 v[38:41], v[154:157], v[190:193], v[38:41]
	v_mfma_f32_16x16x32_bf16 v[38:41], v[150:153], v[186:189], v[38:41]
	v_mfma_f32_16x16x32_bf16 v[42:45], v[142:145], v[186:189], v[42:45]
	v_mfma_f32_16x16x32_bf16 v[42:45], v[146:149], v[190:193], v[42:45]
	v_mfma_f32_16x16x32_bf16 v[46:49], v[138:141], v[190:193], v[46:49]
	v_mfma_f32_16x16x32_bf16 v[46:49], v[134:137], v[186:189], v[46:49]
	v_mfma_f32_16x16x32_bf16 v[30:33], v[134:137], v[204:207], v[30:33]
	v_mfma_f32_16x16x32_bf16 v[30:33], v[138:141], v[208:211], v[30:33]
	v_mfma_f32_16x16x32_bf16 v[26:29], v[146:149], v[208:211], v[26:29]
	v_mfma_f32_16x16x32_bf16 v[26:29], v[142:145], v[204:207], v[26:29]
	v_mfma_f32_16x16x32_bf16 v[22:25], v[150:153], v[204:207], v[22:25]
	v_mfma_f32_16x16x32_bf16 v[22:25], v[154:157], v[208:211], v[22:25]
	v_mfma_f32_16x16x32_bf16 v[18:21], v[174:177], v[208:211], v[18:21]
	v_mfma_f32_16x16x32_bf16 v[18:21], v[158:161], v[204:207], v[18:21]
	v_mfma_f32_16x16x32_bf16 v[2:5], v[158:161], v[212:215], v[2:5]
	v_mfma_f32_16x16x32_bf16 v[2:5], v[174:177], v[216:219], v[2:5]
	v_mfma_f32_16x16x32_bf16 v[6:9], v[154:157], v[216:219], v[6:9]
	v_mfma_f32_16x16x32_bf16 v[6:9], v[150:153], v[212:215], v[6:9]
	v_mfma_f32_16x16x32_bf16 v[10:13], v[142:145], v[212:215], v[10:13]
	v_mfma_f32_16x16x32_bf16 v[10:13], v[146:149], v[216:219], v[10:13]
	v_mfma_f32_16x16x32_bf16 v[14:17], v[138:141], v[216:219], v[14:17]
	v_mfma_f32_16x16x32_bf16 v[14:17], v[134:137], v[212:215], v[14:17]
	s_waitcnt vmcnt(8)
	s_barrier
	s_add_i32 s43, s43, 2
	s_add_u32 s76, s76, 0x100
	s_addc_u32 s77, s77, 0
	s_add_u32 s7, s7, 0x100
	s_addc_u32 s41, s41, 0
	s_cmp_gt_u32 s43, 29
	s_cbranch_scc1 .LBB0_288
	s_branch .LBB0_286
.Llw_main_ino:
	s_cmp_eq_u32 s98, 0
	s_cbranch_scc0 .LBB0_285
	s_add_u32 s0, s76, 0xfff80080
	s_addc_u32 s1, s77, -1
	s_and_b64 s[70:71], s[70:71], exec
	s_cselect_b32 vcc_hi, s21, s1
	s_cselect_b32 vcc_lo, s22, s0
	s_cselect_b32 s71, s23, s41
	s_cselect_b32 s70, s39, s7
	s_add_i32 s0, 0, 0x10000
	s_add_i32 s1, 0, 0x14000
	v_add_u32_e32 v146, s0, v1
	v_add_u32_e32 v174, s1, v1
	ds_read_b128 v[134:137], v146
	ds_read_b128 v[138:141], v146 offset:1024
	ds_read_b128 v[142:145], v146 offset:2048
	ds_read_b128 v[146:149], v146 offset:3072
	ds_read_b128 v[150:153], v174
	ds_read_b128 v[154:157], v174 offset:1024
	ds_read_b128 v[158:161], v174 offset:2048
	ds_read_b128 v[174:177], v174 offset:3072
	s_add_i32 m0, s67, 0xc000
	ds_read_b128 v[178:181], v222
	ds_read_b128 v[182:185], v222 offset:1024
	ds_read_b128 v[186:189], v222 offset:2048
	ds_read_b128 v[190:193], v222 offset:3072
	ds_read_b128 v[204:207], v222 offset:4096
	ds_read_b128 v[208:211], v222 offset:5120
	ds_read_b128 v[212:215], v222 offset:6144
	ds_read_b128 v[216:219], v222 offset:7168
	global_load_lds_dwordx4 v170, s[76:77]
	s_add_i32 m0, s67, 0xe000
	s_nop 0
	global_load_lds_dwordx4 v172, s[76:77]
	s_waitcnt lgkmcnt(0)
	s_barrier
	s_waitcnt lgkmcnt(0)
	v_mfma_f32_16x16x32_bf16 v[126:129], v[134:137], v[178:181], v[126:129]
	v_mfma_f32_16x16x32_bf16 v[126:129], v[138:141], v[182:185], v[126:129]
	v_mfma_f32_16x16x32_bf16 v[122:125], v[146:149], v[182:185], v[122:125]
	v_mfma_f32_16x16x32_bf16 v[122:125], v[142:145], v[178:181], v[122:125]
	v_mfma_f32_16x16x32_bf16 v[118:121], v[150:153], v[178:181], v[118:121]
	v_mfma_f32_16x16x32_bf16 v[118:121], v[154:157], v[182:185], v[118:121]
	v_mfma_f32_16x16x32_bf16 v[114:117], v[174:177], v[182:185], v[114:117]
	v_mfma_f32_16x16x32_bf16 v[114:117], v[158:161], v[178:181], v[114:117]
	v_mfma_f32_16x16x32_bf16 v[98:101], v[158:161], v[186:189], v[98:101]
	v_mfma_f32_16x16x32_bf16 v[98:101], v[174:177], v[190:193], v[98:101]
	v_mfma_f32_16x16x32_bf16 v[102:105], v[154:157], v[190:193], v[102:105]
	v_mfma_f32_16x16x32_bf16 v[102:105], v[150:153], v[186:189], v[102:105]
	v_mfma_f32_16x16x32_bf16 v[106:109], v[142:145], v[186:189], v[106:109]
	v_mfma_f32_16x16x32_bf16 v[106:109], v[146:149], v[190:193], v[106:109]
	v_mfma_f32_16x16x32_bf16 v[110:113], v[138:141], v[190:193], v[110:113]
	v_mfma_f32_16x16x32_bf16 v[110:113], v[134:137], v[186:189], v[110:113]
	v_mfma_f32_16x16x32_bf16 v[94:97], v[134:137], v[204:207], v[94:97]
	v_mfma_f32_16x16x32_bf16 v[94:97], v[138:141], v[208:211], v[94:97]
	v_mfma_f32_16x16x32_bf16 v[90:93], v[146:149], v[208:211], v[90:93]
	v_mfma_f32_16x16x32_bf16 v[90:93], v[142:145], v[204:207], v[90:93]
	v_mfma_f32_16x16x32_bf16 v[86:89], v[150:153], v[204:207], v[86:89]
	v_mfma_f32_16x16x32_bf16 v[86:89], v[154:157], v[208:211], v[86:89]
	v_mfma_f32_16x16x32_bf16 v[82:85], v[174:177], v[208:211], v[82:85]
	v_mfma_f32_16x16x32_bf16 v[82:85], v[158:161], v[204:207], v[82:85]
	v_mfma_f32_16x16x32_bf16 v[66:69], v[158:161], v[212:215], v[66:69]
	v_mfma_f32_16x16x32_bf16 v[66:69], v[174:177], v[216:219], v[66:69]
	v_mfma_f32_16x16x32_bf16 v[70:73], v[154:157], v[216:219], v[70:73]
	v_mfma_f32_16x16x32_bf16 v[70:73], v[150:153], v[212:215], v[70:73]
	v_mfma_f32_16x16x32_bf16 v[74:77], v[142:145], v[212:215], v[74:77]
	v_mfma_f32_16x16x32_bf16 v[74:77], v[146:149], v[216:219], v[74:77]
	v_mfma_f32_16x16x32_bf16 v[78:81], v[138:141], v[216:219], v[78:81]
	v_mfma_f32_16x16x32_bf16 v[78:81], v[134:137], v[212:215], v[78:81]
	s_waitcnt vmcnt(8)
	s_barrier
	s_add_i32 s0, s0, s54
	s_mov_b32 m0, s0
	ds_read_b128 v[178:181], v222 offset:16384
	ds_read_b128 v[182:185], v222 offset:17408
	ds_read_b128 v[186:189], v222 offset:18432
	ds_read_b128 v[190:193], v222 offset:19456
	ds_read_b128 v[204:207], v222 offset:20480
	ds_read_b128 v[208:211], v222 offset:21504
	ds_read_b128 v[212:215], v222 offset:22528
	ds_read_b128 v[216:219], v222 offset:23552
	global_load_lds_dwordx4 v164, s[70:71]
	s_add_i32 m0, s0, 0x2000
	s_add_u32 s44, s70, 0x80000
	s_addc_u32 s45, s71, 0
	s_add_i32 s0, s1, s54
	global_load_lds_dwordx4 v162, s[70:71]
	s_mov_b32 m0, s0
	s_nop 0
	global_load_lds_dwordx4 v164, s[44:45]
	s_add_i32 m0, s0, 0x2000
	s_nop 0
	global_load_lds_dwordx4 v162, s[44:45]
	s_mov_b32 m0, s67
	s_nop 0
	global_load_lds_dwordx4 v164, vcc
	s_mov_b32 m0, s68
	s_nop 0
	global_load_lds_dwordx4 v162, vcc
	s_waitcnt lgkmcnt(0)
	s_barrier
	s_waitcnt lgkmcnt(0)
	v_mfma_f32_16x16x32_bf16 v[62:65], v[134:137], v[178:181], v[62:65]
	v_mfma_f32_16x16x32_bf16 v[62:65], v[138:141], v[182:185], v[62:65]
	v_mfma_f32_16x16x32_bf16 v[58:61], v[146:149], v[182:185], v[58:61]
	v_mfma_f32_16x16x32_bf16 v[58:61], v[142:145], v[178:181], v[58:61]
	v_mfma_f32_16x16x32_bf16 v[54:57], v[150:153], v[178:181], v[54:57]
	v_mfma_f32_16x16x32_bf16 v[54:57], v[154:157], v[182:185], v[54:57]
	v_mfma_f32_16x16x32_bf16 v[50:53], v[174:177], v[182:185], v[50:53]
	v_mfma_f32_16x16x32_bf16 v[50:53], v[158:161], v[178:181], v[50:53]
	v_mfma_f32_16x16x32_bf16 v[34:37], v[158:161], v[186:189], v[34:37]
	v_mfma_f32_16x16x32_bf16 v[34:37], v[174:177], v[190:193], v[34:37]
	v_mfma_f32_16x16x32_bf16 v[38:41], v[154:157], v[190:193], v[38:41]
	v_mfma_f32_16x16x32_bf16 v[38:41], v[150:153], v[186:189], v[38:41]
	v_mfma_f32_16x16x32_bf16 v[42:45], v[142:145], v[186:189], v[42:45]
	v_mfma_f32_16x16x32_bf16 v[42:45], v[146:149], v[190:193], v[42:45]
	v_mfma_f32_16x16x32_bf16 v[46:49], v[138:141], v[190:193], v[46:49]
	v_mfma_f32_16x16x32_bf16 v[46:49], v[134:137], v[186:189], v[46:49]
	v_mfma_f32_16x16x32_bf16 v[30:33], v[134:137], v[204:207], v[30:33]
	v_mfma_f32_16x16x32_bf16 v[30:33], v[138:141], v[208:211], v[30:33]
	v_mfma_f32_16x16x32_bf16 v[26:29], v[146:149], v[208:211], v[26:29]
	v_mfma_f32_16x16x32_bf16 v[26:29], v[142:145], v[204:207], v[26:29]
	v_mfma_f32_16x16x32_bf16 v[22:25], v[150:153], v[204:207], v[22:25]
	v_mfma_f32_16x16x32_bf16 v[22:25], v[154:157], v[208:211], v[22:25]
	v_mfma_f32_16x16x32_bf16 v[18:21], v[174:177], v[208:211], v[18:21]
	v_mfma_f32_16x16x32_bf16 v[18:21], v[158:161], v[204:207], v[18:21]
	v_mfma_f32_16x16x32_bf16 v[2:5], v[158:161], v[212:215], v[2:5]
	v_mfma_f32_16x16x32_bf16 v[2:5], v[174:177], v[216:219], v[2:5]
	v_mfma_f32_16x16x32_bf16 v[6:9], v[154:157], v[216:219], v[6:9]
	v_mfma_f32_16x16x32_bf16 v[6:9], v[150:153], v[212:215], v[6:9]
	v_mfma_f32_16x16x32_bf16 v[10:13], v[142:145], v[212:215], v[10:13]
	v_mfma_f32_16x16x32_bf16 v[10:13], v[146:149], v[216:219], v[10:13]
	v_mfma_f32_16x16x32_bf16 v[14:17], v[138:141], v[216:219], v[14:17]
	v_mfma_f32_16x16x32_bf16 v[14:17], v[134:137], v[212:215], v[14:17]
	s_waitcnt vmcnt(8)
	s_barrier
	s_add_i32 s0, 0, 0x18000
	s_add_i32 s1, 0, 0x1c000
	v_add_u32_e32 v146, s0, v1
	v_add_u32_e32 v174, s1, v1
	ds_read_b128 v[134:137], v146
	ds_read_b128 v[138:141], v146 offset:1024
	ds_read_b128 v[142:145], v146 offset:2048
	ds_read_b128 v[146:149], v146 offset:3072
	ds_read_b128 v[150:153], v174
	ds_read_b128 v[154:157], v174 offset:1024
	ds_read_b128 v[158:161], v174 offset:2048
	ds_read_b128 v[174:177], v174 offset:3072
	s_add_u32 s44, vcc_lo, 0x80000
	s_addc_u32 s45, vcc_hi, 0
	s_mov_b32 m0, s8
	ds_read_b128 v[178:181], v222 offset:32768
	ds_read_b128 v[182:185], v222 offset:33792
	ds_read_b128 v[186:189], v222 offset:34816
	ds_read_b128 v[190:193], v222 offset:35840
	ds_read_b128 v[204:207], v222 offset:36864
	ds_read_b128 v[208:211], v222 offset:37888
	ds_read_b128 v[212:215], v222 offset:38912
	ds_read_b128 v[216:219], v222 offset:39936
	global_load_lds_dwordx4 v164, s[44:45]
	s_mov_b32 m0, s9
	s_nop 0
	global_load_lds_dwordx4 v162, s[44:45]
	s_waitcnt lgkmcnt(0)
	s_barrier
	s_waitcnt lgkmcnt(0)
	v_mfma_f32_16x16x32_bf16 v[126:129], v[134:137], v[178:181], v[126:129]
	v_mfma_f32_16x16x32_bf16 v[126:129], v[138:141], v[182:185], v[126:129]
	v_mfma_f32_16x16x32_bf16 v[122:125], v[146:149], v[182:185], v[122:125]
	v_mfma_f32_16x16x32_bf16 v[122:125], v[142:145], v[178:181], v[122:125]
	v_mfma_f32_16x16x32_bf16 v[118:121], v[150:153], v[178:181], v[118:121]
	v_mfma_f32_16x16x32_bf16 v[118:121], v[154:157], v[182:185], v[118:121]
	v_mfma_f32_16x16x32_bf16 v[114:117], v[174:177], v[182:185], v[114:117]
	v_mfma_f32_16x16x32_bf16 v[114:117], v[158:161], v[178:181], v[114:117]
	v_mfma_f32_16x16x32_bf16 v[98:101], v[158:161], v[186:189], v[98:101]
	v_mfma_f32_16x16x32_bf16 v[98:101], v[174:177], v[190:193], v[98:101]
	v_mfma_f32_16x16x32_bf16 v[102:105], v[154:157], v[190:193], v[102:105]
	v_mfma_f32_16x16x32_bf16 v[102:105], v[150:153], v[186:189], v[102:105]
	v_mfma_f32_16x16x32_bf16 v[106:109], v[142:145], v[186:189], v[106:109]
	v_mfma_f32_16x16x32_bf16 v[106:109], v[146:149], v[190:193], v[106:109]
	v_mfma_f32_16x16x32_bf16 v[110:113], v[138:141], v[190:193], v[110:113]
	v_mfma_f32_16x16x32_bf16 v[110:113], v[134:137], v[186:189], v[110:113]
	v_mfma_f32_16x16x32_bf16 v[94:97], v[134:137], v[204:207], v[94:97]
	v_mfma_f32_16x16x32_bf16 v[94:97], v[138:141], v[208:211], v[94:97]
	v_mfma_f32_16x16x32_bf16 v[90:93], v[146:149], v[208:211], v[90:93]
	v_mfma_f32_16x16x32_bf16 v[90:93], v[142:145], v[204:207], v[90:93]
	v_mfma_f32_16x16x32_bf16 v[86:89], v[150:153], v[204:207], v[86:89]
	v_mfma_f32_16x16x32_bf16 v[86:89], v[154:157], v[208:211], v[86:89]
	v_mfma_f32_16x16x32_bf16 v[82:85], v[174:177], v[208:211], v[82:85]
	v_mfma_f32_16x16x32_bf16 v[82:85], v[158:161], v[204:207], v[82:85]
	v_mfma_f32_16x16x32_bf16 v[66:69], v[158:161], v[212:215], v[66:69]
	v_mfma_f32_16x16x32_bf16 v[66:69], v[174:177], v[216:219], v[66:69]
	v_mfma_f32_16x16x32_bf16 v[70:73], v[154:157], v[216:219], v[70:73]
	v_mfma_f32_16x16x32_bf16 v[70:73], v[150:153], v[212:215], v[70:73]
	v_mfma_f32_16x16x32_bf16 v[74:77], v[142:145], v[212:215], v[74:77]
	v_mfma_f32_16x16x32_bf16 v[74:77], v[146:149], v[216:219], v[74:77]
	v_mfma_f32_16x16x32_bf16 v[78:81], v[138:141], v[216:219], v[78:81]
	v_mfma_f32_16x16x32_bf16 v[78:81], v[134:137], v[212:215], v[78:81]
	s_waitcnt vmcnt(8)
	s_barrier
	s_add_u32 s98, s70, 0x80
	s_addc_u32 s99, s71, 0
	s_add_u32 s100, vcc_lo, 0x80
	s_addc_u32 s101, vcc_hi, 0
	s_add_i32 s0, s0, s54
	s_mov_b32 m0, s0
	ds_read_b128 v[178:181], v222 offset:49152
	ds_read_b128 v[182:185], v222 offset:50176
	ds_read_b128 v[186:189], v222 offset:51200
	ds_read_b128 v[190:193], v222 offset:52224
	ds_read_b128 v[204:207], v222 offset:53248
	ds_read_b128 v[208:211], v222 offset:54272
	ds_read_b128 v[212:215], v222 offset:55296
	ds_read_b128 v[216:219], v222 offset:56320
	global_load_lds_dwordx4 v164, s[98:99]
	s_add_i32 m0, s0, 0x2000
	s_add_u32 s44, s70, 0x80080
	s_addc_u32 s45, s71, 0
	s_add_i32 s0, s1, s54
	global_load_lds_dwordx4 v162, s[98:99]
	s_mov_b32 m0, s0
	s_nop 0
	global_load_lds_dwordx4 v164, s[44:45]
	s_add_i32 m0, s0, 0x2000
	s_nop 0
	global_load_lds_dwordx4 v162, s[44:45]
	s_mov_b32 m0, s27
	s_nop 0
	global_load_lds_dwordx4 v164, s[100:101]
	s_mov_b32 m0, s26
	s_nop 0
	global_load_lds_dwordx4 v162, s[100:101]
	s_waitcnt lgkmcnt(0)
	s_barrier
	s_waitcnt lgkmcnt(0)
	v_mfma_f32_16x16x32_bf16 v[62:65], v[134:137], v[178:181], v[62:65]
	v_mfma_f32_16x16x32_bf16 v[62:65], v[138:141], v[182:185], v[62:65]
	v_mfma_f32_16x16x32_bf16 v[58:61], v[146:149], v[182:185], v[58:61]
	v_mfma_f32_16x16x32_bf16 v[58:61], v[142:145], v[178:181], v[58:61]
	v_mfma_f32_16x16x32_bf16 v[54:57], v[150:153], v[178:181], v[54:57]
	v_mfma_f32_16x16x32_bf16 v[54:57], v[154:157], v[182:185], v[54:57]
	v_mfma_f32_16x16x32_bf16 v[50:53], v[174:177], v[182:185], v[50:53]
	v_mfma_f32_16x16x32_bf16 v[50:53], v[158:161], v[178:181], v[50:53]
	v_mfma_f32_16x16x32_bf16 v[34:37], v[158:161], v[186:189], v[34:37]
	v_mfma_f32_16x16x32_bf16 v[34:37], v[174:177], v[190:193], v[34:37]
	v_mfma_f32_16x16x32_bf16 v[38:41], v[154:157], v[190:193], v[38:41]
	v_mfma_f32_16x16x32_bf16 v[38:41], v[150:153], v[186:189], v[38:41]
	v_mfma_f32_16x16x32_bf16 v[42:45], v[142:145], v[186:189], v[42:45]
	v_mfma_f32_16x16x32_bf16 v[42:45], v[146:149], v[190:193], v[42:45]
	v_mfma_f32_16x16x32_bf16 v[46:49], v[138:141], v[190:193], v[46:49]
	v_mfma_f32_16x16x32_bf16 v[46:49], v[134:137], v[186:189], v[46:49]
	v_mfma_f32_16x16x32_bf16 v[30:33], v[134:137], v[204:207], v[30:33]
	v_mfma_f32_16x16x32_bf16 v[30:33], v[138:141], v[208:211], v[30:33]
	v_mfma_f32_16x16x32_bf16 v[26:29], v[146:149], v[208:211], v[26:29]
	v_mfma_f32_16x16x32_bf16 v[26:29], v[142:145], v[204:207], v[26:29]
	v_mfma_f32_16x16x32_bf16 v[22:25], v[150:153], v[204:207], v[22:25]
	v_mfma_f32_16x16x32_bf16 v[22:25], v[154:157], v[208:211], v[22:25]
	v_mfma_f32_16x16x32_bf16 v[18:21], v[174:177], v[208:211], v[18:21]
	v_mfma_f32_16x16x32_bf16 v[18:21], v[158:161], v[204:207], v[18:21]
	v_mfma_f32_16x16x32_bf16 v[2:5], v[158:161], v[212:215], v[2:5]
	v_mfma_f32_16x16x32_bf16 v[2:5], v[174:177], v[216:219], v[2:5]
	v_mfma_f32_16x16x32_bf16 v[6:9], v[154:157], v[216:219], v[6:9]
	v_mfma_f32_16x16x32_bf16 v[6:9], v[150:153], v[212:215], v[6:9]
	v_mfma_f32_16x16x32_bf16 v[10:13], v[142:145], v[212:215], v[10:13]
	v_mfma_f32_16x16x32_bf16 v[10:13], v[146:149], v[216:219], v[10:13]
	v_mfma_f32_16x16x32_bf16 v[14:17], v[138:141], v[216:219], v[14:17]
	v_mfma_f32_16x16x32_bf16 v[14:17], v[134:137], v[212:215], v[14:17]
	s_waitcnt vmcnt(8)
	s_barrier
	s_add_i32 s43, s43, 2
	s_add_u32 s76, s76, 0x100
	s_addc_u32 s77, s77, 0
	s_add_u32 s7, s7, 0x100
	s_addc_u32 s41, s41, 0
	s_cmp_gt_u32 s43, 29
	s_cbranch_scc1 .LBB0_288
	s_branch .LBB0_286

.LBB0_495:
	v_readlane_b32 s4, v254, 1
	v_readlane_b32 s5, v254, 2
	s_cmp_le_i32 s4, s8
	s_cselect_b64 s[0:1], -1, 0
	s_cmp_lt_i32 s8, s5
	s_cselect_b64 s[4:5], -1, 0
	s_and_b64 s[0:1], s[0:1], s[4:5]
	s_andn2_b64 vcc, exec, s[0:1]
	v_readlane_b32 s0, v254, 18
	v_readlane_b32 s1, v254, 19
	v_readlane_b32 s6, v254, 3
	v_readlane_b32 s7, v254, 4
	v_cndmask_b32_e64 v1, 0, 1, s[0:1]
	v_cmp_ne_u32_e64 s[4:5], 1, v1
	s_cbranch_vccnz .LBB0_534
	v_mov_b32_e32 v1, v0
	s_mov_b32 s6, 19
	s_and_b64 vcc, exec, s[4:5]
	v_readfirstlane_b32 s22, v1
	s_cbranch_vccnz .LBB0_534
	v_lshlrev_b32_e32 v10, 4, v1
	v_add_u32_e32 v2, 0x2000, v10
	v_ashrrev_i32_e32 v3, 31, v2
	v_lshrrev_b32_e32 v3, 22, v3
	v_add_u32_e32 v3, v2, v3
	v_ashrrev_i32_e32 v11, 10, v3
	v_mul_i32_i24_e32 v3, 0x400, v11
	v_sub_u32_e32 v2, v2, v3
	s_ashr_i32 s7, s6, 31
	v_lshrrev_b32_e32 v3, 4, v2
	s_lshl_b64 s[0:1], s[6:7], 3
	v_readlane_b32 s6, v254, 7
	v_bitop3_b32 v2, v3, v2, 32 bitop3:0x6c
	v_readlane_b32 s7, v254, 8
	s_add_u32 s0, s6, s0
	v_ashrrev_i32_e32 v3, 31, v2
	s_addc_u32 s1, s7, s1
	v_lshrrev_b32_e32 v3, 26, v3
	s_load_dwordx2 s[6:7], s[0:1], 0x0
	v_add_u32_e32 v3, v2, v3
	v_ashrrev_i32_e32 v12, 6, v3
	v_and_b32_e32 v3, 0xc0, v3
	v_sub_u32_e32 v2, v2, v3
	v_ashrrev_i16_sdwa v2, v233, sext(v2) dst_sel:DWORD dst_unused:UNUSED_PAD src0_sel:DWORD src1_sel:BYTE_0
	v_bfe_i32 v14, v2, 0, 16
	v_bfe_i32 v2, v1, 27, 1
	s_waitcnt lgkmcnt(0)
	s_add_u32 s20, s6, 0x3b000000
	v_readlane_b32 s0, v254, 27
	v_lshrrev_b32_e32 v2, 22, v2
	s_addc_u32 s21, s7, 0
	s_lshl_b32 s8, s0, 23
	v_readlane_b32 s0, v254, 16
	v_lshlrev_b32_e32 v4, 3, v11
	v_add_u32_e32 v2, v10, v2
	v_readlane_b32 s1, v254, 17
	v_and_b32_e32 v4, 0xffff0, v4
	v_lshlrev_b32_e32 v5, 5, v11
	v_and_b32_e32 v2, 0xfffffc00, v2
	s_and_b64 s[0:1], s[0:1], exec
	v_add_u32_e32 v4, v12, v4
	v_and_b32_e32 v13, 32, v5
	v_sub_u32_e32 v2, v10, v2
	s_mov_b32 s0, 0x5800000
	v_lshl_or_b32 v4, v4, 11, v13
	v_lshrrev_b32_e32 v3, 4, v2
	s_cselect_b32 s0, s0, 0x9800000
	v_add_lshl_u32 v204, v4, v14, 1
	v_bitop3_b32 v2, v3, v2, 32 bitop3:0x6c
	v_ashrrev_i32_e32 v4, 31, v1
	s_add_u32 s0, s6, s0
	v_ashrrev_i32_e32 v3, 31, v2
	v_lshrrev_b32_e32 v4, 26, v4
	s_addc_u32 s1, s7, 0
	v_lshrrev_b32_e32 v3, 26, v3
	v_add_u32_e32 v4, v1, v4
	s_add_u32 s26, s0, s8
	v_add_u32_e32 v3, v2, v3
	v_ashrrev_i32_e32 v16, 6, v4
	s_addc_u32 s27, s1, 0
	s_ashr_i32 s23, s22, 6
	v_ashrrev_i32_e32 v15, 6, v3
	v_lshlrev_b32_e32 v4, 3, v16
	v_and_b32_e32 v3, 0xc0, v3
	s_ashr_i32 s40, s22, 8
	s_ashr_i32 s98, s22, 8
	s_lshl_b32 s28, s23, 10
	v_and_b32_e32 v4, 0xffff0, v4
	v_lshlrev_b32_e32 v5, 5, v16
	v_sub_u32_e32 v2, v2, v3
	v_readlane_b32 s0, v255, 10
	v_add_u32_e32 v4, v15, v4
	v_and_b32_e32 v17, 32, v5
	v_ashrrev_i16_sdwa v2, v233, sext(v2) dst_sel:DWORD dst_unused:UNUSED_PAD src0_sel:DWORD src1_sel:BYTE_0
	v_readlane_b32 s1, v255, 11
	s_add_u32 s90, s26, s0
	v_lshl_or_b32 v4, v4, 11, v17
	v_bfe_i32 v18, v2, 0, 16
	s_addc_u32 s91, s27, s1
	s_add_i32 s29, s28, 0
	v_add_lshl_u32 v194, v4, v18, 1
	s_add_i32 m0, s29, 0x10000
	v_mov_b32_e32 v205, v195
	global_load_lds_dwordx4 v194, s[90:91]
	s_add_i32 m0, s29, 0x12000
	s_add_u32 s0, s90, 0x80000
	global_load_lds_dwordx4 v204, s[90:91]
	s_addc_u32 s1, s91, 0
	s_add_i32 m0, s29, 0x14000
	v_lshl_add_u64 v[8:9], s[90:91], 0, v[194:195]
	global_load_lds_dwordx4 v194, s[0:1]
	s_add_i32 m0, s29, 0x16000
	v_lshl_add_u64 v[6:7], s[90:91], 0, v[204:205]
	global_load_lds_dwordx4 v204, s[0:1]
	v_readlane_b32 s0, v255, 8
	v_readlane_b32 s1, v255, 9
	s_add_u32 s76, s20, s0
	s_addc_u32 s77, s21, s1
	s_add_i32 s31, s29, 0x2000
	s_mov_b32 m0, s29
	s_add_u32 s0, s76, 0x80000
	global_load_lds_dwordx4 v194, s[76:77]
	s_mov_b32 m0, s31
	s_addc_u32 s1, s77, 0
	s_add_i32 s33, s29, 0x4000
	global_load_lds_dwordx4 v204, s[76:77]
	s_mov_b32 m0, s33
	s_add_i32 s43, s29, 0x6000
	global_load_lds_dwordx4 v194, s[0:1]
	s_mov_b32 m0, s43
	s_cmp_eq_u32 s40, 1
	global_load_lds_dwordx4 v204, s[0:1]
	v_lshl_add_u64 v[2:3], s[76:77], 0, v[194:195]
	s_cselect_b64 s[8:9], -1, 0
	s_cmp_lg_u32 s40, 1
	v_lshl_add_u64 v[4:5], s[76:77], 0, v[204:205]
	s_cbranch_scc1 .LBB0_499
	s_barrier

.Lpeel_disp_out:
	s_cmp_lg_u32 s57, -2
	s_cbranch_scc1 .Llw_main_out
	s_cmp_eq_u32 s98, 0
	s_cbranch_scc1 .Llw_p0_out
	s_add_u32 s90, s76, 0x100
	s_addc_u32 s91, s77, 0
	s_and_b64 s[0:1], s[70:71], exec
	s_cselect_b32 vcc_hi, s22, s91
	s_cselect_b32 vcc_lo, s23, s90
	s_cselect_b32 s71, s41, s53
	s_cselect_b32 s70, s44, s51
	s_add_i32 s0, 0, 0x10000
	s_add_i32 s18, 0, 0x14000
	v_add_u32_e32 v114, s0, v1
	v_add_u32_e32 v154, s18, v1
	ds_read_b128 v[78:81], v114
	ds_read_b128 v[90:93], v114 offset:1024
	ds_read_b128 v[102:105], v114 offset:2048
	ds_read_b128 v[114:117], v114 offset:3072
	ds_read_b128 v[126:129], v154
	ds_read_b128 v[134:137], v154 offset:1024
	ds_read_b128 v[142:145], v154 offset:2048
	ds_read_b128 v[154:157], v154 offset:3072
	s_add_i32 m0, s29, 0xc000
	ds_read_b128 v[158:161], v237
	ds_read_b128 v[162:165], v237 offset:1024
	ds_read_b128 v[166:169], v237 offset:2048
	ds_read_b128 v[178:181], v237 offset:3072
	ds_read_b128 v[182:185], v237 offset:4096
	ds_read_b128 v[186:189], v237 offset:5120
	ds_read_b128 v[190:193], v237 offset:6144
	ds_read_b128 v[214:217], v237 offset:7168
	global_load_lds_dwordx4 v210, s[76:77]
	s_add_i32 m0, s29, 0xe000
	s_nop 0
	global_load_lds_dwordx4 v212, s[76:77]
	s_waitcnt vmcnt(8)
	s_waitcnt lgkmcnt(0)
	s_barrier
	s_waitcnt lgkmcnt(0)
	v_mfma_f32_16x16x32_bf16 v[174:177], v[78:81], v[158:161], 0
	v_mfma_f32_16x16x32_bf16 v[174:177], v[90:93], v[162:165], v[174:177]
	v_mfma_f32_16x16x32_bf16 v[170:173], v[114:117], v[162:165], 0
	v_mfma_f32_16x16x32_bf16 v[170:173], v[102:105], v[158:161], v[170:173]
	v_mfma_f32_16x16x32_bf16 v[150:153], v[126:129], v[158:161], 0
	v_mfma_f32_16x16x32_bf16 v[150:153], v[134:137], v[162:165], v[150:153]
	v_mfma_f32_16x16x32_bf16 v[146:149], v[154:157], v[162:165], 0
	v_mfma_f32_16x16x32_bf16 v[146:149], v[142:145], v[158:161], v[146:149]
	v_mfma_f32_16x16x32_bf16 v[118:121], v[142:145], v[166:169], 0
	v_mfma_f32_16x16x32_bf16 v[118:121], v[154:157], v[178:181], v[118:121]
	v_mfma_f32_16x16x32_bf16 v[122:125], v[134:137], v[178:181], 0
	v_mfma_f32_16x16x32_bf16 v[122:125], v[126:129], v[166:169], v[122:125]
	v_mfma_f32_16x16x32_bf16 v[130:133], v[102:105], v[166:169], 0
	v_mfma_f32_16x16x32_bf16 v[130:133], v[114:117], v[178:181], v[130:133]
	v_mfma_f32_16x16x32_bf16 v[138:141], v[90:93], v[178:181], 0
	v_mfma_f32_16x16x32_bf16 v[138:141], v[78:81], v[166:169], v[138:141]
	v_mfma_f32_16x16x32_bf16 v[110:113], v[78:81], v[182:185], 0
	v_mfma_f32_16x16x32_bf16 v[110:113], v[90:93], v[186:189], v[110:113]
	v_mfma_f32_16x16x32_bf16 v[106:109], v[114:117], v[186:189], 0
	v_mfma_f32_16x16x32_bf16 v[106:109], v[102:105], v[182:185], v[106:109]
	v_mfma_f32_16x16x32_bf16 v[98:101], v[126:129], v[182:185], 0
	v_mfma_f32_16x16x32_bf16 v[98:101], v[134:137], v[186:189], v[98:101]
	v_mfma_f32_16x16x32_bf16 v[94:97], v[154:157], v[186:189], 0
	v_mfma_f32_16x16x32_bf16 v[94:97], v[142:145], v[182:185], v[94:97]
	v_mfma_f32_16x16x32_bf16 v[66:69], v[142:145], v[190:193], 0
	v_mfma_f32_16x16x32_bf16 v[66:69], v[154:157], v[214:217], v[66:69]
	v_mfma_f32_16x16x32_bf16 v[74:77], v[134:137], v[214:217], 0
	v_mfma_f32_16x16x32_bf16 v[74:77], v[126:129], v[190:193], v[74:77]
	v_mfma_f32_16x16x32_bf16 v[82:85], v[102:105], v[190:193], 0
	v_mfma_f32_16x16x32_bf16 v[82:85], v[114:117], v[214:217], v[82:85]
	v_mfma_f32_16x16x32_bf16 v[86:89], v[90:93], v[214:217], 0
	v_mfma_f32_16x16x32_bf16 v[86:89], v[78:81], v[190:193], v[86:89]
	s_barrier
	s_add_i32 s0, s0, s28
	s_mov_b32 m0, s0
	ds_read_b128 v[158:161], v237 offset:16384
	ds_read_b128 v[162:165], v237 offset:17408
	ds_read_b128 v[166:169], v237 offset:18432
	ds_read_b128 v[178:181], v237 offset:19456
	ds_read_b128 v[182:185], v237 offset:20480
	ds_read_b128 v[186:189], v237 offset:21504
	ds_read_b128 v[190:193], v237 offset:22528
	ds_read_b128 v[214:217], v237 offset:23552
	global_load_lds_dwordx4 v194, s[70:71]
	s_add_i32 m0, s0, 0x2000
	s_add_u32 s0, s70, 0x80000
	s_addc_u32 s1, s71, 0
	s_add_i32 s18, s18, s28
	global_load_lds_dwordx4 v204, s[70:71]
	s_mov_b32 m0, s18
	s_nop 0
	global_load_lds_dwordx4 v194, s[0:1]
	s_add_i32 m0, s18, 0x2000
	s_nop 0
	global_load_lds_dwordx4 v204, s[0:1]
	s_mov_b32 m0, s29
	s_nop 0
	global_load_lds_dwordx4 v194, vcc
	s_mov_b32 m0, s31
	s_nop 0
	global_load_lds_dwordx4 v204, vcc
	s_waitcnt vmcnt(8)
	s_waitcnt lgkmcnt(0)
	s_barrier
	s_waitcnt lgkmcnt(0)
	v_mfma_f32_16x16x32_bf16 v[62:65], v[78:81], v[158:161], 0
	v_mfma_f32_16x16x32_bf16 v[62:65], v[90:93], v[162:165], v[62:65]
	v_mfma_f32_16x16x32_bf16 v[58:61], v[114:117], v[162:165], 0
	v_mfma_f32_16x16x32_bf16 v[58:61], v[102:105], v[158:161], v[58:61]
	v_mfma_f32_16x16x32_bf16 v[54:57], v[126:129], v[158:161], 0
	v_mfma_f32_16x16x32_bf16 v[54:57], v[134:137], v[162:165], v[54:57]
	v_mfma_f32_16x16x32_bf16 v[50:53], v[154:157], v[162:165], 0
	v_mfma_f32_16x16x32_bf16 v[50:53], v[142:145], v[158:161], v[50:53]
	v_mfma_f32_16x16x32_bf16 v[34:37], v[142:145], v[166:169], 0
	v_mfma_f32_16x16x32_bf16 v[34:37], v[154:157], v[178:181], v[34:37]
	v_mfma_f32_16x16x32_bf16 v[38:41], v[134:137], v[178:181], 0
	v_mfma_f32_16x16x32_bf16 v[38:41], v[126:129], v[166:169], v[38:41]
	v_mfma_f32_16x16x32_bf16 v[42:45], v[102:105], v[166:169], 0
	v_mfma_f32_16x16x32_bf16 v[42:45], v[114:117], v[178:181], v[42:45]
	v_mfma_f32_16x16x32_bf16 v[46:49], v[90:93], v[178:181], 0
	v_mfma_f32_16x16x32_bf16 v[46:49], v[78:81], v[166:169], v[46:49]
	v_mfma_f32_16x16x32_bf16 v[30:33], v[78:81], v[182:185], 0
	v_mfma_f32_16x16x32_bf16 v[30:33], v[90:93], v[186:189], v[30:33]
	v_mfma_f32_16x16x32_bf16 v[26:29], v[114:117], v[186:189], 0
	v_mfma_f32_16x16x32_bf16 v[26:29], v[102:105], v[182:185], v[26:29]
	v_mfma_f32_16x16x32_bf16 v[22:25], v[126:129], v[182:185], 0
	v_mfma_f32_16x16x32_bf16 v[22:25], v[134:137], v[186:189], v[22:25]
	v_mfma_f32_16x16x32_bf16 v[18:21], v[154:157], v[186:189], 0
	v_mfma_f32_16x16x32_bf16 v[18:21], v[142:145], v[182:185], v[18:21]
	v_mfma_f32_16x16x32_bf16 v[2:5], v[142:145], v[190:193], 0
	v_mfma_f32_16x16x32_bf16 v[2:5], v[154:157], v[214:217], v[2:5]
	v_mfma_f32_16x16x32_bf16 v[6:9], v[134:137], v[214:217], 0
	v_mfma_f32_16x16x32_bf16 v[6:9], v[126:129], v[190:193], v[6:9]
	v_mfma_f32_16x16x32_bf16 v[10:13], v[102:105], v[190:193], 0
	v_mfma_f32_16x16x32_bf16 v[10:13], v[114:117], v[214:217], v[10:13]
	v_mfma_f32_16x16x32_bf16 v[14:17], v[90:93], v[214:217], 0
	v_mfma_f32_16x16x32_bf16 v[14:17], v[78:81], v[190:193], v[14:17]
	s_barrier
	s_add_i32 s18, 0, 0x18000
	s_add_i32 s19, 0, 0x1c000
	v_add_u32_e32 v114, s18, v1
	v_add_u32_e32 v154, s19, v1
	ds_read_b128 v[78:81], v114
	ds_read_b128 v[90:93], v114 offset:1024
	ds_read_b128 v[102:105], v114 offset:2048
	ds_read_b128 v[114:117], v114 offset:3072
	ds_read_b128 v[126:129], v154
	ds_read_b128 v[134:137], v154 offset:1024
	ds_read_b128 v[142:145], v154 offset:2048
	ds_read_b128 v[154:157], v154 offset:3072
	s_add_u32 s0, vcc_lo, 0x80000
	s_addc_u32 s1, vcc_hi, 0
	s_mov_b32 m0, s33
	ds_read_b128 v[158:161], v237 offset:32768
	ds_read_b128 v[162:165], v237 offset:33792
	ds_read_b128 v[166:169], v237 offset:34816
	ds_read_b128 v[178:181], v237 offset:35840
	ds_read_b128 v[182:185], v237 offset:36864
	ds_read_b128 v[186:189], v237 offset:37888
	ds_read_b128 v[190:193], v237 offset:38912
	ds_read_b128 v[214:217], v237 offset:39936
	global_load_lds_dwordx4 v194, s[0:1]
	s_mov_b32 m0, s43
	s_nop 0
	global_load_lds_dwordx4 v204, s[0:1]
	s_waitcnt vmcnt(8)
	s_waitcnt lgkmcnt(0)
	s_barrier
	s_waitcnt lgkmcnt(0)
	v_mfma_f32_16x16x32_bf16 v[174:177], v[78:81], v[158:161], v[174:177]
	v_mfma_f32_16x16x32_bf16 v[174:177], v[90:93], v[162:165], v[174:177]
	v_mfma_f32_16x16x32_bf16 v[170:173], v[114:117], v[162:165], v[170:173]
	v_mfma_f32_16x16x32_bf16 v[170:173], v[102:105], v[158:161], v[170:173]
	v_mfma_f32_16x16x32_bf16 v[150:153], v[126:129], v[158:161], v[150:153]
	v_mfma_f32_16x16x32_bf16 v[150:153], v[134:137], v[162:165], v[150:153]
	v_mfma_f32_16x16x32_bf16 v[146:149], v[154:157], v[162:165], v[146:149]
	v_mfma_f32_16x16x32_bf16 v[146:149], v[142:145], v[158:161], v[146:149]
	v_mfma_f32_16x16x32_bf16 v[118:121], v[142:145], v[166:169], v[118:121]
	v_mfma_f32_16x16x32_bf16 v[118:121], v[154:157], v[178:181], v[118:121]
	v_mfma_f32_16x16x32_bf16 v[122:125], v[134:137], v[178:181], v[122:125]
	v_mfma_f32_16x16x32_bf16 v[122:125], v[126:129], v[166:169], v[122:125]
	v_mfma_f32_16x16x32_bf16 v[130:133], v[102:105], v[166:169], v[130:133]
	v_mfma_f32_16x16x32_bf16 v[130:133], v[114:117], v[178:181], v[130:133]
	v_mfma_f32_16x16x32_bf16 v[138:141], v[90:93], v[178:181], v[138:141]
	v_mfma_f32_16x16x32_bf16 v[138:141], v[78:81], v[166:169], v[138:141]
	v_mfma_f32_16x16x32_bf16 v[110:113], v[78:81], v[182:185], v[110:113]
	v_mfma_f32_16x16x32_bf16 v[110:113], v[90:93], v[186:189], v[110:113]
	v_mfma_f32_16x16x32_bf16 v[106:109], v[114:117], v[186:189], v[106:109]
	v_mfma_f32_16x16x32_bf16 v[106:109], v[102:105], v[182:185], v[106:109]
	v_mfma_f32_16x16x32_bf16 v[98:101], v[126:129], v[182:185], v[98:101]
	v_mfma_f32_16x16x32_bf16 v[98:101], v[134:137], v[186:189], v[98:101]
	v_mfma_f32_16x16x32_bf16 v[94:97], v[154:157], v[186:189], v[94:97]
	v_mfma_f32_16x16x32_bf16 v[94:97], v[142:145], v[182:185], v[94:97]
	v_mfma_f32_16x16x32_bf16 v[66:69], v[142:145], v[190:193], v[66:69]
	v_mfma_f32_16x16x32_bf16 v[66:69], v[154:157], v[214:217], v[66:69]
	v_mfma_f32_16x16x32_bf16 v[74:77], v[134:137], v[214:217], v[74:77]
	v_mfma_f32_16x16x32_bf16 v[74:77], v[126:129], v[190:193], v[74:77]
	v_mfma_f32_16x16x32_bf16 v[82:85], v[102:105], v[190:193], v[82:85]
	v_mfma_f32_16x16x32_bf16 v[82:85], v[114:117], v[214:217], v[82:85]
	v_mfma_f32_16x16x32_bf16 v[86:89], v[90:93], v[214:217], v[86:89]
	v_mfma_f32_16x16x32_bf16 v[86:89], v[78:81], v[190:193], v[86:89]
	s_barrier
	s_add_u32 s98, s70, 0x80
	s_addc_u32 s99, s71, 0
	s_add_u32 s100, vcc_lo, 0x80
	s_addc_u32 s101, vcc_hi, 0
	s_add_i32 s0, s18, s28
	s_mov_b32 m0, s0
	ds_read_b128 v[158:161], v237 offset:49152
	ds_read_b128 v[162:165], v237 offset:50176
	ds_read_b128 v[166:169], v237 offset:51200
	ds_read_b128 v[178:181], v237 offset:52224
	ds_read_b128 v[182:185], v237 offset:53248
	ds_read_b128 v[186:189], v237 offset:54272
	ds_read_b128 v[190:193], v237 offset:55296
	ds_read_b128 v[214:217], v237 offset:56320
	global_load_lds_dwordx4 v194, s[98:99]
	s_add_i32 m0, s0, 0x2000
	s_add_u32 s0, s70, 0x80080
	s_addc_u32 s1, s71, 0
	s_add_i32 s18, s19, s28
	global_load_lds_dwordx4 v204, s[98:99]
	s_mov_b32 m0, s18
	s_nop 0
	global_load_lds_dwordx4 v194, s[0:1]
	s_add_i32 m0, s18, 0x2000
	s_nop 0
	global_load_lds_dwordx4 v204, s[0:1]
	s_mov_b32 m0, s68
	s_nop 0
	global_load_lds_dwordx4 v194, s[100:101]
	s_mov_b32 m0, s79
	s_nop 0
	global_load_lds_dwordx4 v204, s[100:101]
	s_waitcnt vmcnt(8)
	s_waitcnt lgkmcnt(0)
	s_barrier
	s_waitcnt lgkmcnt(0)
	v_mfma_f32_16x16x32_bf16 v[62:65], v[78:81], v[158:161], v[62:65]
	v_mfma_f32_16x16x32_bf16 v[62:65], v[90:93], v[162:165], v[62:65]
	v_mfma_f32_16x16x32_bf16 v[58:61], v[114:117], v[162:165], v[58:61]
	v_mfma_f32_16x16x32_bf16 v[58:61], v[102:105], v[158:161], v[58:61]
	v_mfma_f32_16x16x32_bf16 v[54:57], v[126:129], v[158:161], v[54:57]
	v_mfma_f32_16x16x32_bf16 v[54:57], v[134:137], v[162:165], v[54:57]
	v_mfma_f32_16x16x32_bf16 v[50:53], v[154:157], v[162:165], v[50:53]
	v_mfma_f32_16x16x32_bf16 v[50:53], v[142:145], v[158:161], v[50:53]
	v_mfma_f32_16x16x32_bf16 v[34:37], v[142:145], v[166:169], v[34:37]
	v_mfma_f32_16x16x32_bf16 v[34:37], v[154:157], v[178:181], v[34:37]
	v_mfma_f32_16x16x32_bf16 v[38:41], v[134:137], v[178:181], v[38:41]
	v_mfma_f32_16x16x32_bf16 v[38:41], v[126:129], v[166:169], v[38:41]
	v_mfma_f32_16x16x32_bf16 v[42:45], v[102:105], v[166:169], v[42:45]
	v_mfma_f32_16x16x32_bf16 v[42:45], v[114:117], v[178:181], v[42:45]
	v_mfma_f32_16x16x32_bf16 v[46:49], v[90:93], v[178:181], v[46:49]
	v_mfma_f32_16x16x32_bf16 v[46:49], v[78:81], v[166:169], v[46:49]
	v_mfma_f32_16x16x32_bf16 v[30:33], v[78:81], v[182:185], v[30:33]
	v_mfma_f32_16x16x32_bf16 v[30:33], v[90:93], v[186:189], v[30:33]
	v_mfma_f32_16x16x32_bf16 v[26:29], v[114:117], v[186:189], v[26:29]
	v_mfma_f32_16x16x32_bf16 v[26:29], v[102:105], v[182:185], v[26:29]
	v_mfma_f32_16x16x32_bf16 v[22:25], v[126:129], v[182:185], v[22:25]
	v_mfma_f32_16x16x32_bf16 v[22:25], v[134:137], v[186:189], v[22:25]
	v_mfma_f32_16x16x32_bf16 v[18:21], v[154:157], v[186:189], v[18:21]
	v_mfma_f32_16x16x32_bf16 v[18:21], v[142:145], v[182:185], v[18:21]
	v_mfma_f32_16x16x32_bf16 v[2:5], v[142:145], v[190:193], v[2:5]
	v_mfma_f32_16x16x32_bf16 v[2:5], v[154:157], v[214:217], v[2:5]
	v_mfma_f32_16x16x32_bf16 v[6:9], v[134:137], v[214:217], v[6:9]
	v_mfma_f32_16x16x32_bf16 v[6:9], v[126:129], v[190:193], v[6:9]
	v_mfma_f32_16x16x32_bf16 v[10:13], v[102:105], v[190:193], v[10:13]
	v_mfma_f32_16x16x32_bf16 v[10:13], v[114:117], v[214:217], v[10:13]
	v_mfma_f32_16x16x32_bf16 v[14:17], v[90:93], v[214:217], v[14:17]
	v_mfma_f32_16x16x32_bf16 v[14:17], v[78:81], v[190:193], v[14:17]
	s_barrier
	s_add_i32 s57, s57, 2
	s_add_u32 s51, s51, 0x100
	s_addc_u32 s53, s53, 0
	s_cmp_gt_u32 s57, 29
	s_mov_b64 s[76:77], s[90:91]
	s_cbranch_scc1 .LBB0_512
	s_branch .LBB0_510
.Llw_p0_out:
	s_add_u32 s90, s76, 0x100
	s_addc_u32 s91, s77, 0
	s_and_b64 s[0:1], s[70:71], exec
	s_cselect_b32 vcc_hi, s22, s91
	s_cselect_b32 vcc_lo, s23, s90
	s_cselect_b32 s71, s41, s53
	s_cselect_b32 s70, s44, s51
	s_add_i32 s0, 0, 0x10000
	s_add_i32 s18, 0, 0x14000
	v_add_u32_e32 v114, s0, v1
	v_add_u32_e32 v154, s18, v1
	ds_read_b128 v[78:81], v114
	ds_read_b128 v[90:93], v114 offset:1024
	ds_read_b128 v[102:105], v114 offset:2048
	ds_read_b128 v[114:117], v114 offset:3072
	ds_read_b128 v[126:129], v154
	ds_read_b128 v[134:137], v154 offset:1024
	ds_read_b128 v[142:145], v154 offset:2048
	ds_read_b128 v[154:157], v154 offset:3072
	s_add_i32 m0, s29, 0xc000
	ds_read_b128 v[158:161], v237
	ds_read_b128 v[162:165], v237 offset:1024
	ds_read_b128 v[166:169], v237 offset:2048
	ds_read_b128 v[178:181], v237 offset:3072
	ds_read_b128 v[182:185], v237 offset:4096
	ds_read_b128 v[186:189], v237 offset:5120
	ds_read_b128 v[190:193], v237 offset:6144
	ds_read_b128 v[214:217], v237 offset:7168
	global_load_lds_dwordx4 v210, s[76:77]
	s_add_i32 m0, s29, 0xe000
	s_nop 0
	global_load_lds_dwordx4 v212, s[76:77]
	s_waitcnt lgkmcnt(0)
	s_barrier
	s_waitcnt lgkmcnt(0)
	v_mfma_f32_16x16x32_bf16 v[174:177], v[78:81], v[158:161], 0
	v_mfma_f32_16x16x32_bf16 v[174:177], v[90:93], v[162:165], v[174:177]
	v_mfma_f32_16x16x32_bf16 v[170:173], v[114:117], v[162:165], 0
	v_mfma_f32_16x16x32_bf16 v[170:173], v[102:105], v[158:161], v[170:173]
	v_mfma_f32_16x16x32_bf16 v[150:153], v[126:129], v[158:161], 0
	v_mfma_f32_16x16x32_bf16 v[150:153], v[134:137], v[162:165], v[150:153]
	v_mfma_f32_16x16x32_bf16 v[146:149], v[154:157], v[162:165], 0
	v_mfma_f32_16x16x32_bf16 v[146:149], v[142:145], v[158:161], v[146:149]
	v_mfma_f32_16x16x32_bf16 v[118:121], v[142:145], v[166:169], 0
	v_mfma_f32_16x16x32_bf16 v[118:121], v[154:157], v[178:181], v[118:121]
	v_mfma_f32_16x16x32_bf16 v[122:125], v[134:137], v[178:181], 0
	v_mfma_f32_16x16x32_bf16 v[122:125], v[126:129], v[166:169], v[122:125]
	v_mfma_f32_16x16x32_bf16 v[130:133], v[102:105], v[166:169], 0
	v_mfma_f32_16x16x32_bf16 v[130:133], v[114:117], v[178:181], v[130:133]
	v_mfma_f32_16x16x32_bf16 v[138:141], v[90:93], v[178:181], 0
	v_mfma_f32_16x16x32_bf16 v[138:141], v[78:81], v[166:169], v[138:141]
	v_mfma_f32_16x16x32_bf16 v[110:113], v[78:81], v[182:185], 0
	v_mfma_f32_16x16x32_bf16 v[110:113], v[90:93], v[186:189], v[110:113]
	v_mfma_f32_16x16x32_bf16 v[106:109], v[114:117], v[186:189], 0
	v_mfma_f32_16x16x32_bf16 v[106:109], v[102:105], v[182:185], v[106:109]
	v_mfma_f32_16x16x32_bf16 v[98:101], v[126:129], v[182:185], 0
	v_mfma_f32_16x16x32_bf16 v[98:101], v[134:137], v[186:189], v[98:101]
	v_mfma_f32_16x16x32_bf16 v[94:97], v[154:157], v[186:189], 0
	v_mfma_f32_16x16x32_bf16 v[94:97], v[142:145], v[182:185], v[94:97]
	v_mfma_f32_16x16x32_bf16 v[66:69], v[142:145], v[190:193], 0
	v_mfma_f32_16x16x32_bf16 v[66:69], v[154:157], v[214:217], v[66:69]
	v_mfma_f32_16x16x32_bf16 v[74:77], v[134:137], v[214:217], 0
	v_mfma_f32_16x16x32_bf16 v[74:77], v[126:129], v[190:193], v[74:77]
	v_mfma_f32_16x16x32_bf16 v[82:85], v[102:105], v[190:193], 0
	v_mfma_f32_16x16x32_bf16 v[82:85], v[114:117], v[214:217], v[82:85]
	v_mfma_f32_16x16x32_bf16 v[86:89], v[90:93], v[214:217], 0
	v_mfma_f32_16x16x32_bf16 v[86:89], v[78:81], v[190:193], v[86:89]
	s_waitcnt vmcnt(8)
	s_barrier
	s_add_i32 s0, s0, s28
	s_mov_b32 m0, s0
	ds_read_b128 v[158:161], v237 offset:16384
	ds_read_b128 v[162:165], v237 offset:17408
	ds_read_b128 v[166:169], v237 offset:18432
	ds_read_b128 v[178:181], v237 offset:19456
	ds_read_b128 v[182:185], v237 offset:20480
	ds_read_b128 v[186:189], v237 offset:21504
	ds_read_b128 v[190:193], v237 offset:22528
	ds_read_b128 v[214:217], v237 offset:23552
	global_load_lds_dwordx4 v194, s[70:71]
	s_add_i32 m0, s0, 0x2000
	s_add_u32 s0, s70, 0x80000
	s_addc_u32 s1, s71, 0
	s_add_i32 s18, s18, s28
	global_load_lds_dwordx4 v204, s[70:71]
	s_mov_b32 m0, s18
	s_nop 0
	global_load_lds_dwordx4 v194, s[0:1]
	s_add_i32 m0, s18, 0x2000
	s_nop 0
	global_load_lds_dwordx4 v204, s[0:1]
	s_mov_b32 m0, s29
	s_nop 0
	global_load_lds_dwordx4 v194, vcc
	s_mov_b32 m0, s31
	s_nop 0
	global_load_lds_dwordx4 v204, vcc
	s_waitcnt lgkmcnt(0)
	s_barrier
	s_waitcnt lgkmcnt(0)
	v_mfma_f32_16x16x32_bf16 v[62:65], v[78:81], v[158:161], 0
	v_mfma_f32_16x16x32_bf16 v[62:65], v[90:93], v[162:165], v[62:65]
	v_mfma_f32_16x16x32_bf16 v[58:61], v[114:117], v[162:165], 0
	v_mfma_f32_16x16x32_bf16 v[58:61], v[102:105], v[158:161], v[58:61]
	v_mfma_f32_16x16x32_bf16 v[54:57], v[126:129], v[158:161], 0
	v_mfma_f32_16x16x32_bf16 v[54:57], v[134:137], v[162:165], v[54:57]
	v_mfma_f32_16x16x32_bf16 v[50:53], v[154:157], v[162:165], 0
	v_mfma_f32_16x16x32_bf16 v[50:53], v[142:145], v[158:161], v[50:53]
	v_mfma_f32_16x16x32_bf16 v[34:37], v[142:145], v[166:169], 0
	v_mfma_f32_16x16x32_bf16 v[34:37], v[154:157], v[178:181], v[34:37]
	v_mfma_f32_16x16x32_bf16 v[38:41], v[134:137], v[178:181], 0
	v_mfma_f32_16x16x32_bf16 v[38:41], v[126:129], v[166:169], v[38:41]
	v_mfma_f32_16x16x32_bf16 v[42:45], v[102:105], v[166:169], 0
	v_mfma_f32_16x16x32_bf16 v[42:45], v[114:117], v[178:181], v[42:45]
	v_mfma_f32_16x16x32_bf16 v[46:49], v[90:93], v[178:181], 0
	v_mfma_f32_16x16x32_bf16 v[46:49], v[78:81], v[166:169], v[46:49]
	v_mfma_f32_16x16x32_bf16 v[30:33], v[78:81], v[182:185], 0
	v_mfma_f32_16x16x32_bf16 v[30:33], v[90:93], v[186:189], v[30:33]
	v_mfma_f32_16x16x32_bf16 v[26:29], v[114:117], v[186:189], 0
	v_mfma_f32_16x16x32_bf16 v[26:29], v[102:105], v[182:185], v[26:29]
	v_mfma_f32_16x16x32_bf16 v[22:25], v[126:129], v[182:185], 0
	v_mfma_f32_16x16x32_bf16 v[22:25], v[134:137], v[186:189], v[22:25]
	v_mfma_f32_16x16x32_bf16 v[18:21], v[154:157], v[186:189], 0
	v_mfma_f32_16x16x32_bf16 v[18:21], v[142:145], v[182:185], v[18:21]
	v_mfma_f32_16x16x32_bf16 v[2:5], v[142:145], v[190:193], 0
	v_mfma_f32_16x16x32_bf16 v[2:5], v[154:157], v[214:217], v[2:5]
	v_mfma_f32_16x16x32_bf16 v[6:9], v[134:137], v[214:217], 0
	v_mfma_f32_16x16x32_bf16 v[6:9], v[126:129], v[190:193], v[6:9]
	v_mfma_f32_16x16x32_bf16 v[10:13], v[102:105], v[190:193], 0
	v_mfma_f32_16x16x32_bf16 v[10:13], v[114:117], v[214:217], v[10:13]
	v_mfma_f32_16x16x32_bf16 v[14:17], v[90:93], v[214:217], 0
	v_mfma_f32_16x16x32_bf16 v[14:17], v[78:81], v[190:193], v[14:17]
	s_waitcnt vmcnt(8)
	s_barrier
	s_add_i32 s18, 0, 0x18000
	s_add_i32 s19, 0, 0x1c000
	v_add_u32_e32 v114, s18, v1
	v_add_u32_e32 v154, s19, v1
	ds_read_b128 v[78:81], v114
	ds_read_b128 v[90:93], v114 offset:1024
	ds_read_b128 v[102:105], v114 offset:2048
	ds_read_b128 v[114:117], v114 offset:3072
	ds_read_b128 v[126:129], v154
	ds_read_b128 v[134:137], v154 offset:1024
	ds_read_b128 v[142:145], v154 offset:2048
	ds_read_b128 v[154:157], v154 offset:3072
	s_add_u32 s0, vcc_lo, 0x80000
	s_addc_u32 s1, vcc_hi, 0
	s_mov_b32 m0, s33
	ds_read_b128 v[158:161], v237 offset:32768
	ds_read_b128 v[162:165], v237 offset:33792
	ds_read_b128 v[166:169], v237 offset:34816
	ds_read_b128 v[178:181], v237 offset:35840
	ds_read_b128 v[182:185], v237 offset:36864
	ds_read_b128 v[186:189], v237 offset:37888
	ds_read_b128 v[190:193], v237 offset:38912
	ds_read_b128 v[214:217], v237 offset:39936
	global_load_lds_dwordx4 v194, s[0:1]
	s_mov_b32 m0, s43
	s_nop 0
	global_load_lds_dwordx4 v204, s[0:1]
	s_waitcnt lgkmcnt(0)
	s_barrier
	s_waitcnt lgkmcnt(0)
	v_mfma_f32_16x16x32_bf16 v[174:177], v[78:81], v[158:161], v[174:177]
	v_mfma_f32_16x16x32_bf16 v[174:177], v[90:93], v[162:165], v[174:177]
	v_mfma_f32_16x16x32_bf16 v[170:173], v[114:117], v[162:165], v[170:173]
	v_mfma_f32_16x16x32_bf16 v[170:173], v[102:105], v[158:161], v[170:173]
	v_mfma_f32_16x16x32_bf16 v[150:153], v[126:129], v[158:161], v[150:153]
	v_mfma_f32_16x16x32_bf16 v[150:153], v[134:137], v[162:165], v[150:153]
	v_mfma_f32_16x16x32_bf16 v[146:149], v[154:157], v[162:165], v[146:149]
	v_mfma_f32_16x16x32_bf16 v[146:149], v[142:145], v[158:161], v[146:149]
	v_mfma_f32_16x16x32_bf16 v[118:121], v[142:145], v[166:169], v[118:121]
	v_mfma_f32_16x16x32_bf16 v[118:121], v[154:157], v[178:181], v[118:121]
	v_mfma_f32_16x16x32_bf16 v[122:125], v[134:137], v[178:181], v[122:125]
	v_mfma_f32_16x16x32_bf16 v[122:125], v[126:129], v[166:169], v[122:125]
	v_mfma_f32_16x16x32_bf16 v[130:133], v[102:105], v[166:169], v[130:133]
	v_mfma_f32_16x16x32_bf16 v[130:133], v[114:117], v[178:181], v[130:133]
	v_mfma_f32_16x16x32_bf16 v[138:141], v[90:93], v[178:181], v[138:141]
	v_mfma_f32_16x16x32_bf16 v[138:141], v[78:81], v[166:169], v[138:141]
	v_mfma_f32_16x16x32_bf16 v[110:113], v[78:81], v[182:185], v[110:113]
	v_mfma_f32_16x16x32_bf16 v[110:113], v[90:93], v[186:189], v[110:113]
	v_mfma_f32_16x16x32_bf16 v[106:109], v[114:117], v[186:189], v[106:109]
	v_mfma_f32_16x16x32_bf16 v[106:109], v[102:105], v[182:185], v[106:109]
	v_mfma_f32_16x16x32_bf16 v[98:101], v[126:129], v[182:185], v[98:101]
	v_mfma_f32_16x16x32_bf16 v[98:101], v[134:137], v[186:189], v[98:101]
	v_mfma_f32_16x16x32_bf16 v[94:97], v[154:157], v[186:189], v[94:97]
	v_mfma_f32_16x16x32_bf16 v[94:97], v[142:145], v[182:185], v[94:97]
	v_mfma_f32_16x16x32_bf16 v[66:69], v[142:145], v[190:193], v[66:69]
	v_mfma_f32_16x16x32_bf16 v[66:69], v[154:157], v[214:217], v[66:69]
	v_mfma_f32_16x16x32_bf16 v[74:77], v[134:137], v[214:217], v[74:77]
	v_mfma_f32_16x16x32_bf16 v[74:77], v[126:129], v[190:193], v[74:77]
	v_mfma_f32_16x16x32_bf16 v[82:85], v[102:105], v[190:193], v[82:85]
	v_mfma_f32_16x16x32_bf16 v[82:85], v[114:117], v[214:217], v[82:85]
	v_mfma_f32_16x16x32_bf16 v[86:89], v[90:93], v[214:217], v[86:89]
	v_mfma_f32_16x16x32_bf16 v[86:89], v[78:81], v[190:193], v[86:89]
	s_waitcnt vmcnt(8)
	s_barrier
	s_add_u32 s98, s70, 0x80
	s_addc_u32 s99, s71, 0
	s_add_u32 s100, vcc_lo, 0x80
	s_addc_u32 s101, vcc_hi, 0
	s_add_i32 s0, s18, s28
	s_mov_b32 m0, s0
	ds_read_b128 v[158:161], v237 offset:49152
	ds_read_b128 v[162:165], v237 offset:50176
	ds_read_b128 v[166:169], v237 offset:51200
	ds_read_b128 v[178:181], v237 offset:52224
	ds_read_b128 v[182:185], v237 offset:53248
	ds_read_b128 v[186:189], v237 offset:54272
	ds_read_b128 v[190:193], v237 offset:55296
	ds_read_b128 v[214:217], v237 offset:56320
	global_load_lds_dwordx4 v194, s[98:99]
	s_add_i32 m0, s0, 0x2000
	s_add_u32 s0, s70, 0x80080
	s_addc_u32 s1, s71, 0
	s_add_i32 s18, s19, s28
	global_load_lds_dwordx4 v204, s[98:99]
	s_mov_b32 m0, s18
	s_nop 0
	global_load_lds_dwordx4 v194, s[0:1]
	s_add_i32 m0, s18, 0x2000
	s_nop 0
	global_load_lds_dwordx4 v204, s[0:1]
	s_mov_b32 m0, s68
	s_nop 0
	global_load_lds_dwordx4 v194, s[100:101]
	s_mov_b32 m0, s79
	s_nop 0
	global_load_lds_dwordx4 v204, s[100:101]
	s_waitcnt lgkmcnt(0)
	s_barrier
	s_waitcnt lgkmcnt(0)
	v_mfma_f32_16x16x32_bf16 v[62:65], v[78:81], v[158:161], v[62:65]
	v_mfma_f32_16x16x32_bf16 v[62:65], v[90:93], v[162:165], v[62:65]
	v_mfma_f32_16x16x32_bf16 v[58:61], v[114:117], v[162:165], v[58:61]
	v_mfma_f32_16x16x32_bf16 v[58:61], v[102:105], v[158:161], v[58:61]
	v_mfma_f32_16x16x32_bf16 v[54:57], v[126:129], v[158:161], v[54:57]
	v_mfma_f32_16x16x32_bf16 v[54:57], v[134:137], v[162:165], v[54:57]
	v_mfma_f32_16x16x32_bf16 v[50:53], v[154:157], v[162:165], v[50:53]
	v_mfma_f32_16x16x32_bf16 v[50:53], v[142:145], v[158:161], v[50:53]
	v_mfma_f32_16x16x32_bf16 v[34:37], v[142:145], v[166:169], v[34:37]
	v_mfma_f32_16x16x32_bf16 v[34:37], v[154:157], v[178:181], v[34:37]
	v_mfma_f32_16x16x32_bf16 v[38:41], v[134:137], v[178:181], v[38:41]
	v_mfma_f32_16x16x32_bf16 v[38:41], v[126:129], v[166:169], v[38:41]
	v_mfma_f32_16x16x32_bf16 v[42:45], v[102:105], v[166:169], v[42:45]
	v_mfma_f32_16x16x32_bf16 v[42:45], v[114:117], v[178:181], v[42:45]
	v_mfma_f32_16x16x32_bf16 v[46:49], v[90:93], v[178:181], v[46:49]
	v_mfma_f32_16x16x32_bf16 v[46:49], v[78:81], v[166:169], v[46:49]
	v_mfma_f32_16x16x32_bf16 v[30:33], v[78:81], v[182:185], v[30:33]
	v_mfma_f32_16x16x32_bf16 v[30:33], v[90:93], v[186:189], v[30:33]
	v_mfma_f32_16x16x32_bf16 v[26:29], v[114:117], v[186:189], v[26:29]
	v_mfma_f32_16x16x32_bf16 v[26:29], v[102:105], v[182:185], v[26:29]
	v_mfma_f32_16x16x32_bf16 v[22:25], v[126:129], v[182:185], v[22:25]
	v_mfma_f32_16x16x32_bf16 v[22:25], v[134:137], v[186:189], v[22:25]
	v_mfma_f32_16x16x32_bf16 v[18:21], v[154:157], v[186:189], v[18:21]
	v_mfma_f32_16x16x32_bf16 v[18:21], v[142:145], v[182:185], v[18:21]
	v_mfma_f32_16x16x32_bf16 v[2:5], v[142:145], v[190:193], v[2:5]
	v_mfma_f32_16x16x32_bf16 v[2:5], v[154:157], v[214:217], v[2:5]
	v_mfma_f32_16x16x32_bf16 v[6:9], v[134:137], v[214:217], v[6:9]
	v_mfma_f32_16x16x32_bf16 v[6:9], v[126:129], v[190:193], v[6:9]
	v_mfma_f32_16x16x32_bf16 v[10:13], v[102:105], v[190:193], v[10:13]
	v_mfma_f32_16x16x32_bf16 v[10:13], v[114:117], v[214:217], v[10:13]
	v_mfma_f32_16x16x32_bf16 v[14:17], v[90:93], v[214:217], v[14:17]
	v_mfma_f32_16x16x32_bf16 v[14:17], v[78:81], v[190:193], v[14:17]
	s_waitcnt vmcnt(8)
	s_barrier
	s_add_i32 s57, s57, 2
	s_add_u32 s51, s51, 0x100
	s_addc_u32 s53, s53, 0
	s_cmp_gt_u32 s57, 29
	s_mov_b64 s[76:77], s[90:91]
	s_cbranch_scc1 .LBB0_512
	s_branch .LBB0_510
.Llw_main_out:
	s_cmp_eq_u32 s98, 0
	s_cbranch_scc0 .LBB0_509
	s_add_u32 s90, s76, 0x100
	s_addc_u32 s91, s77, 0
	s_and_b64 s[0:1], s[70:71], exec
	s_cselect_b32 vcc_hi, s22, s91
	s_cselect_b32 vcc_lo, s23, s90
	s_cselect_b32 s71, s41, s53
	s_cselect_b32 s70, s44, s51
	s_add_i32 s0, 0, 0x10000
	s_add_i32 s18, 0, 0x14000
	v_add_u32_e32 v114, s0, v1
	v_add_u32_e32 v154, s18, v1
	ds_read_b128 v[78:81], v114
	ds_read_b128 v[90:93], v114 offset:1024
	ds_read_b128 v[102:105], v114 offset:2048
	ds_read_b128 v[114:117], v114 offset:3072
	ds_read_b128 v[126:129], v154
	ds_read_b128 v[134:137], v154 offset:1024
	ds_read_b128 v[142:145], v154 offset:2048
	ds_read_b128 v[154:157], v154 offset:3072
	s_add_i32 m0, s29, 0xc000
	ds_read_b128 v[158:161], v237
	ds_read_b128 v[162:165], v237 offset:1024
	ds_read_b128 v[166:169], v237 offset:2048
	ds_read_b128 v[178:181], v237 offset:3072
	ds_read_b128 v[182:185], v237 offset:4096
	ds_read_b128 v[186:189], v237 offset:5120
	ds_read_b128 v[190:193], v237 offset:6144
	ds_read_b128 v[214:217], v237 offset:7168
	global_load_lds_dwordx4 v210, s[76:77]
	s_add_i32 m0, s29, 0xe000
	s_nop 0
	global_load_lds_dwordx4 v212, s[76:77]
	s_waitcnt lgkmcnt(0)
	s_barrier
	s_waitcnt lgkmcnt(0)
	v_mfma_f32_16x16x32_bf16 v[174:177], v[78:81], v[158:161], v[174:177]
	v_mfma_f32_16x16x32_bf16 v[174:177], v[90:93], v[162:165], v[174:177]
	v_mfma_f32_16x16x32_bf16 v[170:173], v[114:117], v[162:165], v[170:173]
	v_mfma_f32_16x16x32_bf16 v[170:173], v[102:105], v[158:161], v[170:173]
	v_mfma_f32_16x16x32_bf16 v[150:153], v[126:129], v[158:161], v[150:153]
	v_mfma_f32_16x16x32_bf16 v[150:153], v[134:137], v[162:165], v[150:153]
	v_mfma_f32_16x16x32_bf16 v[146:149], v[154:157], v[162:165], v[146:149]
	v_mfma_f32_16x16x32_bf16 v[146:149], v[142:145], v[158:161], v[146:149]
	v_mfma_f32_16x16x32_bf16 v[118:121], v[142:145], v[166:169], v[118:121]
	v_mfma_f32_16x16x32_bf16 v[118:121], v[154:157], v[178:181], v[118:121]
	v_mfma_f32_16x16x32_bf16 v[122:125], v[134:137], v[178:181], v[122:125]
	v_mfma_f32_16x16x32_bf16 v[122:125], v[126:129], v[166:169], v[122:125]
	v_mfma_f32_16x16x32_bf16 v[130:133], v[102:105], v[166:169], v[130:133]
	v_mfma_f32_16x16x32_bf16 v[130:133], v[114:117], v[178:181], v[130:133]
	v_mfma_f32_16x16x32_bf16 v[138:141], v[90:93], v[178:181], v[138:141]
	v_mfma_f32_16x16x32_bf16 v[138:141], v[78:81], v[166:169], v[138:141]
	v_mfma_f32_16x16x32_bf16 v[110:113], v[78:81], v[182:185], v[110:113]
	v_mfma_f32_16x16x32_bf16 v[110:113], v[90:93], v[186:189], v[110:113]
	v_mfma_f32_16x16x32_bf16 v[106:109], v[114:117], v[186:189], v[106:109]
	v_mfma_f32_16x16x32_bf16 v[106:109], v[102:105], v[182:185], v[106:109]
	v_mfma_f32_16x16x32_bf16 v[98:101], v[126:129], v[182:185], v[98:101]
	v_mfma_f32_16x16x32_bf16 v[98:101], v[134:137], v[186:189], v[98:101]
	v_mfma_f32_16x16x32_bf16 v[94:97], v[154:157], v[186:189], v[94:97]
	v_mfma_f32_16x16x32_bf16 v[94:97], v[142:145], v[182:185], v[94:97]
	v_mfma_f32_16x16x32_bf16 v[66:69], v[142:145], v[190:193], v[66:69]
	v_mfma_f32_16x16x32_bf16 v[66:69], v[154:157], v[214:217], v[66:69]
	v_mfma_f32_16x16x32_bf16 v[74:77], v[134:137], v[214:217], v[74:77]
	v_mfma_f32_16x16x32_bf16 v[74:77], v[126:129], v[190:193], v[74:77]
	v_mfma_f32_16x16x32_bf16 v[82:85], v[102:105], v[190:193], v[82:85]
	v_mfma_f32_16x16x32_bf16 v[82:85], v[114:117], v[214:217], v[82:85]
	v_mfma_f32_16x16x32_bf16 v[86:89], v[90:93], v[214:217], v[86:89]
	v_mfma_f32_16x16x32_bf16 v[86:89], v[78:81], v[190:193], v[86:89]
	s_waitcnt vmcnt(8)
	s_barrier
	s_add_i32 s0, s0, s28
	s_mov_b32 m0, s0
	ds_read_b128 v[158:161], v237 offset:16384
	ds_read_b128 v[162:165], v237 offset:17408
	ds_read_b128 v[166:169], v237 offset:18432
	ds_read_b128 v[178:181], v237 offset:19456
	ds_read_b128 v[182:185], v237 offset:20480
	ds_read_b128 v[186:189], v237 offset:21504
	ds_read_b128 v[190:193], v237 offset:22528
	ds_read_b128 v[214:217], v237 offset:23552
	global_load_lds_dwordx4 v194, s[70:71]
	s_add_i32 m0, s0, 0x2000
	s_add_u32 s0, s70, 0x80000
	s_addc_u32 s1, s71, 0
	s_add_i32 s18, s18, s28
	global_load_lds_dwordx4 v204, s[70:71]
	s_mov_b32 m0, s18
	s_nop 0
	global_load_lds_dwordx4 v194, s[0:1]
	s_add_i32 m0, s18, 0x2000
	s_nop 0
	global_load_lds_dwordx4 v204, s[0:1]
	s_mov_b32 m0, s29
	s_nop 0
	global_load_lds_dwordx4 v194, vcc
	s_mov_b32 m0, s31
	s_nop 0
	global_load_lds_dwordx4 v204, vcc
	s_waitcnt lgkmcnt(0)
	s_barrier
	s_waitcnt lgkmcnt(0)
	v_mfma_f32_16x16x32_bf16 v[62:65], v[78:81], v[158:161], v[62:65]
	v_mfma_f32_16x16x32_bf16 v[62:65], v[90:93], v[162:165], v[62:65]
	v_mfma_f32_16x16x32_bf16 v[58:61], v[114:117], v[162:165], v[58:61]
	v_mfma_f32_16x16x32_bf16 v[58:61], v[102:105], v[158:161], v[58:61]
	v_mfma_f32_16x16x32_bf16 v[54:57], v[126:129], v[158:161], v[54:57]
	v_mfma_f32_16x16x32_bf16 v[54:57], v[134:137], v[162:165], v[54:57]
	v_mfma_f32_16x16x32_bf16 v[50:53], v[154:157], v[162:165], v[50:53]
	v_mfma_f32_16x16x32_bf16 v[50:53], v[142:145], v[158:161], v[50:53]
	v_mfma_f32_16x16x32_bf16 v[34:37], v[142:145], v[166:169], v[34:37]
	v_mfma_f32_16x16x32_bf16 v[34:37], v[154:157], v[178:181], v[34:37]
	v_mfma_f32_16x16x32_bf16 v[38:41], v[134:137], v[178:181], v[38:41]
	v_mfma_f32_16x16x32_bf16 v[38:41], v[126:129], v[166:169], v[38:41]
	v_mfma_f32_16x16x32_bf16 v[42:45], v[102:105], v[166:169], v[42:45]
	v_mfma_f32_16x16x32_bf16 v[42:45], v[114:117], v[178:181], v[42:45]
	v_mfma_f32_16x16x32_bf16 v[46:49], v[90:93], v[178:181], v[46:49]
	v_mfma_f32_16x16x32_bf16 v[46:49], v[78:81], v[166:169], v[46:49]
	v_mfma_f32_16x16x32_bf16 v[30:33], v[78:81], v[182:185], v[30:33]
	v_mfma_f32_16x16x32_bf16 v[30:33], v[90:93], v[186:189], v[30:33]
	v_mfma_f32_16x16x32_bf16 v[26:29], v[114:117], v[186:189], v[26:29]
	v_mfma_f32_16x16x32_bf16 v[26:29], v[102:105], v[182:185], v[26:29]
	v_mfma_f32_16x16x32_bf16 v[22:25], v[126:129], v[182:185], v[22:25]
	v_mfma_f32_16x16x32_bf16 v[22:25], v[134:137], v[186:189], v[22:25]
	v_mfma_f32_16x16x32_bf16 v[18:21], v[154:157], v[186:189], v[18:21]
	v_mfma_f32_16x16x32_bf16 v[18:21], v[142:145], v[182:185], v[18:21]
	v_mfma_f32_16x16x32_bf16 v[2:5], v[142:145], v[190:193], v[2:5]
	v_mfma_f32_16x16x32_bf16 v[2:5], v[154:157], v[214:217], v[2:5]
	v_mfma_f32_16x16x32_bf16 v[6:9], v[134:137], v[214:217], v[6:9]
	v_mfma_f32_16x16x32_bf16 v[6:9], v[126:129], v[190:193], v[6:9]
	v_mfma_f32_16x16x32_bf16 v[10:13], v[102:105], v[190:193], v[10:13]
	v_mfma_f32_16x16x32_bf16 v[10:13], v[114:117], v[214:217], v[10:13]
	v_mfma_f32_16x16x32_bf16 v[14:17], v[90:93], v[214:217], v[14:17]
	v_mfma_f32_16x16x32_bf16 v[14:17], v[78:81], v[190:193], v[14:17]
	s_waitcnt vmcnt(8)
	s_barrier
	s_add_i32 s18, 0, 0x18000
	s_add_i32 s19, 0, 0x1c000
	v_add_u32_e32 v114, s18, v1
	v_add_u32_e32 v154, s19, v1
	ds_read_b128 v[78:81], v114
	ds_read_b128 v[90:93], v114 offset:1024
	ds_read_b128 v[102:105], v114 offset:2048
	ds_read_b128 v[114:117], v114 offset:3072
	ds_read_b128 v[126:129], v154
	ds_read_b128 v[134:137], v154 offset:1024
	ds_read_b128 v[142:145], v154 offset:2048
	ds_read_b128 v[154:157], v154 offset:3072
	s_add_u32 s0, vcc_lo, 0x80000
	s_addc_u32 s1, vcc_hi, 0
	s_mov_b32 m0, s33
	ds_read_b128 v[158:161], v237 offset:32768
	ds_read_b128 v[162:165], v237 offset:33792
	ds_read_b128 v[166:169], v237 offset:34816
	ds_read_b128 v[178:181], v237 offset:35840
	ds_read_b128 v[182:185], v237 offset:36864
	ds_read_b128 v[186:189], v237 offset:37888
	ds_read_b128 v[190:193], v237 offset:38912
	ds_read_b128 v[214:217], v237 offset:39936
	global_load_lds_dwordx4 v194, s[0:1]
	s_mov_b32 m0, s43
	s_nop 0
	global_load_lds_dwordx4 v204, s[0:1]
	s_waitcnt lgkmcnt(0)
	s_barrier
	s_waitcnt lgkmcnt(0)
	v_mfma_f32_16x16x32_bf16 v[174:177], v[78:81], v[158:161], v[174:177]
	v_mfma_f32_16x16x32_bf16 v[174:177], v[90:93], v[162:165], v[174:177]
	v_mfma_f32_16x16x32_bf16 v[170:173], v[114:117], v[162:165], v[170:173]
	v_mfma_f32_16x16x32_bf16 v[170:173], v[102:105], v[158:161], v[170:173]
	v_mfma_f32_16x16x32_bf16 v[150:153], v[126:129], v[158:161], v[150:153]
	v_mfma_f32_16x16x32_bf16 v[150:153], v[134:137], v[162:165], v[150:153]
	v_mfma_f32_16x16x32_bf16 v[146:149], v[154:157], v[162:165], v[146:149]
	v_mfma_f32_16x16x32_bf16 v[146:149], v[142:145], v[158:161], v[146:149]
	v_mfma_f32_16x16x32_bf16 v[118:121], v[142:145], v[166:169], v[118:121]
	v_mfma_f32_16x16x32_bf16 v[118:121], v[154:157], v[178:181], v[118:121]
	v_mfma_f32_16x16x32_bf16 v[122:125], v[134:137], v[178:181], v[122:125]
	v_mfma_f32_16x16x32_bf16 v[122:125], v[126:129], v[166:169], v[122:125]
	v_mfma_f32_16x16x32_bf16 v[130:133], v[102:105], v[166:169], v[130:133]
	v_mfma_f32_16x16x32_bf16 v[130:133], v[114:117], v[178:181], v[130:133]
	v_mfma_f32_16x16x32_bf16 v[138:141], v[90:93], v[178:181], v[138:141]
	v_mfma_f32_16x16x32_bf16 v[138:141], v[78:81], v[166:169], v[138:141]
	v_mfma_f32_16x16x32_bf16 v[110:113], v[78:81], v[182:185], v[110:113]
	v_mfma_f32_16x16x32_bf16 v[110:113], v[90:93], v[186:189], v[110:113]
	v_mfma_f32_16x16x32_bf16 v[106:109], v[114:117], v[186:189], v[106:109]
	v_mfma_f32_16x16x32_bf16 v[106:109], v[102:105], v[182:185], v[106:109]
	v_mfma_f32_16x16x32_bf16 v[98:101], v[126:129], v[182:185], v[98:101]
	v_mfma_f32_16x16x32_bf16 v[98:101], v[134:137], v[186:189], v[98:101]
	v_mfma_f32_16x16x32_bf16 v[94:97], v[154:157], v[186:189], v[94:97]
	v_mfma_f32_16x16x32_bf16 v[94:97], v[142:145], v[182:185], v[94:97]
	v_mfma_f32_16x16x32_bf16 v[66:69], v[142:145], v[190:193], v[66:69]
	v_mfma_f32_16x16x32_bf16 v[66:69], v[154:157], v[214:217], v[66:69]
	v_mfma_f32_16x16x32_bf16 v[74:77], v[134:137], v[214:217], v[74:77]
	v_mfma_f32_16x16x32_bf16 v[74:77], v[126:129], v[190:193], v[74:77]
	v_mfma_f32_16x16x32_bf16 v[82:85], v[102:105], v[190:193], v[82:85]
	v_mfma_f32_16x16x32_bf16 v[82:85], v[114:117], v[214:217], v[82:85]
	v_mfma_f32_16x16x32_bf16 v[86:89], v[90:93], v[214:217], v[86:89]
	v_mfma_f32_16x16x32_bf16 v[86:89], v[78:81], v[190:193], v[86:89]
	s_waitcnt vmcnt(8)
	s_barrier
	s_add_u32 s98, s70, 0x80
	s_addc_u32 s99, s71, 0
	s_add_u32 s100, vcc_lo, 0x80
	s_addc_u32 s101, vcc_hi, 0
	s_add_i32 s0, s18, s28
	s_mov_b32 m0, s0
	ds_read_b128 v[158:161], v237 offset:49152
	ds_read_b128 v[162:165], v237 offset:50176
	ds_read_b128 v[166:169], v237 offset:51200
	ds_read_b128 v[178:181], v237 offset:52224
	ds_read_b128 v[182:185], v237 offset:53248
	ds_read_b128 v[186:189], v237 offset:54272
	ds_read_b128 v[190:193], v237 offset:55296
	ds_read_b128 v[214:217], v237 offset:56320
	global_load_lds_dwordx4 v194, s[98:99]
	s_add_i32 m0, s0, 0x2000
	s_add_u32 s0, s70, 0x80080
	s_addc_u32 s1, s71, 0
	s_add_i32 s18, s19, s28
	global_load_lds_dwordx4 v204, s[98:99]
	s_mov_b32 m0, s18
	s_nop 0
	global_load_lds_dwordx4 v194, s[0:1]
	s_add_i32 m0, s18, 0x2000
	s_nop 0
	global_load_lds_dwordx4 v204, s[0:1]
	s_mov_b32 m0, s68
	s_nop 0
	global_load_lds_dwordx4 v194, s[100:101]
	s_mov_b32 m0, s79
	s_nop 0
	global_load_lds_dwordx4 v204, s[100:101]
	s_waitcnt lgkmcnt(0)
	s_barrier
	s_waitcnt lgkmcnt(0)
	v_mfma_f32_16x16x32_bf16 v[62:65], v[78:81], v[158:161], v[62:65]
	v_mfma_f32_16x16x32_bf16 v[62:65], v[90:93], v[162:165], v[62:65]
	v_mfma_f32_16x16x32_bf16 v[58:61], v[114:117], v[162:165], v[58:61]
	v_mfma_f32_16x16x32_bf16 v[58:61], v[102:105], v[158:161], v[58:61]
	v_mfma_f32_16x16x32_bf16 v[54:57], v[126:129], v[158:161], v[54:57]
	v_mfma_f32_16x16x32_bf16 v[54:57], v[134:137], v[162:165], v[54:57]
	v_mfma_f32_16x16x32_bf16 v[50:53], v[154:157], v[162:165], v[50:53]
	v_mfma_f32_16x16x32_bf16 v[50:53], v[142:145], v[158:161], v[50:53]
	v_mfma_f32_16x16x32_bf16 v[34:37], v[142:145], v[166:169], v[34:37]
	v_mfma_f32_16x16x32_bf16 v[34:37], v[154:157], v[178:181], v[34:37]
	v_mfma_f32_16x16x32_bf16 v[38:41], v[134:137], v[178:181], v[38:41]
	v_mfma_f32_16x16x32_bf16 v[38:41], v[126:129], v[166:169], v[38:41]
	v_mfma_f32_16x16x32_bf16 v[42:45], v[102:105], v[166:169], v[42:45]
	v_mfma_f32_16x16x32_bf16 v[42:45], v[114:117], v[178:181], v[42:45]
	v_mfma_f32_16x16x32_bf16 v[46:49], v[90:93], v[178:181], v[46:49]
	v_mfma_f32_16x16x32_bf16 v[46:49], v[78:81], v[166:169], v[46:49]
	v_mfma_f32_16x16x32_bf16 v[30:33], v[78:81], v[182:185], v[30:33]
	v_mfma_f32_16x16x32_bf16 v[30:33], v[90:93], v[186:189], v[30:33]
	v_mfma_f32_16x16x32_bf16 v[26:29], v[114:117], v[186:189], v[26:29]
	v_mfma_f32_16x16x32_bf16 v[26:29], v[102:105], v[182:185], v[26:29]
	v_mfma_f32_16x16x32_bf16 v[22:25], v[126:129], v[182:185], v[22:25]
	v_mfma_f32_16x16x32_bf16 v[22:25], v[134:137], v[186:189], v[22:25]
	v_mfma_f32_16x16x32_bf16 v[18:21], v[154:157], v[186:189], v[18:21]
	v_mfma_f32_16x16x32_bf16 v[18:21], v[142:145], v[182:185], v[18:21]
	v_mfma_f32_16x16x32_bf16 v[2:5], v[142:145], v[190:193], v[2:5]
	v_mfma_f32_16x16x32_bf16 v[2:5], v[154:157], v[214:217], v[2:5]
	v_mfma_f32_16x16x32_bf16 v[6:9], v[134:137], v[214:217], v[6:9]
	v_mfma_f32_16x16x32_bf16 v[6:9], v[126:129], v[190:193], v[6:9]
	v_mfma_f32_16x16x32_bf16 v[10:13], v[102:105], v[190:193], v[10:13]
	v_mfma_f32_16x16x32_bf16 v[10:13], v[114:117], v[214:217], v[10:13]
	v_mfma_f32_16x16x32_bf16 v[14:17], v[90:93], v[214:217], v[14:17]
	v_mfma_f32_16x16x32_bf16 v[14:17], v[78:81], v[190:193], v[14:17]
	s_waitcnt vmcnt(8)
	s_barrier
	s_add_i32 s57, s57, 2
	s_add_u32 s51, s51, 0x100
	s_addc_u32 s53, s53, 0
	s_cmp_gt_u32 s57, 29
	s_mov_b64 s[76:77], s[90:91]
	s_cbranch_scc1 .LBB0_512
	s_branch .LBB0_510

.LBB0_571:
	s_add_i32 s6, s42, 9
	v_readlane_b32 s8, v254, 1
	v_readlane_b32 s9, v254, 2
	s_cmp_le_i32 s8, s6
	s_cselect_b64 s[0:1], -1, 0
	s_cmp_lt_i32 s6, s9
	s_cselect_b64 s[6:7], -1, 0
	s_and_b64 s[0:1], s[0:1], s[6:7]
	s_andn2_b64 vcc, exec, s[0:1]
	v_readlane_b32 s10, v254, 3
	v_readlane_b32 s11, v254, 4
	s_cbranch_vccnz .LBB0_590
	v_readlane_b32 s0, v254, 49
	v_mov_b32_e32 v1, v0
	v_readlane_b32 s1, v254, 50
	s_mov_b32 s6, 19
	s_andn2_b64 vcc, exec, s[0:1]
	v_readfirstlane_b32 s22, v1
	s_cbranch_vccnz .LBB0_590
	v_lshlrev_b32_e32 v13, 4, v1
	v_add_u32_e32 v2, 0x2000, v13
	v_ashrrev_i32_e32 v3, 31, v2
	v_lshrrev_b32_e32 v3, 22, v3
	v_add_u32_e32 v3, v2, v3
	v_ashrrev_i32_e32 v10, 10, v3
	v_mul_i32_i24_e32 v4, 0x400, v10
	v_sub_u32_e32 v2, v2, v4
	v_lshrrev_b32_e32 v4, 4, v2
	v_bitop3_b32 v2, v4, v2, 32 bitop3:0x6c
	v_ashrrev_i32_e32 v4, 31, v2
	v_lshrrev_b32_e32 v4, 26, v4
	v_add_u32_e32 v4, v2, v4
	v_ashrrev_i32_e32 v11, 6, v4
	v_and_b32_e32 v4, 0xc0, v4
	v_sub_u32_e32 v2, v2, v4
	v_lshlrev_b32_e32 v3, 5, v10
	v_ashrrev_i16_sdwa v2, v233, sext(v2) dst_sel:DWORD dst_unused:UNUSED_PAD src0_sel:DWORD src1_sel:BYTE_0
	v_and_b32_e32 v3, 32, v3
	v_bfe_i32 v12, v2, 0, 16
	v_add_u32_e32 v2, v3, v12
	v_lshlrev_b32_e32 v3, 3, v10
	s_ashr_i32 s7, s6, 31
	v_and_b32_e32 v3, 0xffff0, v3
	s_lshl_b64 s[0:1], s[6:7], 3
	v_readlane_b32 s6, v254, 7
	v_add_lshl_u32 v3, v11, v3, 12
	v_readlane_b32 s7, v254, 8
	s_add_u32 s0, s6, s0
	v_lshl_add_u32 v130, v2, 1, v3
	v_bfe_i32 v3, v1, 27, 1
	s_addc_u32 s1, s7, s1
	v_lshrrev_b32_e32 v3, 22, v3
	s_load_dwordx2 s[6:7], s[0:1], 0x0
	v_add_u32_e32 v3, v13, v3
	v_and_b32_e32 v3, 0xfffffc00, v3
	v_sub_u32_e32 v3, v13, v3
	v_lshrrev_b32_e32 v4, 4, v3
	v_bitop3_b32 v3, v4, v3, 32 bitop3:0x6c
	s_waitcnt lgkmcnt(0)
	s_add_u32 s20, s6, 0x1b000000
	v_ashrrev_i32_e32 v4, 31, v3
	s_mul_i32 s1, s75, 0x2c00000
	s_addc_u32 s21, s7, 0
	v_lshrrev_b32_e32 v4, 26, v4
	s_mul_hi_u32 s0, s75, 0x2c00000
	s_add_u32 s1, s6, s1
	v_ashrrev_i32_e32 v2, 31, v1
	v_add_u32_e32 v4, v3, v4
	s_addc_u32 s0, s7, s0
	v_lshrrev_b32_e32 v2, 26, v2
	v_ashrrev_i32_e32 v15, 6, v4
	v_and_b32_e32 v4, 0xc0, v4
	s_add_u32 s26, s1, 0xa800000
	v_add_u32_e32 v2, v1, v2
	v_sub_u32_e32 v3, v3, v4
	s_addc_u32 s27, s0, 0
	s_ashr_i32 s12, s22, 6
	v_ashrrev_i32_e32 v14, 6, v2
	v_ashrrev_i16_sdwa v3, v233, sext(v3) dst_sel:DWORD dst_unused:UNUSED_PAD src0_sel:DWORD src1_sel:BYTE_0
	s_ashr_i32 s13, s22, 8
	s_ashr_i32 s98, s22, 8
	s_lshl_b32 s28, s12, 10
	v_lshlrev_b32_e32 v2, 5, v14
	v_bfe_i32 v16, v3, 0, 16
	v_lshlrev_b32_e32 v3, 3, v14
	v_readlane_b32 s0, v255, 0
	v_and_b32_e32 v2, 32, v2
	v_and_b32_e32 v3, 0xffff0, v3
	v_readlane_b32 s1, v255, 1
	s_add_u32 s64, s26, s0
	v_add_u32_e32 v2, v2, v16
	v_add_lshl_u32 v3, v15, v3, 12
	s_addc_u32 s65, s27, s1
	s_add_i32 s29, s28, 0
	v_lshl_add_u32 v194, v2, 1, v3
	s_add_i32 m0, s29, 0x10000
	v_mov_b32_e32 v131, v195
	global_load_lds_dwordx4 v194, s[64:65]
	s_add_i32 m0, s29, 0x12000
	s_add_u32 s0, s64, 0x80000
	global_load_lds_dwordx4 v130, s[64:65]
	s_addc_u32 s1, s65, 0
	s_add_i32 m0, s29, 0x14000
	v_lshl_add_u64 v[8:9], s[64:65], 0, v[194:195]
	global_load_lds_dwordx4 v194, s[0:1]
	s_add_i32 m0, s29, 0x16000
	v_lshl_add_u64 v[6:7], s[64:65], 0, v[130:131]
	global_load_lds_dwordx4 v130, s[0:1]
	v_readlane_b32 s0, v254, 62
	v_readlane_b32 s1, v254, 63
	s_add_u32 s62, s20, s0
	s_addc_u32 s63, s21, s1
	s_add_i32 s31, s29, 0x2000
	s_mov_b32 m0, s29
	s_add_u32 s0, s62, 0x80000
	global_load_lds_dwordx4 v194, s[62:63]
	s_mov_b32 m0, s31
	s_addc_u32 s1, s63, 0
	s_add_i32 s33, s29, 0x4000
	global_load_lds_dwordx4 v130, s[62:63]
	s_mov_b32 m0, s33
	s_add_i32 s40, s29, 0x6000
	global_load_lds_dwordx4 v194, s[0:1]
	s_mov_b32 m0, s40
	s_cmp_eq_u32 s13, 1
	global_load_lds_dwordx4 v130, s[0:1]
	v_lshl_add_u64 v[2:3], s[62:63], 0, v[194:195]
	s_cselect_b64 s[8:9], -1, 0
	s_cmp_lg_u32 s13, 1
	v_lshl_add_u64 v[4:5], s[62:63], 0, v[130:131]
	s_cbranch_scc1 .LBB0_575
	s_barrier

.Lpeel_disp_gu:
	s_cmp_lg_u32 s76, -2
	s_cbranch_scc1 .Llw_main_gu
	s_cmp_eq_u32 s98, 0
	s_cbranch_scc1 .Llw_p0_gu
	s_add_u32 s18, s62, 0xfff80080
	s_addc_u32 s19, s63, -1
	s_and_b64 s[0:1], s[64:65], exec
	s_cselect_b32 s71, s22, s19
	s_cselect_b32 s70, s23, s18
	s_cselect_b32 s65, s39, s58
	s_cselect_b32 s64, s47, s53
	s_add_i32 s0, 0, 0x10000
	v_add_u32_e32 v153, s0, v1
	s_add_i32 s18, 0, 0x14000
	ds_read_b128 v[144:147], v153
	ds_read_b128 v[148:151], v153 offset:1024
	ds_read_b128 v[154:157], v153 offset:2048
	ds_read_b128 v[158:161], v153 offset:3072
	v_add_u32_e32 v153, s18, v1
	ds_read_b128 v[162:165], v153
	ds_read_b128 v[166:169], v153 offset:1024
	ds_read_b128 v[170:173], v153 offset:2048
	ds_read_b128 v[174:177], v153 offset:3072
	s_add_i32 m0, s29, 0xc000
	ds_read_b128 v[178:181], v152
	ds_read_b128 v[182:185], v152 offset:1024
	ds_read_b128 v[186:189], v152 offset:2048
	ds_read_b128 v[190:193], v152 offset:3072
	ds_read_b128 v[204:207], v152 offset:4096
	ds_read_b128 v[208:211], v152 offset:5120
	ds_read_b128 v[212:215], v152 offset:6144
	ds_read_b128 v[216:219], v152 offset:7168
	global_load_lds_dwordx4 v136, s[62:63]
	s_add_i32 m0, s29, 0xe000
	s_nop 0
	global_load_lds_dwordx4 v138, s[62:63]
	s_waitcnt vmcnt(8)
	s_waitcnt lgkmcnt(0)
	s_barrier
	s_waitcnt lgkmcnt(0)
	v_mfma_f32_16x16x32_bf16 v[126:129], v[144:147], v[178:181], 0
	v_mfma_f32_16x16x32_bf16 v[126:129], v[148:151], v[182:185], v[126:129]
	v_mfma_f32_16x16x32_bf16 v[122:125], v[158:161], v[182:185], 0
	v_mfma_f32_16x16x32_bf16 v[122:125], v[154:157], v[178:181], v[122:125]
	v_mfma_f32_16x16x32_bf16 v[118:121], v[162:165], v[178:181], 0
	v_mfma_f32_16x16x32_bf16 v[118:121], v[166:169], v[182:185], v[118:121]
	v_mfma_f32_16x16x32_bf16 v[114:117], v[174:177], v[182:185], 0
	v_mfma_f32_16x16x32_bf16 v[114:117], v[170:173], v[178:181], v[114:117]
	v_mfma_f32_16x16x32_bf16 v[98:101], v[170:173], v[186:189], 0
	v_mfma_f32_16x16x32_bf16 v[98:101], v[174:177], v[190:193], v[98:101]
	v_mfma_f32_16x16x32_bf16 v[102:105], v[166:169], v[190:193], 0
	v_mfma_f32_16x16x32_bf16 v[102:105], v[162:165], v[186:189], v[102:105]
	v_mfma_f32_16x16x32_bf16 v[106:109], v[154:157], v[186:189], 0
	v_mfma_f32_16x16x32_bf16 v[106:109], v[158:161], v[190:193], v[106:109]
	v_mfma_f32_16x16x32_bf16 v[110:113], v[148:151], v[190:193], 0
	v_mfma_f32_16x16x32_bf16 v[110:113], v[144:147], v[186:189], v[110:113]
	v_mfma_f32_16x16x32_bf16 v[94:97], v[144:147], v[204:207], 0
	v_mfma_f32_16x16x32_bf16 v[94:97], v[148:151], v[208:211], v[94:97]
	v_mfma_f32_16x16x32_bf16 v[90:93], v[158:161], v[208:211], 0
	v_mfma_f32_16x16x32_bf16 v[90:93], v[154:157], v[204:207], v[90:93]
	v_mfma_f32_16x16x32_bf16 v[86:89], v[162:165], v[204:207], 0
	v_mfma_f32_16x16x32_bf16 v[86:89], v[166:169], v[208:211], v[86:89]
	v_mfma_f32_16x16x32_bf16 v[82:85], v[174:177], v[208:211], 0
	v_mfma_f32_16x16x32_bf16 v[82:85], v[170:173], v[204:207], v[82:85]
	v_mfma_f32_16x16x32_bf16 v[66:69], v[170:173], v[212:215], 0
	v_mfma_f32_16x16x32_bf16 v[66:69], v[174:177], v[216:219], v[66:69]
	v_mfma_f32_16x16x32_bf16 v[70:73], v[166:169], v[216:219], 0
	v_mfma_f32_16x16x32_bf16 v[70:73], v[162:165], v[212:215], v[70:73]
	v_mfma_f32_16x16x32_bf16 v[74:77], v[154:157], v[212:215], 0
	v_mfma_f32_16x16x32_bf16 v[74:77], v[158:161], v[216:219], v[74:77]
	v_mfma_f32_16x16x32_bf16 v[78:81], v[148:151], v[216:219], 0
	v_mfma_f32_16x16x32_bf16 v[78:81], v[144:147], v[212:215], v[78:81]
	s_barrier
	s_add_i32 s0, s0, s28
	s_mov_b32 m0, s0
	ds_read_b128 v[178:181], v152 offset:16384
	ds_read_b128 v[182:185], v152 offset:17408
	ds_read_b128 v[186:189], v152 offset:18432
	ds_read_b128 v[190:193], v152 offset:19456
	ds_read_b128 v[204:207], v152 offset:20480
	ds_read_b128 v[208:211], v152 offset:21504
	ds_read_b128 v[212:215], v152 offset:22528
	ds_read_b128 v[216:219], v152 offset:23552
	global_load_lds_dwordx4 v194, s[64:65]
	s_add_i32 m0, s0, 0x2000
	s_add_u32 s0, s64, 0x80000
	s_addc_u32 s1, s65, 0
	s_add_i32 s18, s18, s28
	global_load_lds_dwordx4 v130, s[64:65]
	s_mov_b32 m0, s18
	s_nop 0
	global_load_lds_dwordx4 v194, s[0:1]
	s_add_i32 m0, s18, 0x2000
	s_nop 0
	global_load_lds_dwordx4 v130, s[0:1]
	s_mov_b32 m0, s29
	s_nop 0
	global_load_lds_dwordx4 v194, s[70:71]
	s_mov_b32 m0, s31
	s_nop 0
	global_load_lds_dwordx4 v130, s[70:71]
	s_waitcnt vmcnt(8)
	s_waitcnt lgkmcnt(0)
	s_barrier
	s_waitcnt lgkmcnt(0)
	v_mfma_f32_16x16x32_bf16 v[62:65], v[144:147], v[178:181], 0
	v_mfma_f32_16x16x32_bf16 v[62:65], v[148:151], v[182:185], v[62:65]
	v_mfma_f32_16x16x32_bf16 v[58:61], v[158:161], v[182:185], 0
	v_mfma_f32_16x16x32_bf16 v[58:61], v[154:157], v[178:181], v[58:61]
	v_mfma_f32_16x16x32_bf16 v[54:57], v[162:165], v[178:181], 0
	v_mfma_f32_16x16x32_bf16 v[54:57], v[166:169], v[182:185], v[54:57]
	v_mfma_f32_16x16x32_bf16 v[50:53], v[174:177], v[182:185], 0
	v_mfma_f32_16x16x32_bf16 v[50:53], v[170:173], v[178:181], v[50:53]
	v_mfma_f32_16x16x32_bf16 v[34:37], v[170:173], v[186:189], 0
	v_mfma_f32_16x16x32_bf16 v[34:37], v[174:177], v[190:193], v[34:37]
	v_mfma_f32_16x16x32_bf16 v[38:41], v[166:169], v[190:193], 0
	v_mfma_f32_16x16x32_bf16 v[38:41], v[162:165], v[186:189], v[38:41]
	v_mfma_f32_16x16x32_bf16 v[42:45], v[154:157], v[186:189], 0
	v_mfma_f32_16x16x32_bf16 v[42:45], v[158:161], v[190:193], v[42:45]
	v_mfma_f32_16x16x32_bf16 v[46:49], v[148:151], v[190:193], 0
	v_mfma_f32_16x16x32_bf16 v[46:49], v[144:147], v[186:189], v[46:49]
	v_mfma_f32_16x16x32_bf16 v[30:33], v[144:147], v[204:207], 0
	v_mfma_f32_16x16x32_bf16 v[30:33], v[148:151], v[208:211], v[30:33]
	v_mfma_f32_16x16x32_bf16 v[26:29], v[158:161], v[208:211], 0
	v_mfma_f32_16x16x32_bf16 v[26:29], v[154:157], v[204:207], v[26:29]
	v_mfma_f32_16x16x32_bf16 v[22:25], v[162:165], v[204:207], 0
	v_mfma_f32_16x16x32_bf16 v[22:25], v[166:169], v[208:211], v[22:25]
	v_mfma_f32_16x16x32_bf16 v[18:21], v[174:177], v[208:211], 0
	v_mfma_f32_16x16x32_bf16 v[18:21], v[170:173], v[204:207], v[18:21]
	v_mfma_f32_16x16x32_bf16 v[2:5], v[170:173], v[212:215], 0
	v_mfma_f32_16x16x32_bf16 v[2:5], v[174:177], v[216:219], v[2:5]
	v_mfma_f32_16x16x32_bf16 v[6:9], v[166:169], v[216:219], 0
	v_mfma_f32_16x16x32_bf16 v[6:9], v[162:165], v[212:215], v[6:9]
	v_mfma_f32_16x16x32_bf16 v[10:13], v[154:157], v[212:215], 0
	v_mfma_f32_16x16x32_bf16 v[10:13], v[158:161], v[216:219], v[10:13]
	v_mfma_f32_16x16x32_bf16 v[14:17], v[148:151], v[216:219], 0
	v_mfma_f32_16x16x32_bf16 v[14:17], v[144:147], v[212:215], v[14:17]
	s_barrier
	s_add_i32 s18, 0, 0x18000
	v_add_u32_e32 v153, s18, v1
	s_add_i32 s19, 0, 0x1c000
	ds_read_b128 v[144:147], v153
	ds_read_b128 v[148:151], v153 offset:1024
	ds_read_b128 v[154:157], v153 offset:2048
	ds_read_b128 v[158:161], v153 offset:3072
	v_add_u32_e32 v153, s19, v1
	ds_read_b128 v[162:165], v153
	ds_read_b128 v[166:169], v153 offset:1024
	ds_read_b128 v[170:173], v153 offset:2048
	ds_read_b128 v[174:177], v153 offset:3072
	s_add_u32 s0, s70, 0x80000
	s_addc_u32 s1, s71, 0
	s_mov_b32 m0, s33
	ds_read_b128 v[178:181], v152 offset:32768
	ds_read_b128 v[182:185], v152 offset:33792
	ds_read_b128 v[186:189], v152 offset:34816
	ds_read_b128 v[190:193], v152 offset:35840
	ds_read_b128 v[204:207], v152 offset:36864
	ds_read_b128 v[208:211], v152 offset:37888
	ds_read_b128 v[212:215], v152 offset:38912
	ds_read_b128 v[216:219], v152 offset:39936
	global_load_lds_dwordx4 v194, s[0:1]
	s_mov_b32 m0, s40
	s_nop 0
	global_load_lds_dwordx4 v130, s[0:1]
	s_waitcnt vmcnt(8)
	s_waitcnt lgkmcnt(0)
	s_barrier
	s_waitcnt lgkmcnt(0)
	v_mfma_f32_16x16x32_bf16 v[126:129], v[144:147], v[178:181], v[126:129]
	v_mfma_f32_16x16x32_bf16 v[126:129], v[148:151], v[182:185], v[126:129]
	v_mfma_f32_16x16x32_bf16 v[122:125], v[158:161], v[182:185], v[122:125]
	v_mfma_f32_16x16x32_bf16 v[122:125], v[154:157], v[178:181], v[122:125]
	v_mfma_f32_16x16x32_bf16 v[118:121], v[162:165], v[178:181], v[118:121]
	v_mfma_f32_16x16x32_bf16 v[118:121], v[166:169], v[182:185], v[118:121]
	v_mfma_f32_16x16x32_bf16 v[114:117], v[174:177], v[182:185], v[114:117]
	v_mfma_f32_16x16x32_bf16 v[114:117], v[170:173], v[178:181], v[114:117]
	v_mfma_f32_16x16x32_bf16 v[98:101], v[170:173], v[186:189], v[98:101]
	v_mfma_f32_16x16x32_bf16 v[98:101], v[174:177], v[190:193], v[98:101]
	v_mfma_f32_16x16x32_bf16 v[102:105], v[166:169], v[190:193], v[102:105]
	v_mfma_f32_16x16x32_bf16 v[102:105], v[162:165], v[186:189], v[102:105]
	v_mfma_f32_16x16x32_bf16 v[106:109], v[154:157], v[186:189], v[106:109]
	v_mfma_f32_16x16x32_bf16 v[106:109], v[158:161], v[190:193], v[106:109]
	v_mfma_f32_16x16x32_bf16 v[110:113], v[148:151], v[190:193], v[110:113]
	v_mfma_f32_16x16x32_bf16 v[110:113], v[144:147], v[186:189], v[110:113]
	v_mfma_f32_16x16x32_bf16 v[94:97], v[144:147], v[204:207], v[94:97]
	v_mfma_f32_16x16x32_bf16 v[94:97], v[148:151], v[208:211], v[94:97]
	v_mfma_f32_16x16x32_bf16 v[90:93], v[158:161], v[208:211], v[90:93]
	v_mfma_f32_16x16x32_bf16 v[90:93], v[154:157], v[204:207], v[90:93]
	v_mfma_f32_16x16x32_bf16 v[86:89], v[162:165], v[204:207], v[86:89]
	v_mfma_f32_16x16x32_bf16 v[86:89], v[166:169], v[208:211], v[86:89]
	v_mfma_f32_16x16x32_bf16 v[82:85], v[174:177], v[208:211], v[82:85]
	v_mfma_f32_16x16x32_bf16 v[82:85], v[170:173], v[204:207], v[82:85]
	v_mfma_f32_16x16x32_bf16 v[66:69], v[170:173], v[212:215], v[66:69]
	v_mfma_f32_16x16x32_bf16 v[66:69], v[174:177], v[216:219], v[66:69]
	v_mfma_f32_16x16x32_bf16 v[70:73], v[166:169], v[216:219], v[70:73]
	v_mfma_f32_16x16x32_bf16 v[70:73], v[162:165], v[212:215], v[70:73]
	v_mfma_f32_16x16x32_bf16 v[74:77], v[154:157], v[212:215], v[74:77]
	v_mfma_f32_16x16x32_bf16 v[74:77], v[158:161], v[216:219], v[74:77]
	v_mfma_f32_16x16x32_bf16 v[78:81], v[148:151], v[216:219], v[78:81]
	v_mfma_f32_16x16x32_bf16 v[78:81], v[144:147], v[212:215], v[78:81]
	s_barrier
	s_add_u32 s98, s64, 0x80
	s_addc_u32 s99, s65, 0
	s_add_u32 s100, s70, 0x80
	s_addc_u32 s101, s71, 0
	s_add_i32 s0, s18, s28
	s_mov_b32 m0, s0
	ds_read_b128 v[178:181], v152 offset:49152
	ds_read_b128 v[182:185], v152 offset:50176
	ds_read_b128 v[186:189], v152 offset:51200
	ds_read_b128 v[190:193], v152 offset:52224
	ds_read_b128 v[204:207], v152 offset:53248
	ds_read_b128 v[208:211], v152 offset:54272
	ds_read_b128 v[212:215], v152 offset:55296
	ds_read_b128 v[216:219], v152 offset:56320
	global_load_lds_dwordx4 v194, s[98:99]
	s_add_i32 m0, s0, 0x2000
	s_add_u32 s0, s64, 0x80080
	s_addc_u32 s1, s65, 0
	s_add_i32 s18, s19, s28
	global_load_lds_dwordx4 v130, s[98:99]
	s_mov_b32 m0, s18
	s_nop 0
	global_load_lds_dwordx4 v194, s[0:1]
	s_add_i32 m0, s18, 0x2000
	s_nop 0
	global_load_lds_dwordx4 v130, s[0:1]
	s_mov_b32 m0, s54
	s_nop 0
	global_load_lds_dwordx4 v194, s[100:101]
	s_mov_b32 m0, s57
	s_nop 0
	global_load_lds_dwordx4 v130, s[100:101]
	s_waitcnt vmcnt(8)
	s_waitcnt lgkmcnt(0)
	s_barrier
	s_waitcnt lgkmcnt(0)
	v_mfma_f32_16x16x32_bf16 v[62:65], v[144:147], v[178:181], v[62:65]
	v_mfma_f32_16x16x32_bf16 v[62:65], v[148:151], v[182:185], v[62:65]
	v_mfma_f32_16x16x32_bf16 v[58:61], v[158:161], v[182:185], v[58:61]
	v_mfma_f32_16x16x32_bf16 v[58:61], v[154:157], v[178:181], v[58:61]
	v_mfma_f32_16x16x32_bf16 v[54:57], v[162:165], v[178:181], v[54:57]
	v_mfma_f32_16x16x32_bf16 v[54:57], v[166:169], v[182:185], v[54:57]
	v_mfma_f32_16x16x32_bf16 v[50:53], v[174:177], v[182:185], v[50:53]
	v_mfma_f32_16x16x32_bf16 v[50:53], v[170:173], v[178:181], v[50:53]
	v_mfma_f32_16x16x32_bf16 v[34:37], v[170:173], v[186:189], v[34:37]
	v_mfma_f32_16x16x32_bf16 v[34:37], v[174:177], v[190:193], v[34:37]
	v_mfma_f32_16x16x32_bf16 v[38:41], v[166:169], v[190:193], v[38:41]
	v_mfma_f32_16x16x32_bf16 v[38:41], v[162:165], v[186:189], v[38:41]
	v_mfma_f32_16x16x32_bf16 v[42:45], v[154:157], v[186:189], v[42:45]
	v_mfma_f32_16x16x32_bf16 v[42:45], v[158:161], v[190:193], v[42:45]
	v_mfma_f32_16x16x32_bf16 v[46:49], v[148:151], v[190:193], v[46:49]
	v_mfma_f32_16x16x32_bf16 v[46:49], v[144:147], v[186:189], v[46:49]
	v_mfma_f32_16x16x32_bf16 v[30:33], v[144:147], v[204:207], v[30:33]
	v_mfma_f32_16x16x32_bf16 v[30:33], v[148:151], v[208:211], v[30:33]
	v_mfma_f32_16x16x32_bf16 v[26:29], v[158:161], v[208:211], v[26:29]
	v_mfma_f32_16x16x32_bf16 v[26:29], v[154:157], v[204:207], v[26:29]
	v_mfma_f32_16x16x32_bf16 v[22:25], v[162:165], v[204:207], v[22:25]
	v_mfma_f32_16x16x32_bf16 v[22:25], v[166:169], v[208:211], v[22:25]
	v_mfma_f32_16x16x32_bf16 v[18:21], v[174:177], v[208:211], v[18:21]
	v_mfma_f32_16x16x32_bf16 v[18:21], v[170:173], v[204:207], v[18:21]
	v_mfma_f32_16x16x32_bf16 v[2:5], v[170:173], v[212:215], v[2:5]
	v_mfma_f32_16x16x32_bf16 v[2:5], v[174:177], v[216:219], v[2:5]
	v_mfma_f32_16x16x32_bf16 v[6:9], v[166:169], v[216:219], v[6:9]
	v_mfma_f32_16x16x32_bf16 v[6:9], v[162:165], v[212:215], v[6:9]
	v_mfma_f32_16x16x32_bf16 v[10:13], v[154:157], v[212:215], v[10:13]
	v_mfma_f32_16x16x32_bf16 v[10:13], v[158:161], v[216:219], v[10:13]
	v_mfma_f32_16x16x32_bf16 v[14:17], v[148:151], v[216:219], v[14:17]
	v_mfma_f32_16x16x32_bf16 v[14:17], v[144:147], v[212:215], v[14:17]
	s_barrier
	s_add_i32 s76, s76, 2
	s_add_u32 s62, s62, 0x100
	s_addc_u32 s63, s63, 0
	s_add_u32 s53, s53, 0x100
	s_addc_u32 s58, s58, 0
	s_cmp_gt_u32 s76, 29
	s_cbranch_scc1 .LBB0_584
	s_branch .LBB0_582
.Llw_p0_gu:
	s_add_u32 s18, s62, 0xfff80080
	s_addc_u32 s19, s63, -1
	s_and_b64 s[0:1], s[64:65], exec
	s_cselect_b32 s71, s22, s19
	s_cselect_b32 s70, s23, s18
	s_cselect_b32 s65, s39, s58
	s_cselect_b32 s64, s47, s53
	s_add_i32 s0, 0, 0x10000
	v_add_u32_e32 v153, s0, v1
	s_add_i32 s18, 0, 0x14000
	ds_read_b128 v[144:147], v153
	ds_read_b128 v[148:151], v153 offset:1024
	ds_read_b128 v[154:157], v153 offset:2048
	ds_read_b128 v[158:161], v153 offset:3072
	v_add_u32_e32 v153, s18, v1
	ds_read_b128 v[162:165], v153
	ds_read_b128 v[166:169], v153 offset:1024
	ds_read_b128 v[170:173], v153 offset:2048
	ds_read_b128 v[174:177], v153 offset:3072
	s_add_i32 m0, s29, 0xc000
	ds_read_b128 v[178:181], v152
	ds_read_b128 v[182:185], v152 offset:1024
	ds_read_b128 v[186:189], v152 offset:2048
	ds_read_b128 v[190:193], v152 offset:3072
	ds_read_b128 v[204:207], v152 offset:4096
	ds_read_b128 v[208:211], v152 offset:5120
	ds_read_b128 v[212:215], v152 offset:6144
	ds_read_b128 v[216:219], v152 offset:7168
	global_load_lds_dwordx4 v136, s[62:63]
	s_add_i32 m0, s29, 0xe000
	s_nop 0
	global_load_lds_dwordx4 v138, s[62:63]
	s_waitcnt lgkmcnt(0)
	s_barrier
	s_waitcnt lgkmcnt(0)
	v_mfma_f32_16x16x32_bf16 v[126:129], v[144:147], v[178:181], 0
	v_mfma_f32_16x16x32_bf16 v[126:129], v[148:151], v[182:185], v[126:129]
	v_mfma_f32_16x16x32_bf16 v[122:125], v[158:161], v[182:185], 0
	v_mfma_f32_16x16x32_bf16 v[122:125], v[154:157], v[178:181], v[122:125]
	v_mfma_f32_16x16x32_bf16 v[118:121], v[162:165], v[178:181], 0
	v_mfma_f32_16x16x32_bf16 v[118:121], v[166:169], v[182:185], v[118:121]
	v_mfma_f32_16x16x32_bf16 v[114:117], v[174:177], v[182:185], 0
	v_mfma_f32_16x16x32_bf16 v[114:117], v[170:173], v[178:181], v[114:117]
	v_mfma_f32_16x16x32_bf16 v[98:101], v[170:173], v[186:189], 0
	v_mfma_f32_16x16x32_bf16 v[98:101], v[174:177], v[190:193], v[98:101]
	v_mfma_f32_16x16x32_bf16 v[102:105], v[166:169], v[190:193], 0
	v_mfma_f32_16x16x32_bf16 v[102:105], v[162:165], v[186:189], v[102:105]
	v_mfma_f32_16x16x32_bf16 v[106:109], v[154:157], v[186:189], 0
	v_mfma_f32_16x16x32_bf16 v[106:109], v[158:161], v[190:193], v[106:109]
	v_mfma_f32_16x16x32_bf16 v[110:113], v[148:151], v[190:193], 0
	v_mfma_f32_16x16x32_bf16 v[110:113], v[144:147], v[186:189], v[110:113]
	v_mfma_f32_16x16x32_bf16 v[94:97], v[144:147], v[204:207], 0
	v_mfma_f32_16x16x32_bf16 v[94:97], v[148:151], v[208:211], v[94:97]
	v_mfma_f32_16x16x32_bf16 v[90:93], v[158:161], v[208:211], 0
	v_mfma_f32_16x16x32_bf16 v[90:93], v[154:157], v[204:207], v[90:93]
	v_mfma_f32_16x16x32_bf16 v[86:89], v[162:165], v[204:207], 0
	v_mfma_f32_16x16x32_bf16 v[86:89], v[166:169], v[208:211], v[86:89]
	v_mfma_f32_16x16x32_bf16 v[82:85], v[174:177], v[208:211], 0
	v_mfma_f32_16x16x32_bf16 v[82:85], v[170:173], v[204:207], v[82:85]
	v_mfma_f32_16x16x32_bf16 v[66:69], v[170:173], v[212:215], 0
	v_mfma_f32_16x16x32_bf16 v[66:69], v[174:177], v[216:219], v[66:69]
	v_mfma_f32_16x16x32_bf16 v[70:73], v[166:169], v[216:219], 0
	v_mfma_f32_16x16x32_bf16 v[70:73], v[162:165], v[212:215], v[70:73]
	v_mfma_f32_16x16x32_bf16 v[74:77], v[154:157], v[212:215], 0
	v_mfma_f32_16x16x32_bf16 v[74:77], v[158:161], v[216:219], v[74:77]
	v_mfma_f32_16x16x32_bf16 v[78:81], v[148:151], v[216:219], 0
	v_mfma_f32_16x16x32_bf16 v[78:81], v[144:147], v[212:215], v[78:81]
	s_waitcnt vmcnt(8)
	s_barrier
	s_add_i32 s0, s0, s28
	s_mov_b32 m0, s0
	ds_read_b128 v[178:181], v152 offset:16384
	ds_read_b128 v[182:185], v152 offset:17408
	ds_read_b128 v[186:189], v152 offset:18432
	ds_read_b128 v[190:193], v152 offset:19456
	ds_read_b128 v[204:207], v152 offset:20480
	ds_read_b128 v[208:211], v152 offset:21504
	ds_read_b128 v[212:215], v152 offset:22528
	ds_read_b128 v[216:219], v152 offset:23552
	global_load_lds_dwordx4 v194, s[64:65]
	s_add_i32 m0, s0, 0x2000
	s_add_u32 s0, s64, 0x80000
	s_addc_u32 s1, s65, 0
	s_add_i32 s18, s18, s28
	global_load_lds_dwordx4 v130, s[64:65]
	s_mov_b32 m0, s18
	s_nop 0
	global_load_lds_dwordx4 v194, s[0:1]
	s_add_i32 m0, s18, 0x2000
	s_nop 0
	global_load_lds_dwordx4 v130, s[0:1]
	s_mov_b32 m0, s29
	s_nop 0
	global_load_lds_dwordx4 v194, s[70:71]
	s_mov_b32 m0, s31
	s_nop 0
	global_load_lds_dwordx4 v130, s[70:71]
	s_waitcnt lgkmcnt(0)
	s_barrier
	s_waitcnt lgkmcnt(0)
	v_mfma_f32_16x16x32_bf16 v[62:65], v[144:147], v[178:181], 0
	v_mfma_f32_16x16x32_bf16 v[62:65], v[148:151], v[182:185], v[62:65]
	v_mfma_f32_16x16x32_bf16 v[58:61], v[158:161], v[182:185], 0
	v_mfma_f32_16x16x32_bf16 v[58:61], v[154:157], v[178:181], v[58:61]
	v_mfma_f32_16x16x32_bf16 v[54:57], v[162:165], v[178:181], 0
	v_mfma_f32_16x16x32_bf16 v[54:57], v[166:169], v[182:185], v[54:57]
	v_mfma_f32_16x16x32_bf16 v[50:53], v[174:177], v[182:185], 0
	v_mfma_f32_16x16x32_bf16 v[50:53], v[170:173], v[178:181], v[50:53]
	v_mfma_f32_16x16x32_bf16 v[34:37], v[170:173], v[186:189], 0
	v_mfma_f32_16x16x32_bf16 v[34:37], v[174:177], v[190:193], v[34:37]
	v_mfma_f32_16x16x32_bf16 v[38:41], v[166:169], v[190:193], 0
	v_mfma_f32_16x16x32_bf16 v[38:41], v[162:165], v[186:189], v[38:41]
	v_mfma_f32_16x16x32_bf16 v[42:45], v[154:157], v[186:189], 0
	v_mfma_f32_16x16x32_bf16 v[42:45], v[158:161], v[190:193], v[42:45]
	v_mfma_f32_16x16x32_bf16 v[46:49], v[148:151], v[190:193], 0
	v_mfma_f32_16x16x32_bf16 v[46:49], v[144:147], v[186:189], v[46:49]
	v_mfma_f32_16x16x32_bf16 v[30:33], v[144:147], v[204:207], 0
	v_mfma_f32_16x16x32_bf16 v[30:33], v[148:151], v[208:211], v[30:33]
	v_mfma_f32_16x16x32_bf16 v[26:29], v[158:161], v[208:211], 0
	v_mfma_f32_16x16x32_bf16 v[26:29], v[154:157], v[204:207], v[26:29]
	v_mfma_f32_16x16x32_bf16 v[22:25], v[162:165], v[204:207], 0
	v_mfma_f32_16x16x32_bf16 v[22:25], v[166:169], v[208:211], v[22:25]
	v_mfma_f32_16x16x32_bf16 v[18:21], v[174:177], v[208:211], 0
	v_mfma_f32_16x16x32_bf16 v[18:21], v[170:173], v[204:207], v[18:21]
	v_mfma_f32_16x16x32_bf16 v[2:5], v[170:173], v[212:215], 0
	v_mfma_f32_16x16x32_bf16 v[2:5], v[174:177], v[216:219], v[2:5]
	v_mfma_f32_16x16x32_bf16 v[6:9], v[166:169], v[216:219], 0
	v_mfma_f32_16x16x32_bf16 v[6:9], v[162:165], v[212:215], v[6:9]
	v_mfma_f32_16x16x32_bf16 v[10:13], v[154:157], v[212:215], 0
	v_mfma_f32_16x16x32_bf16 v[10:13], v[158:161], v[216:219], v[10:13]
	v_mfma_f32_16x16x32_bf16 v[14:17], v[148:151], v[216:219], 0
	v_mfma_f32_16x16x32_bf16 v[14:17], v[144:147], v[212:215], v[14:17]
	s_waitcnt vmcnt(8)
	s_barrier
	s_add_i32 s18, 0, 0x18000
	v_add_u32_e32 v153, s18, v1
	s_add_i32 s19, 0, 0x1c000
	ds_read_b128 v[144:147], v153
	ds_read_b128 v[148:151], v153 offset:1024
	ds_read_b128 v[154:157], v153 offset:2048
	ds_read_b128 v[158:161], v153 offset:3072
	v_add_u32_e32 v153, s19, v1
	ds_read_b128 v[162:165], v153
	ds_read_b128 v[166:169], v153 offset:1024
	ds_read_b128 v[170:173], v153 offset:2048
	ds_read_b128 v[174:177], v153 offset:3072
	s_add_u32 s0, s70, 0x80000
	s_addc_u32 s1, s71, 0
	s_mov_b32 m0, s33
	ds_read_b128 v[178:181], v152 offset:32768
	ds_read_b128 v[182:185], v152 offset:33792
	ds_read_b128 v[186:189], v152 offset:34816
	ds_read_b128 v[190:193], v152 offset:35840
	ds_read_b128 v[204:207], v152 offset:36864
	ds_read_b128 v[208:211], v152 offset:37888
	ds_read_b128 v[212:215], v152 offset:38912
	ds_read_b128 v[216:219], v152 offset:39936
	global_load_lds_dwordx4 v194, s[0:1]
	s_mov_b32 m0, s40
	s_nop 0
	global_load_lds_dwordx4 v130, s[0:1]
	s_waitcnt lgkmcnt(0)
	s_barrier
	s_waitcnt lgkmcnt(0)
	v_mfma_f32_16x16x32_bf16 v[126:129], v[144:147], v[178:181], v[126:129]
	v_mfma_f32_16x16x32_bf16 v[126:129], v[148:151], v[182:185], v[126:129]
	v_mfma_f32_16x16x32_bf16 v[122:125], v[158:161], v[182:185], v[122:125]
	v_mfma_f32_16x16x32_bf16 v[122:125], v[154:157], v[178:181], v[122:125]
	v_mfma_f32_16x16x32_bf16 v[118:121], v[162:165], v[178:181], v[118:121]
	v_mfma_f32_16x16x32_bf16 v[118:121], v[166:169], v[182:185], v[118:121]
	v_mfma_f32_16x16x32_bf16 v[114:117], v[174:177], v[182:185], v[114:117]
	v_mfma_f32_16x16x32_bf16 v[114:117], v[170:173], v[178:181], v[114:117]
	v_mfma_f32_16x16x32_bf16 v[98:101], v[170:173], v[186:189], v[98:101]
	v_mfma_f32_16x16x32_bf16 v[98:101], v[174:177], v[190:193], v[98:101]
	v_mfma_f32_16x16x32_bf16 v[102:105], v[166:169], v[190:193], v[102:105]
	v_mfma_f32_16x16x32_bf16 v[102:105], v[162:165], v[186:189], v[102:105]
	v_mfma_f32_16x16x32_bf16 v[106:109], v[154:157], v[186:189], v[106:109]
	v_mfma_f32_16x16x32_bf16 v[106:109], v[158:161], v[190:193], v[106:109]
	v_mfma_f32_16x16x32_bf16 v[110:113], v[148:151], v[190:193], v[110:113]
	v_mfma_f32_16x16x32_bf16 v[110:113], v[144:147], v[186:189], v[110:113]
	v_mfma_f32_16x16x32_bf16 v[94:97], v[144:147], v[204:207], v[94:97]
	v_mfma_f32_16x16x32_bf16 v[94:97], v[148:151], v[208:211], v[94:97]
	v_mfma_f32_16x16x32_bf16 v[90:93], v[158:161], v[208:211], v[90:93]
	v_mfma_f32_16x16x32_bf16 v[90:93], v[154:157], v[204:207], v[90:93]
	v_mfma_f32_16x16x32_bf16 v[86:89], v[162:165], v[204:207], v[86:89]
	v_mfma_f32_16x16x32_bf16 v[86:89], v[166:169], v[208:211], v[86:89]
	v_mfma_f32_16x16x32_bf16 v[82:85], v[174:177], v[208:211], v[82:85]
	v_mfma_f32_16x16x32_bf16 v[82:85], v[170:173], v[204:207], v[82:85]
	v_mfma_f32_16x16x32_bf16 v[66:69], v[170:173], v[212:215], v[66:69]
	v_mfma_f32_16x16x32_bf16 v[66:69], v[174:177], v[216:219], v[66:69]
	v_mfma_f32_16x16x32_bf16 v[70:73], v[166:169], v[216:219], v[70:73]
	v_mfma_f32_16x16x32_bf16 v[70:73], v[162:165], v[212:215], v[70:73]
	v_mfma_f32_16x16x32_bf16 v[74:77], v[154:157], v[212:215], v[74:77]
	v_mfma_f32_16x16x32_bf16 v[74:77], v[158:161], v[216:219], v[74:77]
	v_mfma_f32_16x16x32_bf16 v[78:81], v[148:151], v[216:219], v[78:81]
	v_mfma_f32_16x16x32_bf16 v[78:81], v[144:147], v[212:215], v[78:81]
	s_waitcnt vmcnt(8)
	s_barrier
	s_add_u32 s98, s64, 0x80
	s_addc_u32 s99, s65, 0
	s_add_u32 s100, s70, 0x80
	s_addc_u32 s101, s71, 0
	s_add_i32 s0, s18, s28
	s_mov_b32 m0, s0
	ds_read_b128 v[178:181], v152 offset:49152
	ds_read_b128 v[182:185], v152 offset:50176
	ds_read_b128 v[186:189], v152 offset:51200
	ds_read_b128 v[190:193], v152 offset:52224
	ds_read_b128 v[204:207], v152 offset:53248
	ds_read_b128 v[208:211], v152 offset:54272
	ds_read_b128 v[212:215], v152 offset:55296
	ds_read_b128 v[216:219], v152 offset:56320
	global_load_lds_dwordx4 v194, s[98:99]
	s_add_i32 m0, s0, 0x2000
	s_add_u32 s0, s64, 0x80080
	s_addc_u32 s1, s65, 0
	s_add_i32 s18, s19, s28
	global_load_lds_dwordx4 v130, s[98:99]
	s_mov_b32 m0, s18
	s_nop 0
	global_load_lds_dwordx4 v194, s[0:1]
	s_add_i32 m0, s18, 0x2000
	s_nop 0
	global_load_lds_dwordx4 v130, s[0:1]
	s_mov_b32 m0, s54
	s_nop 0
	global_load_lds_dwordx4 v194, s[100:101]
	s_mov_b32 m0, s57
	s_nop 0
	global_load_lds_dwordx4 v130, s[100:101]
	s_waitcnt lgkmcnt(0)
	s_barrier
	s_waitcnt lgkmcnt(0)
	v_mfma_f32_16x16x32_bf16 v[62:65], v[144:147], v[178:181], v[62:65]
	v_mfma_f32_16x16x32_bf16 v[62:65], v[148:151], v[182:185], v[62:65]
	v_mfma_f32_16x16x32_bf16 v[58:61], v[158:161], v[182:185], v[58:61]
	v_mfma_f32_16x16x32_bf16 v[58:61], v[154:157], v[178:181], v[58:61]
	v_mfma_f32_16x16x32_bf16 v[54:57], v[162:165], v[178:181], v[54:57]
	v_mfma_f32_16x16x32_bf16 v[54:57], v[166:169], v[182:185], v[54:57]
	v_mfma_f32_16x16x32_bf16 v[50:53], v[174:177], v[182:185], v[50:53]
	v_mfma_f32_16x16x32_bf16 v[50:53], v[170:173], v[178:181], v[50:53]
	v_mfma_f32_16x16x32_bf16 v[34:37], v[170:173], v[186:189], v[34:37]
	v_mfma_f32_16x16x32_bf16 v[34:37], v[174:177], v[190:193], v[34:37]
	v_mfma_f32_16x16x32_bf16 v[38:41], v[166:169], v[190:193], v[38:41]
	v_mfma_f32_16x16x32_bf16 v[38:41], v[162:165], v[186:189], v[38:41]
	v_mfma_f32_16x16x32_bf16 v[42:45], v[154:157], v[186:189], v[42:45]
	v_mfma_f32_16x16x32_bf16 v[42:45], v[158:161], v[190:193], v[42:45]
	v_mfma_f32_16x16x32_bf16 v[46:49], v[148:151], v[190:193], v[46:49]
	v_mfma_f32_16x16x32_bf16 v[46:49], v[144:147], v[186:189], v[46:49]
	v_mfma_f32_16x16x32_bf16 v[30:33], v[144:147], v[204:207], v[30:33]
	v_mfma_f32_16x16x32_bf16 v[30:33], v[148:151], v[208:211], v[30:33]
	v_mfma_f32_16x16x32_bf16 v[26:29], v[158:161], v[208:211], v[26:29]
	v_mfma_f32_16x16x32_bf16 v[26:29], v[154:157], v[204:207], v[26:29]
	v_mfma_f32_16x16x32_bf16 v[22:25], v[162:165], v[204:207], v[22:25]
	v_mfma_f32_16x16x32_bf16 v[22:25], v[166:169], v[208:211], v[22:25]
	v_mfma_f32_16x16x32_bf16 v[18:21], v[174:177], v[208:211], v[18:21]
	v_mfma_f32_16x16x32_bf16 v[18:21], v[170:173], v[204:207], v[18:21]
	v_mfma_f32_16x16x32_bf16 v[2:5], v[170:173], v[212:215], v[2:5]
	v_mfma_f32_16x16x32_bf16 v[2:5], v[174:177], v[216:219], v[2:5]
	v_mfma_f32_16x16x32_bf16 v[6:9], v[166:169], v[216:219], v[6:9]
	v_mfma_f32_16x16x32_bf16 v[6:9], v[162:165], v[212:215], v[6:9]
	v_mfma_f32_16x16x32_bf16 v[10:13], v[154:157], v[212:215], v[10:13]
	v_mfma_f32_16x16x32_bf16 v[10:13], v[158:161], v[216:219], v[10:13]
	v_mfma_f32_16x16x32_bf16 v[14:17], v[148:151], v[216:219], v[14:17]
	v_mfma_f32_16x16x32_bf16 v[14:17], v[144:147], v[212:215], v[14:17]
	s_waitcnt vmcnt(8)
	s_barrier
	s_add_i32 s76, s76, 2
	s_add_u32 s62, s62, 0x100
	s_addc_u32 s63, s63, 0
	s_add_u32 s53, s53, 0x100
	s_addc_u32 s58, s58, 0
	s_cmp_gt_u32 s76, 29
	s_cbranch_scc1 .LBB0_584
	s_branch .LBB0_582
.Llw_main_gu:
	s_cmp_eq_u32 s98, 0
	s_cbranch_scc0 .LBB0_581
	s_add_u32 s18, s62, 0xfff80080
	s_addc_u32 s19, s63, -1
	s_and_b64 s[0:1], s[64:65], exec
	s_cselect_b32 s71, s22, s19
	s_cselect_b32 s70, s23, s18
	s_cselect_b32 s65, s39, s58
	s_cselect_b32 s64, s47, s53
	s_add_i32 s0, 0, 0x10000
	v_add_u32_e32 v153, s0, v1
	s_add_i32 s18, 0, 0x14000
	ds_read_b128 v[144:147], v153
	ds_read_b128 v[148:151], v153 offset:1024
	ds_read_b128 v[154:157], v153 offset:2048
	ds_read_b128 v[158:161], v153 offset:3072
	v_add_u32_e32 v153, s18, v1
	ds_read_b128 v[162:165], v153
	ds_read_b128 v[166:169], v153 offset:1024
	ds_read_b128 v[170:173], v153 offset:2048
	ds_read_b128 v[174:177], v153 offset:3072
	s_add_i32 m0, s29, 0xc000
	ds_read_b128 v[178:181], v152
	ds_read_b128 v[182:185], v152 offset:1024
	ds_read_b128 v[186:189], v152 offset:2048
	ds_read_b128 v[190:193], v152 offset:3072
	ds_read_b128 v[204:207], v152 offset:4096
	ds_read_b128 v[208:211], v152 offset:5120
	ds_read_b128 v[212:215], v152 offset:6144
	ds_read_b128 v[216:219], v152 offset:7168
	global_load_lds_dwordx4 v136, s[62:63]
	s_add_i32 m0, s29, 0xe000
	s_nop 0
	global_load_lds_dwordx4 v138, s[62:63]
	s_waitcnt lgkmcnt(0)
	s_barrier
	s_waitcnt lgkmcnt(0)
	v_mfma_f32_16x16x32_bf16 v[126:129], v[144:147], v[178:181], v[126:129]
	v_mfma_f32_16x16x32_bf16 v[126:129], v[148:151], v[182:185], v[126:129]
	v_mfma_f32_16x16x32_bf16 v[122:125], v[158:161], v[182:185], v[122:125]
	v_mfma_f32_16x16x32_bf16 v[122:125], v[154:157], v[178:181], v[122:125]
	v_mfma_f32_16x16x32_bf16 v[118:121], v[162:165], v[178:181], v[118:121]
	v_mfma_f32_16x16x32_bf16 v[118:121], v[166:169], v[182:185], v[118:121]
	v_mfma_f32_16x16x32_bf16 v[114:117], v[174:177], v[182:185], v[114:117]
	v_mfma_f32_16x16x32_bf16 v[114:117], v[170:173], v[178:181], v[114:117]
	v_mfma_f32_16x16x32_bf16 v[98:101], v[170:173], v[186:189], v[98:101]
	v_mfma_f32_16x16x32_bf16 v[98:101], v[174:177], v[190:193], v[98:101]
	v_mfma_f32_16x16x32_bf16 v[102:105], v[166:169], v[190:193], v[102:105]
	v_mfma_f32_16x16x32_bf16 v[102:105], v[162:165], v[186:189], v[102:105]
	v_mfma_f32_16x16x32_bf16 v[106:109], v[154:157], v[186:189], v[106:109]
	v_mfma_f32_16x16x32_bf16 v[106:109], v[158:161], v[190:193], v[106:109]
	v_mfma_f32_16x16x32_bf16 v[110:113], v[148:151], v[190:193], v[110:113]
	v_mfma_f32_16x16x32_bf16 v[110:113], v[144:147], v[186:189], v[110:113]
	v_mfma_f32_16x16x32_bf16 v[94:97], v[144:147], v[204:207], v[94:97]
	v_mfma_f32_16x16x32_bf16 v[94:97], v[148:151], v[208:211], v[94:97]
	v_mfma_f32_16x16x32_bf16 v[90:93], v[158:161], v[208:211], v[90:93]
	v_mfma_f32_16x16x32_bf16 v[90:93], v[154:157], v[204:207], v[90:93]
	v_mfma_f32_16x16x32_bf16 v[86:89], v[162:165], v[204:207], v[86:89]
	v_mfma_f32_16x16x32_bf16 v[86:89], v[166:169], v[208:211], v[86:89]
	v_mfma_f32_16x16x32_bf16 v[82:85], v[174:177], v[208:211], v[82:85]
	v_mfma_f32_16x16x32_bf16 v[82:85], v[170:173], v[204:207], v[82:85]
	v_mfma_f32_16x16x32_bf16 v[66:69], v[170:173], v[212:215], v[66:69]
	v_mfma_f32_16x16x32_bf16 v[66:69], v[174:177], v[216:219], v[66:69]
	v_mfma_f32_16x16x32_bf16 v[70:73], v[166:169], v[216:219], v[70:73]
	v_mfma_f32_16x16x32_bf16 v[70:73], v[162:165], v[212:215], v[70:73]
	v_mfma_f32_16x16x32_bf16 v[74:77], v[154:157], v[212:215], v[74:77]
	v_mfma_f32_16x16x32_bf16 v[74:77], v[158:161], v[216:219], v[74:77]
	v_mfma_f32_16x16x32_bf16 v[78:81], v[148:151], v[216:219], v[78:81]
	v_mfma_f32_16x16x32_bf16 v[78:81], v[144:147], v[212:215], v[78:81]
	s_waitcnt vmcnt(8)
	s_barrier
	s_add_i32 s0, s0, s28
	s_mov_b32 m0, s0
	ds_read_b128 v[178:181], v152 offset:16384
	ds_read_b128 v[182:185], v152 offset:17408
	ds_read_b128 v[186:189], v152 offset:18432
	ds_read_b128 v[190:193], v152 offset:19456
	ds_read_b128 v[204:207], v152 offset:20480
	ds_read_b128 v[208:211], v152 offset:21504
	ds_read_b128 v[212:215], v152 offset:22528
	ds_read_b128 v[216:219], v152 offset:23552
	global_load_lds_dwordx4 v194, s[64:65]
	s_add_i32 m0, s0, 0x2000
	s_add_u32 s0, s64, 0x80000
	s_addc_u32 s1, s65, 0
	s_add_i32 s18, s18, s28
	global_load_lds_dwordx4 v130, s[64:65]
	s_mov_b32 m0, s18
	s_nop 0
	global_load_lds_dwordx4 v194, s[0:1]
	s_add_i32 m0, s18, 0x2000
	s_nop 0
	global_load_lds_dwordx4 v130, s[0:1]
	s_mov_b32 m0, s29
	s_nop 0
	global_load_lds_dwordx4 v194, s[70:71]
	s_mov_b32 m0, s31
	s_nop 0
	global_load_lds_dwordx4 v130, s[70:71]
	s_waitcnt lgkmcnt(0)
	s_barrier
	s_waitcnt lgkmcnt(0)
	v_mfma_f32_16x16x32_bf16 v[62:65], v[144:147], v[178:181], v[62:65]
	v_mfma_f32_16x16x32_bf16 v[62:65], v[148:151], v[182:185], v[62:65]
	v_mfma_f32_16x16x32_bf16 v[58:61], v[158:161], v[182:185], v[58:61]
	v_mfma_f32_16x16x32_bf16 v[58:61], v[154:157], v[178:181], v[58:61]
	v_mfma_f32_16x16x32_bf16 v[54:57], v[162:165], v[178:181], v[54:57]
	v_mfma_f32_16x16x32_bf16 v[54:57], v[166:169], v[182:185], v[54:57]
	v_mfma_f32_16x16x32_bf16 v[50:53], v[174:177], v[182:185], v[50:53]
	v_mfma_f32_16x16x32_bf16 v[50:53], v[170:173], v[178:181], v[50:53]
	v_mfma_f32_16x16x32_bf16 v[34:37], v[170:173], v[186:189], v[34:37]
	v_mfma_f32_16x16x32_bf16 v[34:37], v[174:177], v[190:193], v[34:37]
	v_mfma_f32_16x16x32_bf16 v[38:41], v[166:169], v[190:193], v[38:41]
	v_mfma_f32_16x16x32_bf16 v[38:41], v[162:165], v[186:189], v[38:41]
	v_mfma_f32_16x16x32_bf16 v[42:45], v[154:157], v[186:189], v[42:45]
	v_mfma_f32_16x16x32_bf16 v[42:45], v[158:161], v[190:193], v[42:45]
	v_mfma_f32_16x16x32_bf16 v[46:49], v[148:151], v[190:193], v[46:49]
	v_mfma_f32_16x16x32_bf16 v[46:49], v[144:147], v[186:189], v[46:49]
	v_mfma_f32_16x16x32_bf16 v[30:33], v[144:147], v[204:207], v[30:33]
	v_mfma_f32_16x16x32_bf16 v[30:33], v[148:151], v[208:211], v[30:33]
	v_mfma_f32_16x16x32_bf16 v[26:29], v[158:161], v[208:211], v[26:29]
	v_mfma_f32_16x16x32_bf16 v[26:29], v[154:157], v[204:207], v[26:29]
	v_mfma_f32_16x16x32_bf16 v[22:25], v[162:165], v[204:207], v[22:25]
	v_mfma_f32_16x16x32_bf16 v[22:25], v[166:169], v[208:211], v[22:25]
	v_mfma_f32_16x16x32_bf16 v[18:21], v[174:177], v[208:211], v[18:21]
	v_mfma_f32_16x16x32_bf16 v[18:21], v[170:173], v[204:207], v[18:21]
	v_mfma_f32_16x16x32_bf16 v[2:5], v[170:173], v[212:215], v[2:5]
	v_mfma_f32_16x16x32_bf16 v[2:5], v[174:177], v[216:219], v[2:5]
	v_mfma_f32_16x16x32_bf16 v[6:9], v[166:169], v[216:219], v[6:9]
	v_mfma_f32_16x16x32_bf16 v[6:9], v[162:165], v[212:215], v[6:9]
	v_mfma_f32_16x16x32_bf16 v[10:13], v[154:157], v[212:215], v[10:13]
	v_mfma_f32_16x16x32_bf16 v[10:13], v[158:161], v[216:219], v[10:13]
	v_mfma_f32_16x16x32_bf16 v[14:17], v[148:151], v[216:219], v[14:17]
	v_mfma_f32_16x16x32_bf16 v[14:17], v[144:147], v[212:215], v[14:17]
	s_waitcnt vmcnt(8)
	s_barrier
	s_add_i32 s18, 0, 0x18000
	v_add_u32_e32 v153, s18, v1
	s_add_i32 s19, 0, 0x1c000
	ds_read_b128 v[144:147], v153
	ds_read_b128 v[148:151], v153 offset:1024
	ds_read_b128 v[154:157], v153 offset:2048
	ds_read_b128 v[158:161], v153 offset:3072
	v_add_u32_e32 v153, s19, v1
	ds_read_b128 v[162:165], v153
	ds_read_b128 v[166:169], v153 offset:1024
	ds_read_b128 v[170:173], v153 offset:2048
	ds_read_b128 v[174:177], v153 offset:3072
	s_add_u32 s0, s70, 0x80000
	s_addc_u32 s1, s71, 0
	s_mov_b32 m0, s33
	ds_read_b128 v[178:181], v152 offset:32768
	ds_read_b128 v[182:185], v152 offset:33792
	ds_read_b128 v[186:189], v152 offset:34816
	ds_read_b128 v[190:193], v152 offset:35840
	ds_read_b128 v[204:207], v152 offset:36864
	ds_read_b128 v[208:211], v152 offset:37888
	ds_read_b128 v[212:215], v152 offset:38912
	ds_read_b128 v[216:219], v152 offset:39936
	global_load_lds_dwordx4 v194, s[0:1]
	s_mov_b32 m0, s40
	s_nop 0
	global_load_lds_dwordx4 v130, s[0:1]
	s_waitcnt lgkmcnt(0)
	s_barrier
	s_waitcnt lgkmcnt(0)
	v_mfma_f32_16x16x32_bf16 v[126:129], v[144:147], v[178:181], v[126:129]
	v_mfma_f32_16x16x32_bf16 v[126:129], v[148:151], v[182:185], v[126:129]
	v_mfma_f32_16x16x32_bf16 v[122:125], v[158:161], v[182:185], v[122:125]
	v_mfma_f32_16x16x32_bf16 v[122:125], v[154:157], v[178:181], v[122:125]
	v_mfma_f32_16x16x32_bf16 v[118:121], v[162:165], v[178:181], v[118:121]
	v_mfma_f32_16x16x32_bf16 v[118:121], v[166:169], v[182:185], v[118:121]
	v_mfma_f32_16x16x32_bf16 v[114:117], v[174:177], v[182:185], v[114:117]
	v_mfma_f32_16x16x32_bf16 v[114:117], v[170:173], v[178:181], v[114:117]
	v_mfma_f32_16x16x32_bf16 v[98:101], v[170:173], v[186:189], v[98:101]
	v_mfma_f32_16x16x32_bf16 v[98:101], v[174:177], v[190:193], v[98:101]
	v_mfma_f32_16x16x32_bf16 v[102:105], v[166:169], v[190:193], v[102:105]
	v_mfma_f32_16x16x32_bf16 v[102:105], v[162:165], v[186:189], v[102:105]
	v_mfma_f32_16x16x32_bf16 v[106:109], v[154:157], v[186:189], v[106:109]
	v_mfma_f32_16x16x32_bf16 v[106:109], v[158:161], v[190:193], v[106:109]
	v_mfma_f32_16x16x32_bf16 v[110:113], v[148:151], v[190:193], v[110:113]
	v_mfma_f32_16x16x32_bf16 v[110:113], v[144:147], v[186:189], v[110:113]
	v_mfma_f32_16x16x32_bf16 v[94:97], v[144:147], v[204:207], v[94:97]
	v_mfma_f32_16x16x32_bf16 v[94:97], v[148:151], v[208:211], v[94:97]
	v_mfma_f32_16x16x32_bf16 v[90:93], v[158:161], v[208:211], v[90:93]
	v_mfma_f32_16x16x32_bf16 v[90:93], v[154:157], v[204:207], v[90:93]
	v_mfma_f32_16x16x32_bf16 v[86:89], v[162:165], v[204:207], v[86:89]
	v_mfma_f32_16x16x32_bf16 v[86:89], v[166:169], v[208:211], v[86:89]
	v_mfma_f32_16x16x32_bf16 v[82:85], v[174:177], v[208:211], v[82:85]
	v_mfma_f32_16x16x32_bf16 v[82:85], v[170:173], v[204:207], v[82:85]
	v_mfma_f32_16x16x32_bf16 v[66:69], v[170:173], v[212:215], v[66:69]
	v_mfma_f32_16x16x32_bf16 v[66:69], v[174:177], v[216:219], v[66:69]
	v_mfma_f32_16x16x32_bf16 v[70:73], v[166:169], v[216:219], v[70:73]
	v_mfma_f32_16x16x32_bf16 v[70:73], v[162:165], v[212:215], v[70:73]
	v_mfma_f32_16x16x32_bf16 v[74:77], v[154:157], v[212:215], v[74:77]
	v_mfma_f32_16x16x32_bf16 v[74:77], v[158:161], v[216:219], v[74:77]
	v_mfma_f32_16x16x32_bf16 v[78:81], v[148:151], v[216:219], v[78:81]
	v_mfma_f32_16x16x32_bf16 v[78:81], v[144:147], v[212:215], v[78:81]
	s_waitcnt vmcnt(8)
	s_barrier
	s_add_u32 s98, s64, 0x80
	s_addc_u32 s99, s65, 0
	s_add_u32 s100, s70, 0x80
	s_addc_u32 s101, s71, 0
	s_add_i32 s0, s18, s28
	s_mov_b32 m0, s0
	ds_read_b128 v[178:181], v152 offset:49152
	ds_read_b128 v[182:185], v152 offset:50176
	ds_read_b128 v[186:189], v152 offset:51200
	ds_read_b128 v[190:193], v152 offset:52224
	ds_read_b128 v[204:207], v152 offset:53248
	ds_read_b128 v[208:211], v152 offset:54272
	ds_read_b128 v[212:215], v152 offset:55296
	ds_read_b128 v[216:219], v152 offset:56320
	global_load_lds_dwordx4 v194, s[98:99]
	s_add_i32 m0, s0, 0x2000
	s_add_u32 s0, s64, 0x80080
	s_addc_u32 s1, s65, 0
	s_add_i32 s18, s19, s28
	global_load_lds_dwordx4 v130, s[98:99]
	s_mov_b32 m0, s18
	s_nop 0
	global_load_lds_dwordx4 v194, s[0:1]
	s_add_i32 m0, s18, 0x2000
	s_nop 0
	global_load_lds_dwordx4 v130, s[0:1]
	s_mov_b32 m0, s54
	s_nop 0
	global_load_lds_dwordx4 v194, s[100:101]
	s_mov_b32 m0, s57
	s_nop 0
	global_load_lds_dwordx4 v130, s[100:101]
	s_waitcnt lgkmcnt(0)
	s_barrier
	s_waitcnt lgkmcnt(0)
	v_mfma_f32_16x16x32_bf16 v[62:65], v[144:147], v[178:181], v[62:65]
	v_mfma_f32_16x16x32_bf16 v[62:65], v[148:151], v[182:185], v[62:65]
	v_mfma_f32_16x16x32_bf16 v[58:61], v[158:161], v[182:185], v[58:61]
	v_mfma_f32_16x16x32_bf16 v[58:61], v[154:157], v[178:181], v[58:61]
	v_mfma_f32_16x16x32_bf16 v[54:57], v[162:165], v[178:181], v[54:57]
	v_mfma_f32_16x16x32_bf16 v[54:57], v[166:169], v[182:185], v[54:57]
	v_mfma_f32_16x16x32_bf16 v[50:53], v[174:177], v[182:185], v[50:53]
	v_mfma_f32_16x16x32_bf16 v[50:53], v[170:173], v[178:181], v[50:53]
	v_mfma_f32_16x16x32_bf16 v[34:37], v[170:173], v[186:189], v[34:37]
	v_mfma_f32_16x16x32_bf16 v[34:37], v[174:177], v[190:193], v[34:37]
	v_mfma_f32_16x16x32_bf16 v[38:41], v[166:169], v[190:193], v[38:41]
	v_mfma_f32_16x16x32_bf16 v[38:41], v[162:165], v[186:189], v[38:41]
	v_mfma_f32_16x16x32_bf16 v[42:45], v[154:157], v[186:189], v[42:45]
	v_mfma_f32_16x16x32_bf16 v[42:45], v[158:161], v[190:193], v[42:45]
	v_mfma_f32_16x16x32_bf16 v[46:49], v[148:151], v[190:193], v[46:49]
	v_mfma_f32_16x16x32_bf16 v[46:49], v[144:147], v[186:189], v[46:49]
	v_mfma_f32_16x16x32_bf16 v[30:33], v[144:147], v[204:207], v[30:33]
	v_mfma_f32_16x16x32_bf16 v[30:33], v[148:151], v[208:211], v[30:33]
	v_mfma_f32_16x16x32_bf16 v[26:29], v[158:161], v[208:211], v[26:29]
	v_mfma_f32_16x16x32_bf16 v[26:29], v[154:157], v[204:207], v[26:29]
	v_mfma_f32_16x16x32_bf16 v[22:25], v[162:165], v[204:207], v[22:25]
	v_mfma_f32_16x16x32_bf16 v[22:25], v[166:169], v[208:211], v[22:25]
	v_mfma_f32_16x16x32_bf16 v[18:21], v[174:177], v[208:211], v[18:21]
	v_mfma_f32_16x16x32_bf16 v[18:21], v[170:173], v[204:207], v[18:21]
	v_mfma_f32_16x16x32_bf16 v[2:5], v[170:173], v[212:215], v[2:5]
	v_mfma_f32_16x16x32_bf16 v[2:5], v[174:177], v[216:219], v[2:5]
	v_mfma_f32_16x16x32_bf16 v[6:9], v[166:169], v[216:219], v[6:9]
	v_mfma_f32_16x16x32_bf16 v[6:9], v[162:165], v[212:215], v[6:9]
	v_mfma_f32_16x16x32_bf16 v[10:13], v[154:157], v[212:215], v[10:13]
	v_mfma_f32_16x16x32_bf16 v[10:13], v[158:161], v[216:219], v[10:13]
	v_mfma_f32_16x16x32_bf16 v[14:17], v[148:151], v[216:219], v[14:17]
	v_mfma_f32_16x16x32_bf16 v[14:17], v[144:147], v[212:215], v[14:17]
	s_waitcnt vmcnt(8)
	s_barrier
	s_add_i32 s76, s76, 2
	s_add_u32 s62, s62, 0x100
	s_addc_u32 s63, s63, 0
	s_add_u32 s53, s53, 0x100
	s_addc_u32 s58, s58, 0
	s_cmp_gt_u32 s76, 29
	s_cbranch_scc1 .LBB0_584
	s_branch .LBB0_582

.LBB0_627:
	v_readlane_b32 s8, v254, 1
	s_cmp_gt_i32 s8, s20
	s_cselect_b64 s[0:1], -1, 0
	s_xor_b64 s[6:7], s[6:7], -1
	s_or_b64 s[0:1], s[0:1], s[6:7]
	s_and_b64 vcc, exec, s[0:1]
	v_readlane_b32 s9, v254, 2
	v_readlane_b32 s10, v254, 3
	v_readlane_b32 s11, v254, 4
	s_cbranch_vccnz .LBB0_702
	v_mov_b32_e32 v1, v0
	s_mov_b32 s6, 19
	s_and_b64 vcc, exec, s[4:5]
	v_readfirstlane_b32 s22, v1
	s_cbranch_vccnz .LBB0_702
	v_lshlrev_b32_e32 v2, 4, v1
	v_add_u32_e32 v3, 0x2000, v2
	v_ashrrev_i32_e32 v4, 31, v3
	v_lshrrev_b32_e32 v4, 22, v4
	v_add_u32_e32 v4, v3, v4
	v_ashrrev_i32_e32 v10, 10, v4
	v_mul_i32_i24_e32 v4, 0x400, v10
	v_sub_u32_e32 v3, v3, v4
	v_lshrrev_b32_e32 v4, 4, v3
	v_bitop3_b32 v3, v4, v3, 32 bitop3:0x6c
	v_ashrrev_i32_e32 v4, 31, v3
	s_ashr_i32 s7, s6, 31
	v_lshrrev_b32_e32 v4, 26, v4
	s_lshl_b64 s[0:1], s[6:7], 3
	v_readlane_b32 s4, v254, 7
	v_add_u32_e32 v4, v3, v4
	v_readlane_b32 s5, v254, 8
	s_add_u32 s0, s4, s0
	v_ashrrev_i32_e32 v11, 6, v4
	v_and_b32_e32 v4, 0xc0, v4
	s_addc_u32 s1, s5, s1
	v_sub_u32_e32 v3, v3, v4
	s_load_dwordx2 s[4:5], s[0:1], 0x0
	v_ashrrev_i16_sdwa v3, v233, sext(v3) dst_sel:DWORD dst_unused:UNUSED_PAD src0_sel:DWORD src1_sel:BYTE_0
	v_bfe_i32 v13, v3, 0, 16
	v_bfe_i32 v3, v1, 27, 1
	v_lshrrev_b32_e32 v3, 22, v3
	v_add_u32_e32 v3, v2, v3
	v_and_b32_e32 v3, 0xfffffc00, v3
	s_waitcnt lgkmcnt(0)
	s_add_u32 s20, s4, 0x23000000
	v_sub_u32_e32 v2, v2, v3
	s_mul_i32 s1, s75, 0x1600000
	s_addc_u32 s21, s5, 0
	v_lshrrev_b32_e32 v3, 4, v2
	v_ashrrev_i32_e32 v4, 31, v1
	s_mul_hi_u32 s0, s75, 0x1600000
	s_add_u32 s1, s4, s1
	v_bitop3_b32 v2, v3, v2, 32 bitop3:0x6c
	v_lshrrev_b32_e32 v4, 26, v4
	s_addc_u32 s0, s5, s0
	v_lshlrev_b32_e32 v5, 3, v10
	v_ashrrev_i32_e32 v3, 31, v2
	v_add_u32_e32 v4, v1, v4
	s_add_u32 s26, s1, 0x15800000
	v_and_b32_e32 v5, 0x7ffff0, v5
	v_lshrrev_b32_e32 v3, 26, v3
	v_ashrrev_i32_e32 v15, 6, v4
	s_addc_u32 s27, s0, 0
	v_add_u32_e32 v5, v11, v5
	s_movk_i32 s0, 0x1600
	v_lshlrev_b32_e32 v6, 5, v10
	v_add_u32_e32 v3, v2, v3
	v_lshlrev_b32_e32 v4, 3, v15
	v_mul_lo_u32 v5, v5, s0
	v_and_b32_e32 v12, 32, v6
	v_ashrrev_i32_e32 v14, 6, v3
	v_and_b32_e32 v4, 0x7ffff0, v4
	s_ashr_i32 s6, s22, 6
	v_or_b32_e32 v5, v5, v12
	v_add_u32_e32 v4, v14, v4
	v_and_b32_e32 v3, 0xc0, v3
	v_readlane_b32 s1, v254, 22
	s_ashr_i32 s7, s22, 8
	s_ashr_i32 s98, s22, 8
	s_lshl_b32 s28, s6, 10
	v_add_lshl_u32 v190, v5, v13, 1
	v_mul_lo_u32 v4, v4, s0
	v_lshlrev_b32_e32 v5, 5, v15
	v_sub_u32_e32 v2, v2, v3
	s_mul_i32 s0, s1, 0x2c0000
	v_and_b32_e32 v16, 32, v5
	v_ashrrev_i16_sdwa v2, v233, sext(v2) dst_sel:DWORD dst_unused:UNUSED_PAD src0_sel:DWORD src1_sel:BYTE_0
	s_add_u32 s64, s26, s0
	s_mul_hi_i32 s0, s1, 0x2c0000
	v_or_b32_e32 v4, v4, v16
	v_bfe_i32 v17, v2, 0, 16
	s_addc_u32 s65, s27, s0
	s_add_i32 s29, s28, 0
	v_add_lshl_u32 v192, v4, v17, 1
	s_add_i32 m0, s29, 0x10000
	v_mov_b32_e32 v193, v195
	global_load_lds_dwordx4 v192, s[64:65]
	s_add_i32 m0, s29, 0x12000
	s_add_u32 s0, s64, 0x160000
	global_load_lds_dwordx4 v190, s[64:65]
	s_addc_u32 s1, s65, 0
	s_add_i32 m0, s29, 0x14000
	v_mov_b32_e32 v191, v195
	global_load_lds_dwordx4 v192, s[0:1]
	s_add_i32 m0, s29, 0x16000
	v_lshl_add_u64 v[8:9], s[64:65], 0, v[192:193]
	global_load_lds_dwordx4 v190, s[0:1]
	v_readlane_b32 s0, v254, 20
	s_mov_b32 s10, s0
	s_mul_i32 s0, s0, 0x2c0000
	s_add_u32 s8, s20, s0
	s_mul_hi_i32 s0, s10, 0x2c0000
	s_addc_u32 s9, s21, s0
	s_add_i32 s31, s29, 0x2000
	v_readlane_b32 s1, v254, 21
	s_mov_b32 m0, s29
	s_add_u32 s0, s8, 0x160000
	global_load_lds_dwordx4 v192, s[8:9]
	s_mov_b32 m0, s31
	s_addc_u32 s1, s9, 0
	s_add_i32 s33, s29, 0x4000
	global_load_lds_dwordx4 v190, s[8:9]
	s_mov_b32 m0, s33
	s_add_i32 s43, s29, 0x6000
	global_load_lds_dwordx4 v192, s[0:1]
	s_mov_b32 m0, s43
	s_cmp_eq_u32 s7, 1
	global_load_lds_dwordx4 v190, s[0:1]
	v_lshl_add_u64 v[6:7], s[64:65], 0, v[190:191]
	v_lshl_add_u64 v[2:3], s[8:9], 0, v[192:193]
	s_cselect_b64 s[10:11], -1, 0
	s_cmp_lg_u32 s7, 1
	v_lshl_add_u64 v[4:5], s[8:9], 0, v[190:191]
	s_cbranch_scc1 .LBB0_631
	s_barrier

.Lpeel_disp_down:
	s_cmp_lg_u32 s41, -2
	s_cbranch_scc1 .Llw_main_down
	s_cmp_eq_u32 s98, 0
	s_cbranch_scc1 .Llw_p0_down
	s_add_u32 s64, s8, 0x100
	s_addc_u32 s65, s9, 0
	s_and_b64 s[0:1], s[70:71], exec
	s_cselect_b32 s77, s63, s65
	s_cselect_b32 s76, s62, s64
	s_cselect_b32 s71, s85, s23
	s_cselect_b32 s70, s84, s7
	s_add_i32 s0, 0, 0x10000
	s_add_i32 s18, 0, 0x14000
	v_add_u32_e32 v106, s0, v1
	v_add_u32_e32 v154, s18, v1
	ds_read_b128 v[70:73], v106
	ds_read_b128 v[82:85], v106 offset:1024
	ds_read_b128 v[94:97], v106 offset:2048
	ds_read_b128 v[106:109], v106 offset:3072
	ds_read_b128 v[118:121], v154
	ds_read_b128 v[130:133], v154 offset:1024
	ds_read_b128 v[142:145], v154 offset:2048
	ds_read_b128 v[154:157], v154 offset:3072
	s_add_i32 m0, s29, 0xc000
	ds_read_b128 v[158:161], v237
	ds_read_b128 v[170:173], v237 offset:1024
	ds_read_b128 v[174:177], v237 offset:2048
	ds_read_b128 v[178:181], v237 offset:3072
	ds_read_b128 v[182:185], v237 offset:4096
	ds_read_b128 v[186:189], v237 offset:5120
	ds_read_b128 v[210:213], v237 offset:6144
	ds_read_b128 v[214:217], v237 offset:7168
	global_load_lds_dwordx4 v206, s[8:9]
	s_add_i32 m0, s29, 0xe000
	s_nop 0
	global_load_lds_dwordx4 v208, s[8:9]
	s_waitcnt vmcnt(8)
	s_waitcnt lgkmcnt(0)
	s_barrier
	s_waitcnt lgkmcnt(0)
	v_mfma_f32_16x16x32_bf16 v[166:169], v[70:73], v[158:161], 0
	v_mfma_f32_16x16x32_bf16 v[166:169], v[82:85], v[170:173], v[166:169]
	v_mfma_f32_16x16x32_bf16 v[162:165], v[106:109], v[170:173], 0
	v_mfma_f32_16x16x32_bf16 v[162:165], v[94:97], v[158:161], v[162:165]
	v_mfma_f32_16x16x32_bf16 v[150:153], v[118:121], v[158:161], 0
	v_mfma_f32_16x16x32_bf16 v[150:153], v[130:133], v[170:173], v[150:153]
	v_mfma_f32_16x16x32_bf16 v[146:149], v[154:157], v[170:173], 0
	v_mfma_f32_16x16x32_bf16 v[146:149], v[142:145], v[158:161], v[146:149]
	v_mfma_f32_16x16x32_bf16 v[122:125], v[142:145], v[174:177], 0
	v_mfma_f32_16x16x32_bf16 v[122:125], v[154:157], v[178:181], v[122:125]
	v_mfma_f32_16x16x32_bf16 v[126:129], v[130:133], v[178:181], 0
	v_mfma_f32_16x16x32_bf16 v[126:129], v[118:121], v[174:177], v[126:129]
	v_mfma_f32_16x16x32_bf16 v[134:137], v[94:97], v[174:177], 0
	v_mfma_f32_16x16x32_bf16 v[134:137], v[106:109], v[178:181], v[134:137]
	v_mfma_f32_16x16x32_bf16 v[138:141], v[82:85], v[178:181], 0
	v_mfma_f32_16x16x32_bf16 v[138:141], v[70:73], v[174:177], v[138:141]
	v_mfma_f32_16x16x32_bf16 v[114:117], v[70:73], v[182:185], 0
	v_mfma_f32_16x16x32_bf16 v[114:117], v[82:85], v[186:189], v[114:117]
	v_mfma_f32_16x16x32_bf16 v[110:113], v[106:109], v[186:189], 0
	v_mfma_f32_16x16x32_bf16 v[110:113], v[94:97], v[182:185], v[110:113]
	v_mfma_f32_16x16x32_bf16 v[102:105], v[118:121], v[182:185], 0
	v_mfma_f32_16x16x32_bf16 v[102:105], v[130:133], v[186:189], v[102:105]
	v_mfma_f32_16x16x32_bf16 v[98:101], v[154:157], v[186:189], 0
	v_mfma_f32_16x16x32_bf16 v[98:101], v[142:145], v[182:185], v[98:101]
	v_mfma_f32_16x16x32_bf16 v[74:77], v[142:145], v[210:213], 0
	v_mfma_f32_16x16x32_bf16 v[74:77], v[154:157], v[214:217], v[74:77]
	v_mfma_f32_16x16x32_bf16 v[78:81], v[130:133], v[214:217], 0
	v_mfma_f32_16x16x32_bf16 v[78:81], v[118:121], v[210:213], v[78:81]
	v_mfma_f32_16x16x32_bf16 v[86:89], v[94:97], v[210:213], 0
	v_mfma_f32_16x16x32_bf16 v[86:89], v[106:109], v[214:217], v[86:89]
	v_mfma_f32_16x16x32_bf16 v[90:93], v[82:85], v[214:217], 0
	v_mfma_f32_16x16x32_bf16 v[90:93], v[70:73], v[210:213], v[90:93]
	s_barrier
	s_add_i32 s0, s0, s28
	s_mov_b32 m0, s0
	ds_read_b128 v[158:161], v237 offset:16384
	ds_read_b128 v[170:173], v237 offset:17408
	ds_read_b128 v[174:177], v237 offset:18432
	ds_read_b128 v[178:181], v237 offset:19456
	ds_read_b128 v[182:185], v237 offset:20480
	ds_read_b128 v[186:189], v237 offset:21504
	ds_read_b128 v[210:213], v237 offset:22528
	ds_read_b128 v[214:217], v237 offset:23552
	global_load_lds_dwordx4 v192, s[70:71]
	s_add_i32 m0, s0, 0x2000
	s_add_u32 s0, s70, 0x160000
	s_addc_u32 s1, s71, 0
	s_add_i32 s8, s18, s28
	global_load_lds_dwordx4 v190, s[70:71]
	s_mov_b32 m0, s8
	s_nop 0
	global_load_lds_dwordx4 v192, s[0:1]
	s_add_i32 m0, s8, 0x2000
	s_nop 0
	global_load_lds_dwordx4 v190, s[0:1]
	s_mov_b32 m0, s29
	s_nop 0
	global_load_lds_dwordx4 v192, s[76:77]
	s_mov_b32 m0, s31
	s_nop 0
	global_load_lds_dwordx4 v190, s[76:77]
	s_waitcnt vmcnt(8)
	s_waitcnt lgkmcnt(0)
	s_barrier
	s_waitcnt lgkmcnt(0)
	v_mfma_f32_16x16x32_bf16 v[62:65], v[70:73], v[158:161], 0
	v_mfma_f32_16x16x32_bf16 v[62:65], v[82:85], v[170:173], v[62:65]
	v_mfma_f32_16x16x32_bf16 v[58:61], v[106:109], v[170:173], 0
	v_mfma_f32_16x16x32_bf16 v[58:61], v[94:97], v[158:161], v[58:61]
	v_mfma_f32_16x16x32_bf16 v[54:57], v[118:121], v[158:161], 0
	v_mfma_f32_16x16x32_bf16 v[54:57], v[130:133], v[170:173], v[54:57]
	v_mfma_f32_16x16x32_bf16 v[50:53], v[154:157], v[170:173], 0
	v_mfma_f32_16x16x32_bf16 v[50:53], v[142:145], v[158:161], v[50:53]
	v_mfma_f32_16x16x32_bf16 v[34:37], v[142:145], v[174:177], 0
	v_mfma_f32_16x16x32_bf16 v[34:37], v[154:157], v[178:181], v[34:37]
	v_mfma_f32_16x16x32_bf16 v[38:41], v[130:133], v[178:181], 0
	v_mfma_f32_16x16x32_bf16 v[38:41], v[118:121], v[174:177], v[38:41]
	v_mfma_f32_16x16x32_bf16 v[42:45], v[94:97], v[174:177], 0
	v_mfma_f32_16x16x32_bf16 v[42:45], v[106:109], v[178:181], v[42:45]
	v_mfma_f32_16x16x32_bf16 v[46:49], v[82:85], v[178:181], 0
	v_mfma_f32_16x16x32_bf16 v[46:49], v[70:73], v[174:177], v[46:49]
	v_mfma_f32_16x16x32_bf16 v[30:33], v[70:73], v[182:185], 0
	v_mfma_f32_16x16x32_bf16 v[30:33], v[82:85], v[186:189], v[30:33]
	v_mfma_f32_16x16x32_bf16 v[26:29], v[106:109], v[186:189], 0
	v_mfma_f32_16x16x32_bf16 v[26:29], v[94:97], v[182:185], v[26:29]
	v_mfma_f32_16x16x32_bf16 v[22:25], v[118:121], v[182:185], 0
	v_mfma_f32_16x16x32_bf16 v[22:25], v[130:133], v[186:189], v[22:25]
	v_mfma_f32_16x16x32_bf16 v[18:21], v[154:157], v[186:189], 0
	v_mfma_f32_16x16x32_bf16 v[18:21], v[142:145], v[182:185], v[18:21]
	v_mfma_f32_16x16x32_bf16 v[2:5], v[142:145], v[210:213], 0
	v_mfma_f32_16x16x32_bf16 v[2:5], v[154:157], v[214:217], v[2:5]
	v_mfma_f32_16x16x32_bf16 v[6:9], v[130:133], v[214:217], 0
	v_mfma_f32_16x16x32_bf16 v[6:9], v[118:121], v[210:213], v[6:9]
	v_mfma_f32_16x16x32_bf16 v[10:13], v[94:97], v[210:213], 0
	v_mfma_f32_16x16x32_bf16 v[10:13], v[106:109], v[214:217], v[10:13]
	v_mfma_f32_16x16x32_bf16 v[14:17], v[82:85], v[214:217], 0
	v_mfma_f32_16x16x32_bf16 v[14:17], v[70:73], v[210:213], v[14:17]
	s_barrier
	s_add_i32 s8, 0, 0x18000
	s_add_i32 s9, 0, 0x1c000
	v_add_u32_e32 v106, s8, v1
	v_add_u32_e32 v154, s9, v1
	ds_read_b128 v[70:73], v106
	ds_read_b128 v[82:85], v106 offset:1024
	ds_read_b128 v[94:97], v106 offset:2048
	ds_read_b128 v[106:109], v106 offset:3072
	ds_read_b128 v[118:121], v154
	ds_read_b128 v[130:133], v154 offset:1024
	ds_read_b128 v[142:145], v154 offset:2048
	ds_read_b128 v[154:157], v154 offset:3072
	s_add_u32 s0, s76, 0x160000
	s_addc_u32 s1, s77, 0
	s_mov_b32 m0, s33
	ds_read_b128 v[158:161], v237 offset:32768
	ds_read_b128 v[170:173], v237 offset:33792
	ds_read_b128 v[174:177], v237 offset:34816
	ds_read_b128 v[178:181], v237 offset:35840
	ds_read_b128 v[182:185], v237 offset:36864
	ds_read_b128 v[186:189], v237 offset:37888
	ds_read_b128 v[210:213], v237 offset:38912
	ds_read_b128 v[214:217], v237 offset:39936
	global_load_lds_dwordx4 v192, s[0:1]
	s_mov_b32 m0, s43
	s_nop 0
	global_load_lds_dwordx4 v190, s[0:1]
	s_waitcnt vmcnt(8)
	s_waitcnt lgkmcnt(0)
	s_barrier
	s_waitcnt lgkmcnt(0)
	v_mfma_f32_16x16x32_bf16 v[166:169], v[70:73], v[158:161], v[166:169]
	v_mfma_f32_16x16x32_bf16 v[166:169], v[82:85], v[170:173], v[166:169]
	v_mfma_f32_16x16x32_bf16 v[162:165], v[106:109], v[170:173], v[162:165]
	v_mfma_f32_16x16x32_bf16 v[162:165], v[94:97], v[158:161], v[162:165]
	v_mfma_f32_16x16x32_bf16 v[150:153], v[118:121], v[158:161], v[150:153]
	v_mfma_f32_16x16x32_bf16 v[150:153], v[130:133], v[170:173], v[150:153]
	v_mfma_f32_16x16x32_bf16 v[146:149], v[154:157], v[170:173], v[146:149]
	v_mfma_f32_16x16x32_bf16 v[146:149], v[142:145], v[158:161], v[146:149]
	v_mfma_f32_16x16x32_bf16 v[122:125], v[142:145], v[174:177], v[122:125]
	v_mfma_f32_16x16x32_bf16 v[122:125], v[154:157], v[178:181], v[122:125]
	v_mfma_f32_16x16x32_bf16 v[126:129], v[130:133], v[178:181], v[126:129]
	v_mfma_f32_16x16x32_bf16 v[126:129], v[118:121], v[174:177], v[126:129]
	v_mfma_f32_16x16x32_bf16 v[134:137], v[94:97], v[174:177], v[134:137]
	v_mfma_f32_16x16x32_bf16 v[134:137], v[106:109], v[178:181], v[134:137]
	v_mfma_f32_16x16x32_bf16 v[138:141], v[82:85], v[178:181], v[138:141]
	v_mfma_f32_16x16x32_bf16 v[138:141], v[70:73], v[174:177], v[138:141]
	v_mfma_f32_16x16x32_bf16 v[114:117], v[70:73], v[182:185], v[114:117]
	v_mfma_f32_16x16x32_bf16 v[114:117], v[82:85], v[186:189], v[114:117]
	v_mfma_f32_16x16x32_bf16 v[110:113], v[106:109], v[186:189], v[110:113]
	v_mfma_f32_16x16x32_bf16 v[110:113], v[94:97], v[182:185], v[110:113]
	v_mfma_f32_16x16x32_bf16 v[102:105], v[118:121], v[182:185], v[102:105]
	v_mfma_f32_16x16x32_bf16 v[102:105], v[130:133], v[186:189], v[102:105]
	v_mfma_f32_16x16x32_bf16 v[98:101], v[154:157], v[186:189], v[98:101]
	v_mfma_f32_16x16x32_bf16 v[98:101], v[142:145], v[182:185], v[98:101]
	v_mfma_f32_16x16x32_bf16 v[74:77], v[142:145], v[210:213], v[74:77]
	v_mfma_f32_16x16x32_bf16 v[74:77], v[154:157], v[214:217], v[74:77]
	v_mfma_f32_16x16x32_bf16 v[78:81], v[130:133], v[214:217], v[78:81]
	v_mfma_f32_16x16x32_bf16 v[78:81], v[118:121], v[210:213], v[78:81]
	v_mfma_f32_16x16x32_bf16 v[86:89], v[94:97], v[210:213], v[86:89]
	v_mfma_f32_16x16x32_bf16 v[86:89], v[106:109], v[214:217], v[86:89]
	v_mfma_f32_16x16x32_bf16 v[90:93], v[82:85], v[214:217], v[90:93]
	v_mfma_f32_16x16x32_bf16 v[90:93], v[70:73], v[210:213], v[90:93]
	s_barrier
	s_add_u32 s98, s70, 0x80
	s_addc_u32 s99, s71, 0
	s_add_u32 s100, s76, 0x80
	s_addc_u32 s101, s77, 0
	s_add_i32 s0, s8, s28
	s_mov_b32 m0, s0
	ds_read_b128 v[158:161], v237 offset:49152
	ds_read_b128 v[170:173], v237 offset:50176
	ds_read_b128 v[174:177], v237 offset:51200
	ds_read_b128 v[178:181], v237 offset:52224
	ds_read_b128 v[182:185], v237 offset:53248
	ds_read_b128 v[186:189], v237 offset:54272
	ds_read_b128 v[210:213], v237 offset:55296
	ds_read_b128 v[214:217], v237 offset:56320
	global_load_lds_dwordx4 v192, s[98:99]
	s_add_i32 m0, s0, 0x2000
	s_add_u32 s0, s70, 0x160080
	s_addc_u32 s1, s71, 0
	s_add_i32 s8, s9, s28
	global_load_lds_dwordx4 v190, s[98:99]
	s_mov_b32 m0, s8
	s_nop 0
	global_load_lds_dwordx4 v192, s[0:1]
	s_add_i32 m0, s8, 0x2000
	s_nop 0
	global_load_lds_dwordx4 v190, s[0:1]
	s_mov_b32 m0, s68
	s_nop 0
	global_load_lds_dwordx4 v192, s[100:101]
	s_mov_b32 m0, s79
	s_nop 0
	global_load_lds_dwordx4 v190, s[100:101]
	s_waitcnt vmcnt(8)
	s_waitcnt lgkmcnt(0)
	s_barrier
	s_waitcnt lgkmcnt(0)
	v_mfma_f32_16x16x32_bf16 v[62:65], v[70:73], v[158:161], v[62:65]
	v_mfma_f32_16x16x32_bf16 v[62:65], v[82:85], v[170:173], v[62:65]
	v_mfma_f32_16x16x32_bf16 v[58:61], v[106:109], v[170:173], v[58:61]
	v_mfma_f32_16x16x32_bf16 v[58:61], v[94:97], v[158:161], v[58:61]
	v_mfma_f32_16x16x32_bf16 v[54:57], v[118:121], v[158:161], v[54:57]
	v_mfma_f32_16x16x32_bf16 v[54:57], v[130:133], v[170:173], v[54:57]
	v_mfma_f32_16x16x32_bf16 v[50:53], v[154:157], v[170:173], v[50:53]
	v_mfma_f32_16x16x32_bf16 v[50:53], v[142:145], v[158:161], v[50:53]
	v_mfma_f32_16x16x32_bf16 v[34:37], v[142:145], v[174:177], v[34:37]
	v_mfma_f32_16x16x32_bf16 v[34:37], v[154:157], v[178:181], v[34:37]
	v_mfma_f32_16x16x32_bf16 v[38:41], v[130:133], v[178:181], v[38:41]
	v_mfma_f32_16x16x32_bf16 v[38:41], v[118:121], v[174:177], v[38:41]
	v_mfma_f32_16x16x32_bf16 v[42:45], v[94:97], v[174:177], v[42:45]
	v_mfma_f32_16x16x32_bf16 v[42:45], v[106:109], v[178:181], v[42:45]
	v_mfma_f32_16x16x32_bf16 v[46:49], v[82:85], v[178:181], v[46:49]
	v_mfma_f32_16x16x32_bf16 v[46:49], v[70:73], v[174:177], v[46:49]
	v_mfma_f32_16x16x32_bf16 v[30:33], v[70:73], v[182:185], v[30:33]
	v_mfma_f32_16x16x32_bf16 v[30:33], v[82:85], v[186:189], v[30:33]
	v_mfma_f32_16x16x32_bf16 v[26:29], v[106:109], v[186:189], v[26:29]
	v_mfma_f32_16x16x32_bf16 v[26:29], v[94:97], v[182:185], v[26:29]
	v_mfma_f32_16x16x32_bf16 v[22:25], v[118:121], v[182:185], v[22:25]
	v_mfma_f32_16x16x32_bf16 v[22:25], v[130:133], v[186:189], v[22:25]
	v_mfma_f32_16x16x32_bf16 v[18:21], v[154:157], v[186:189], v[18:21]
	v_mfma_f32_16x16x32_bf16 v[18:21], v[142:145], v[182:185], v[18:21]
	v_mfma_f32_16x16x32_bf16 v[2:5], v[142:145], v[210:213], v[2:5]
	v_mfma_f32_16x16x32_bf16 v[2:5], v[154:157], v[214:217], v[2:5]
	v_mfma_f32_16x16x32_bf16 v[6:9], v[130:133], v[214:217], v[6:9]
	v_mfma_f32_16x16x32_bf16 v[6:9], v[118:121], v[210:213], v[6:9]
	v_mfma_f32_16x16x32_bf16 v[10:13], v[94:97], v[210:213], v[10:13]
	v_mfma_f32_16x16x32_bf16 v[10:13], v[106:109], v[214:217], v[10:13]
	v_mfma_f32_16x16x32_bf16 v[14:17], v[82:85], v[214:217], v[14:17]
	v_mfma_f32_16x16x32_bf16 v[14:17], v[70:73], v[210:213], v[14:17]
	s_barrier
	s_add_i32 s41, s41, 2
	s_add_u32 s7, s7, 0x100
	s_addc_u32 s23, s23, 0
	s_cmpk_gt_u32 s41, 0x55
	s_mov_b64 s[8:9], s[64:65]
	s_cbranch_scc1 .LBB0_648
	s_branch .LBB0_646
.Llw_p0_down:
	s_add_u32 s64, s8, 0x100
	s_addc_u32 s65, s9, 0
	s_and_b64 s[0:1], s[70:71], exec
	s_cselect_b32 s77, s63, s65
	s_cselect_b32 s76, s62, s64
	s_cselect_b32 s71, s85, s23
	s_cselect_b32 s70, s84, s7
	s_add_i32 s0, 0, 0x10000
	s_add_i32 s18, 0, 0x14000
	v_add_u32_e32 v106, s0, v1
	v_add_u32_e32 v154, s18, v1
	ds_read_b128 v[70:73], v106
	ds_read_b128 v[82:85], v106 offset:1024
	ds_read_b128 v[94:97], v106 offset:2048
	ds_read_b128 v[106:109], v106 offset:3072
	ds_read_b128 v[118:121], v154
	ds_read_b128 v[130:133], v154 offset:1024
	ds_read_b128 v[142:145], v154 offset:2048
	ds_read_b128 v[154:157], v154 offset:3072
	s_add_i32 m0, s29, 0xc000
	ds_read_b128 v[158:161], v237
	ds_read_b128 v[170:173], v237 offset:1024
	ds_read_b128 v[174:177], v237 offset:2048
	ds_read_b128 v[178:181], v237 offset:3072
	ds_read_b128 v[182:185], v237 offset:4096
	ds_read_b128 v[186:189], v237 offset:5120
	ds_read_b128 v[210:213], v237 offset:6144
	ds_read_b128 v[214:217], v237 offset:7168
	global_load_lds_dwordx4 v206, s[8:9]
	s_add_i32 m0, s29, 0xe000
	s_nop 0
	global_load_lds_dwordx4 v208, s[8:9]
	s_waitcnt lgkmcnt(0)
	s_barrier
	s_waitcnt lgkmcnt(0)
	v_mfma_f32_16x16x32_bf16 v[166:169], v[70:73], v[158:161], 0
	v_mfma_f32_16x16x32_bf16 v[166:169], v[82:85], v[170:173], v[166:169]
	v_mfma_f32_16x16x32_bf16 v[162:165], v[106:109], v[170:173], 0
	v_mfma_f32_16x16x32_bf16 v[162:165], v[94:97], v[158:161], v[162:165]
	v_mfma_f32_16x16x32_bf16 v[150:153], v[118:121], v[158:161], 0
	v_mfma_f32_16x16x32_bf16 v[150:153], v[130:133], v[170:173], v[150:153]
	v_mfma_f32_16x16x32_bf16 v[146:149], v[154:157], v[170:173], 0
	v_mfma_f32_16x16x32_bf16 v[146:149], v[142:145], v[158:161], v[146:149]
	v_mfma_f32_16x16x32_bf16 v[122:125], v[142:145], v[174:177], 0
	v_mfma_f32_16x16x32_bf16 v[122:125], v[154:157], v[178:181], v[122:125]
	v_mfma_f32_16x16x32_bf16 v[126:129], v[130:133], v[178:181], 0
	v_mfma_f32_16x16x32_bf16 v[126:129], v[118:121], v[174:177], v[126:129]
	v_mfma_f32_16x16x32_bf16 v[134:137], v[94:97], v[174:177], 0
	v_mfma_f32_16x16x32_bf16 v[134:137], v[106:109], v[178:181], v[134:137]
	v_mfma_f32_16x16x32_bf16 v[138:141], v[82:85], v[178:181], 0
	v_mfma_f32_16x16x32_bf16 v[138:141], v[70:73], v[174:177], v[138:141]
	v_mfma_f32_16x16x32_bf16 v[114:117], v[70:73], v[182:185], 0
	v_mfma_f32_16x16x32_bf16 v[114:117], v[82:85], v[186:189], v[114:117]
	v_mfma_f32_16x16x32_bf16 v[110:113], v[106:109], v[186:189], 0
	v_mfma_f32_16x16x32_bf16 v[110:113], v[94:97], v[182:185], v[110:113]
	v_mfma_f32_16x16x32_bf16 v[102:105], v[118:121], v[182:185], 0
	v_mfma_f32_16x16x32_bf16 v[102:105], v[130:133], v[186:189], v[102:105]
	v_mfma_f32_16x16x32_bf16 v[98:101], v[154:157], v[186:189], 0
	v_mfma_f32_16x16x32_bf16 v[98:101], v[142:145], v[182:185], v[98:101]
	v_mfma_f32_16x16x32_bf16 v[74:77], v[142:145], v[210:213], 0
	v_mfma_f32_16x16x32_bf16 v[74:77], v[154:157], v[214:217], v[74:77]
	v_mfma_f32_16x16x32_bf16 v[78:81], v[130:133], v[214:217], 0
	v_mfma_f32_16x16x32_bf16 v[78:81], v[118:121], v[210:213], v[78:81]
	v_mfma_f32_16x16x32_bf16 v[86:89], v[94:97], v[210:213], 0
	v_mfma_f32_16x16x32_bf16 v[86:89], v[106:109], v[214:217], v[86:89]
	v_mfma_f32_16x16x32_bf16 v[90:93], v[82:85], v[214:217], 0
	v_mfma_f32_16x16x32_bf16 v[90:93], v[70:73], v[210:213], v[90:93]
	s_waitcnt vmcnt(8)
	s_barrier
	s_add_i32 s0, s0, s28
	s_mov_b32 m0, s0
	ds_read_b128 v[158:161], v237 offset:16384
	ds_read_b128 v[170:173], v237 offset:17408
	ds_read_b128 v[174:177], v237 offset:18432
	ds_read_b128 v[178:181], v237 offset:19456
	ds_read_b128 v[182:185], v237 offset:20480
	ds_read_b128 v[186:189], v237 offset:21504
	ds_read_b128 v[210:213], v237 offset:22528
	ds_read_b128 v[214:217], v237 offset:23552
	global_load_lds_dwordx4 v192, s[70:71]
	s_add_i32 m0, s0, 0x2000
	s_add_u32 s0, s70, 0x160000
	s_addc_u32 s1, s71, 0
	s_add_i32 s8, s18, s28
	global_load_lds_dwordx4 v190, s[70:71]
	s_mov_b32 m0, s8
	s_nop 0
	global_load_lds_dwordx4 v192, s[0:1]
	s_add_i32 m0, s8, 0x2000
	s_nop 0
	global_load_lds_dwordx4 v190, s[0:1]
	s_mov_b32 m0, s29
	s_nop 0
	global_load_lds_dwordx4 v192, s[76:77]
	s_mov_b32 m0, s31
	s_nop 0
	global_load_lds_dwordx4 v190, s[76:77]
	s_waitcnt lgkmcnt(0)
	s_barrier
	s_waitcnt lgkmcnt(0)
	v_mfma_f32_16x16x32_bf16 v[62:65], v[70:73], v[158:161], 0
	v_mfma_f32_16x16x32_bf16 v[62:65], v[82:85], v[170:173], v[62:65]
	v_mfma_f32_16x16x32_bf16 v[58:61], v[106:109], v[170:173], 0
	v_mfma_f32_16x16x32_bf16 v[58:61], v[94:97], v[158:161], v[58:61]
	v_mfma_f32_16x16x32_bf16 v[54:57], v[118:121], v[158:161], 0
	v_mfma_f32_16x16x32_bf16 v[54:57], v[130:133], v[170:173], v[54:57]
	v_mfma_f32_16x16x32_bf16 v[50:53], v[154:157], v[170:173], 0
	v_mfma_f32_16x16x32_bf16 v[50:53], v[142:145], v[158:161], v[50:53]
	v_mfma_f32_16x16x32_bf16 v[34:37], v[142:145], v[174:177], 0
	v_mfma_f32_16x16x32_bf16 v[34:37], v[154:157], v[178:181], v[34:37]
	v_mfma_f32_16x16x32_bf16 v[38:41], v[130:133], v[178:181], 0
	v_mfma_f32_16x16x32_bf16 v[38:41], v[118:121], v[174:177], v[38:41]
	v_mfma_f32_16x16x32_bf16 v[42:45], v[94:97], v[174:177], 0
	v_mfma_f32_16x16x32_bf16 v[42:45], v[106:109], v[178:181], v[42:45]
	v_mfma_f32_16x16x32_bf16 v[46:49], v[82:85], v[178:181], 0
	v_mfma_f32_16x16x32_bf16 v[46:49], v[70:73], v[174:177], v[46:49]
	v_mfma_f32_16x16x32_bf16 v[30:33], v[70:73], v[182:185], 0
	v_mfma_f32_16x16x32_bf16 v[30:33], v[82:85], v[186:189], v[30:33]
	v_mfma_f32_16x16x32_bf16 v[26:29], v[106:109], v[186:189], 0
	v_mfma_f32_16x16x32_bf16 v[26:29], v[94:97], v[182:185], v[26:29]
	v_mfma_f32_16x16x32_bf16 v[22:25], v[118:121], v[182:185], 0
	v_mfma_f32_16x16x32_bf16 v[22:25], v[130:133], v[186:189], v[22:25]
	v_mfma_f32_16x16x32_bf16 v[18:21], v[154:157], v[186:189], 0
	v_mfma_f32_16x16x32_bf16 v[18:21], v[142:145], v[182:185], v[18:21]
	v_mfma_f32_16x16x32_bf16 v[2:5], v[142:145], v[210:213], 0
	v_mfma_f32_16x16x32_bf16 v[2:5], v[154:157], v[214:217], v[2:5]
	v_mfma_f32_16x16x32_bf16 v[6:9], v[130:133], v[214:217], 0
	v_mfma_f32_16x16x32_bf16 v[6:9], v[118:121], v[210:213], v[6:9]
	v_mfma_f32_16x16x32_bf16 v[10:13], v[94:97], v[210:213], 0
	v_mfma_f32_16x16x32_bf16 v[10:13], v[106:109], v[214:217], v[10:13]
	v_mfma_f32_16x16x32_bf16 v[14:17], v[82:85], v[214:217], 0
	v_mfma_f32_16x16x32_bf16 v[14:17], v[70:73], v[210:213], v[14:17]
	s_waitcnt vmcnt(8)
	s_barrier
	s_add_i32 s8, 0, 0x18000
	s_add_i32 s9, 0, 0x1c000
	v_add_u32_e32 v106, s8, v1
	v_add_u32_e32 v154, s9, v1
	ds_read_b128 v[70:73], v106
	ds_read_b128 v[82:85], v106 offset:1024
	ds_read_b128 v[94:97], v106 offset:2048
	ds_read_b128 v[106:109], v106 offset:3072
	ds_read_b128 v[118:121], v154
	ds_read_b128 v[130:133], v154 offset:1024
	ds_read_b128 v[142:145], v154 offset:2048
	ds_read_b128 v[154:157], v154 offset:3072
	s_add_u32 s0, s76, 0x160000
	s_addc_u32 s1, s77, 0
	s_mov_b32 m0, s33
	ds_read_b128 v[158:161], v237 offset:32768
	ds_read_b128 v[170:173], v237 offset:33792
	ds_read_b128 v[174:177], v237 offset:34816
	ds_read_b128 v[178:181], v237 offset:35840
	ds_read_b128 v[182:185], v237 offset:36864
	ds_read_b128 v[186:189], v237 offset:37888
	ds_read_b128 v[210:213], v237 offset:38912
	ds_read_b128 v[214:217], v237 offset:39936
	global_load_lds_dwordx4 v192, s[0:1]
	s_mov_b32 m0, s43
	s_nop 0
	global_load_lds_dwordx4 v190, s[0:1]
	s_waitcnt lgkmcnt(0)
	s_barrier
	s_waitcnt lgkmcnt(0)
	v_mfma_f32_16x16x32_bf16 v[166:169], v[70:73], v[158:161], v[166:169]
	v_mfma_f32_16x16x32_bf16 v[166:169], v[82:85], v[170:173], v[166:169]
	v_mfma_f32_16x16x32_bf16 v[162:165], v[106:109], v[170:173], v[162:165]
	v_mfma_f32_16x16x32_bf16 v[162:165], v[94:97], v[158:161], v[162:165]
	v_mfma_f32_16x16x32_bf16 v[150:153], v[118:121], v[158:161], v[150:153]
	v_mfma_f32_16x16x32_bf16 v[150:153], v[130:133], v[170:173], v[150:153]
	v_mfma_f32_16x16x32_bf16 v[146:149], v[154:157], v[170:173], v[146:149]
	v_mfma_f32_16x16x32_bf16 v[146:149], v[142:145], v[158:161], v[146:149]
	v_mfma_f32_16x16x32_bf16 v[122:125], v[142:145], v[174:177], v[122:125]
	v_mfma_f32_16x16x32_bf16 v[122:125], v[154:157], v[178:181], v[122:125]
	v_mfma_f32_16x16x32_bf16 v[126:129], v[130:133], v[178:181], v[126:129]
	v_mfma_f32_16x16x32_bf16 v[126:129], v[118:121], v[174:177], v[126:129]
	v_mfma_f32_16x16x32_bf16 v[134:137], v[94:97], v[174:177], v[134:137]
	v_mfma_f32_16x16x32_bf16 v[134:137], v[106:109], v[178:181], v[134:137]
	v_mfma_f32_16x16x32_bf16 v[138:141], v[82:85], v[178:181], v[138:141]
	v_mfma_f32_16x16x32_bf16 v[138:141], v[70:73], v[174:177], v[138:141]
	v_mfma_f32_16x16x32_bf16 v[114:117], v[70:73], v[182:185], v[114:117]
	v_mfma_f32_16x16x32_bf16 v[114:117], v[82:85], v[186:189], v[114:117]
	v_mfma_f32_16x16x32_bf16 v[110:113], v[106:109], v[186:189], v[110:113]
	v_mfma_f32_16x16x32_bf16 v[110:113], v[94:97], v[182:185], v[110:113]
	v_mfma_f32_16x16x32_bf16 v[102:105], v[118:121], v[182:185], v[102:105]
	v_mfma_f32_16x16x32_bf16 v[102:105], v[130:133], v[186:189], v[102:105]
	v_mfma_f32_16x16x32_bf16 v[98:101], v[154:157], v[186:189], v[98:101]
	v_mfma_f32_16x16x32_bf16 v[98:101], v[142:145], v[182:185], v[98:101]
	v_mfma_f32_16x16x32_bf16 v[74:77], v[142:145], v[210:213], v[74:77]
	v_mfma_f32_16x16x32_bf16 v[74:77], v[154:157], v[214:217], v[74:77]
	v_mfma_f32_16x16x32_bf16 v[78:81], v[130:133], v[214:217], v[78:81]
	v_mfma_f32_16x16x32_bf16 v[78:81], v[118:121], v[210:213], v[78:81]
	v_mfma_f32_16x16x32_bf16 v[86:89], v[94:97], v[210:213], v[86:89]
	v_mfma_f32_16x16x32_bf16 v[86:89], v[106:109], v[214:217], v[86:89]
	v_mfma_f32_16x16x32_bf16 v[90:93], v[82:85], v[214:217], v[90:93]
	v_mfma_f32_16x16x32_bf16 v[90:93], v[70:73], v[210:213], v[90:93]
	s_waitcnt vmcnt(8)
	s_barrier
	s_add_u32 s98, s70, 0x80
	s_addc_u32 s99, s71, 0
	s_add_u32 s100, s76, 0x80
	s_addc_u32 s101, s77, 0
	s_add_i32 s0, s8, s28
	s_mov_b32 m0, s0
	ds_read_b128 v[158:161], v237 offset:49152
	ds_read_b128 v[170:173], v237 offset:50176
	ds_read_b128 v[174:177], v237 offset:51200
	ds_read_b128 v[178:181], v237 offset:52224
	ds_read_b128 v[182:185], v237 offset:53248
	ds_read_b128 v[186:189], v237 offset:54272
	ds_read_b128 v[210:213], v237 offset:55296
	ds_read_b128 v[214:217], v237 offset:56320
	global_load_lds_dwordx4 v192, s[98:99]
	s_add_i32 m0, s0, 0x2000
	s_add_u32 s0, s70, 0x160080
	s_addc_u32 s1, s71, 0
	s_add_i32 s8, s9, s28
	global_load_lds_dwordx4 v190, s[98:99]
	s_mov_b32 m0, s8
	s_nop 0
	global_load_lds_dwordx4 v192, s[0:1]
	s_add_i32 m0, s8, 0x2000
	s_nop 0
	global_load_lds_dwordx4 v190, s[0:1]
	s_mov_b32 m0, s68
	s_nop 0
	global_load_lds_dwordx4 v192, s[100:101]
	s_mov_b32 m0, s79
	s_nop 0
	global_load_lds_dwordx4 v190, s[100:101]
	s_waitcnt lgkmcnt(0)
	s_barrier
	s_waitcnt lgkmcnt(0)
	v_mfma_f32_16x16x32_bf16 v[62:65], v[70:73], v[158:161], v[62:65]
	v_mfma_f32_16x16x32_bf16 v[62:65], v[82:85], v[170:173], v[62:65]
	v_mfma_f32_16x16x32_bf16 v[58:61], v[106:109], v[170:173], v[58:61]
	v_mfma_f32_16x16x32_bf16 v[58:61], v[94:97], v[158:161], v[58:61]
	v_mfma_f32_16x16x32_bf16 v[54:57], v[118:121], v[158:161], v[54:57]
	v_mfma_f32_16x16x32_bf16 v[54:57], v[130:133], v[170:173], v[54:57]
	v_mfma_f32_16x16x32_bf16 v[50:53], v[154:157], v[170:173], v[50:53]
	v_mfma_f32_16x16x32_bf16 v[50:53], v[142:145], v[158:161], v[50:53]
	v_mfma_f32_16x16x32_bf16 v[34:37], v[142:145], v[174:177], v[34:37]
	v_mfma_f32_16x16x32_bf16 v[34:37], v[154:157], v[178:181], v[34:37]
	v_mfma_f32_16x16x32_bf16 v[38:41], v[130:133], v[178:181], v[38:41]
	v_mfma_f32_16x16x32_bf16 v[38:41], v[118:121], v[174:177], v[38:41]
	v_mfma_f32_16x16x32_bf16 v[42:45], v[94:97], v[174:177], v[42:45]
	v_mfma_f32_16x16x32_bf16 v[42:45], v[106:109], v[178:181], v[42:45]
	v_mfma_f32_16x16x32_bf16 v[46:49], v[82:85], v[178:181], v[46:49]
	v_mfma_f32_16x16x32_bf16 v[46:49], v[70:73], v[174:177], v[46:49]
	v_mfma_f32_16x16x32_bf16 v[30:33], v[70:73], v[182:185], v[30:33]
	v_mfma_f32_16x16x32_bf16 v[30:33], v[82:85], v[186:189], v[30:33]
	v_mfma_f32_16x16x32_bf16 v[26:29], v[106:109], v[186:189], v[26:29]
	v_mfma_f32_16x16x32_bf16 v[26:29], v[94:97], v[182:185], v[26:29]
	v_mfma_f32_16x16x32_bf16 v[22:25], v[118:121], v[182:185], v[22:25]
	v_mfma_f32_16x16x32_bf16 v[22:25], v[130:133], v[186:189], v[22:25]
	v_mfma_f32_16x16x32_bf16 v[18:21], v[154:157], v[186:189], v[18:21]
	v_mfma_f32_16x16x32_bf16 v[18:21], v[142:145], v[182:185], v[18:21]
	v_mfma_f32_16x16x32_bf16 v[2:5], v[142:145], v[210:213], v[2:5]
	v_mfma_f32_16x16x32_bf16 v[2:5], v[154:157], v[214:217], v[2:5]
	v_mfma_f32_16x16x32_bf16 v[6:9], v[130:133], v[214:217], v[6:9]
	v_mfma_f32_16x16x32_bf16 v[6:9], v[118:121], v[210:213], v[6:9]
	v_mfma_f32_16x16x32_bf16 v[10:13], v[94:97], v[210:213], v[10:13]
	v_mfma_f32_16x16x32_bf16 v[10:13], v[106:109], v[214:217], v[10:13]
	v_mfma_f32_16x16x32_bf16 v[14:17], v[82:85], v[214:217], v[14:17]
	v_mfma_f32_16x16x32_bf16 v[14:17], v[70:73], v[210:213], v[14:17]
	s_waitcnt vmcnt(8)
	s_barrier
	s_add_i32 s41, s41, 2
	s_add_u32 s7, s7, 0x100
	s_addc_u32 s23, s23, 0
	s_cmpk_gt_u32 s41, 0x55
	s_mov_b64 s[8:9], s[64:65]
	s_cbranch_scc1 .LBB0_648
	s_branch .LBB0_646
.Llw_main_down:
	s_cmp_eq_u32 s98, 0
	s_cbranch_scc0 .LBB0_645
	s_add_u32 s64, s8, 0x100
	s_addc_u32 s65, s9, 0
	s_and_b64 s[0:1], s[70:71], exec
	s_cselect_b32 s77, s63, s65
	s_cselect_b32 s76, s62, s64
	s_cselect_b32 s71, s85, s23
	s_cselect_b32 s70, s84, s7
	s_add_i32 s0, 0, 0x10000
	s_add_i32 s18, 0, 0x14000
	v_add_u32_e32 v106, s0, v1
	v_add_u32_e32 v154, s18, v1
	ds_read_b128 v[70:73], v106
	ds_read_b128 v[82:85], v106 offset:1024
	ds_read_b128 v[94:97], v106 offset:2048
	ds_read_b128 v[106:109], v106 offset:3072
	ds_read_b128 v[118:121], v154
	ds_read_b128 v[130:133], v154 offset:1024
	ds_read_b128 v[142:145], v154 offset:2048
	ds_read_b128 v[154:157], v154 offset:3072
	s_add_i32 m0, s29, 0xc000
	ds_read_b128 v[158:161], v237
	ds_read_b128 v[170:173], v237 offset:1024
	ds_read_b128 v[174:177], v237 offset:2048
	ds_read_b128 v[178:181], v237 offset:3072
	ds_read_b128 v[182:185], v237 offset:4096
	ds_read_b128 v[186:189], v237 offset:5120
	ds_read_b128 v[210:213], v237 offset:6144
	ds_read_b128 v[214:217], v237 offset:7168
	global_load_lds_dwordx4 v206, s[8:9]
	s_add_i32 m0, s29, 0xe000
	s_nop 0
	global_load_lds_dwordx4 v208, s[8:9]
	s_waitcnt lgkmcnt(0)
	s_barrier
	s_waitcnt lgkmcnt(0)
	v_mfma_f32_16x16x32_bf16 v[166:169], v[70:73], v[158:161], v[166:169]
	v_mfma_f32_16x16x32_bf16 v[166:169], v[82:85], v[170:173], v[166:169]
	v_mfma_f32_16x16x32_bf16 v[162:165], v[106:109], v[170:173], v[162:165]
	v_mfma_f32_16x16x32_bf16 v[162:165], v[94:97], v[158:161], v[162:165]
	v_mfma_f32_16x16x32_bf16 v[150:153], v[118:121], v[158:161], v[150:153]
	v_mfma_f32_16x16x32_bf16 v[150:153], v[130:133], v[170:173], v[150:153]
	v_mfma_f32_16x16x32_bf16 v[146:149], v[154:157], v[170:173], v[146:149]
	v_mfma_f32_16x16x32_bf16 v[146:149], v[142:145], v[158:161], v[146:149]
	v_mfma_f32_16x16x32_bf16 v[122:125], v[142:145], v[174:177], v[122:125]
	v_mfma_f32_16x16x32_bf16 v[122:125], v[154:157], v[178:181], v[122:125]
	v_mfma_f32_16x16x32_bf16 v[126:129], v[130:133], v[178:181], v[126:129]
	v_mfma_f32_16x16x32_bf16 v[126:129], v[118:121], v[174:177], v[126:129]
	v_mfma_f32_16x16x32_bf16 v[134:137], v[94:97], v[174:177], v[134:137]
	v_mfma_f32_16x16x32_bf16 v[134:137], v[106:109], v[178:181], v[134:137]
	v_mfma_f32_16x16x32_bf16 v[138:141], v[82:85], v[178:181], v[138:141]
	v_mfma_f32_16x16x32_bf16 v[138:141], v[70:73], v[174:177], v[138:141]
	v_mfma_f32_16x16x32_bf16 v[114:117], v[70:73], v[182:185], v[114:117]
	v_mfma_f32_16x16x32_bf16 v[114:117], v[82:85], v[186:189], v[114:117]
	v_mfma_f32_16x16x32_bf16 v[110:113], v[106:109], v[186:189], v[110:113]
	v_mfma_f32_16x16x32_bf16 v[110:113], v[94:97], v[182:185], v[110:113]
	v_mfma_f32_16x16x32_bf16 v[102:105], v[118:121], v[182:185], v[102:105]
	v_mfma_f32_16x16x32_bf16 v[102:105], v[130:133], v[186:189], v[102:105]
	v_mfma_f32_16x16x32_bf16 v[98:101], v[154:157], v[186:189], v[98:101]
	v_mfma_f32_16x16x32_bf16 v[98:101], v[142:145], v[182:185], v[98:101]
	v_mfma_f32_16x16x32_bf16 v[74:77], v[142:145], v[210:213], v[74:77]
	v_mfma_f32_16x16x32_bf16 v[74:77], v[154:157], v[214:217], v[74:77]
	v_mfma_f32_16x16x32_bf16 v[78:81], v[130:133], v[214:217], v[78:81]
	v_mfma_f32_16x16x32_bf16 v[78:81], v[118:121], v[210:213], v[78:81]
	v_mfma_f32_16x16x32_bf16 v[86:89], v[94:97], v[210:213], v[86:89]
	v_mfma_f32_16x16x32_bf16 v[86:89], v[106:109], v[214:217], v[86:89]
	v_mfma_f32_16x16x32_bf16 v[90:93], v[82:85], v[214:217], v[90:93]
	v_mfma_f32_16x16x32_bf16 v[90:93], v[70:73], v[210:213], v[90:93]
	s_waitcnt vmcnt(8)
	s_barrier
	s_add_i32 s0, s0, s28
	s_mov_b32 m0, s0
	ds_read_b128 v[158:161], v237 offset:16384
	ds_read_b128 v[170:173], v237 offset:17408
	ds_read_b128 v[174:177], v237 offset:18432
	ds_read_b128 v[178:181], v237 offset:19456
	ds_read_b128 v[182:185], v237 offset:20480
	ds_read_b128 v[186:189], v237 offset:21504
	ds_read_b128 v[210:213], v237 offset:22528
	ds_read_b128 v[214:217], v237 offset:23552
	global_load_lds_dwordx4 v192, s[70:71]
	s_add_i32 m0, s0, 0x2000
	s_add_u32 s0, s70, 0x160000
	s_addc_u32 s1, s71, 0
	s_add_i32 s8, s18, s28
	global_load_lds_dwordx4 v190, s[70:71]
	s_mov_b32 m0, s8
	s_nop 0
	global_load_lds_dwordx4 v192, s[0:1]
	s_add_i32 m0, s8, 0x2000
	s_nop 0
	global_load_lds_dwordx4 v190, s[0:1]
	s_mov_b32 m0, s29
	s_nop 0
	global_load_lds_dwordx4 v192, s[76:77]
	s_mov_b32 m0, s31
	s_nop 0
	global_load_lds_dwordx4 v190, s[76:77]
	s_waitcnt lgkmcnt(0)
	s_barrier
	s_waitcnt lgkmcnt(0)
	v_mfma_f32_16x16x32_bf16 v[62:65], v[70:73], v[158:161], v[62:65]
	v_mfma_f32_16x16x32_bf16 v[62:65], v[82:85], v[170:173], v[62:65]
	v_mfma_f32_16x16x32_bf16 v[58:61], v[106:109], v[170:173], v[58:61]
	v_mfma_f32_16x16x32_bf16 v[58:61], v[94:97], v[158:161], v[58:61]
	v_mfma_f32_16x16x32_bf16 v[54:57], v[118:121], v[158:161], v[54:57]
	v_mfma_f32_16x16x32_bf16 v[54:57], v[130:133], v[170:173], v[54:57]
	v_mfma_f32_16x16x32_bf16 v[50:53], v[154:157], v[170:173], v[50:53]
	v_mfma_f32_16x16x32_bf16 v[50:53], v[142:145], v[158:161], v[50:53]
	v_mfma_f32_16x16x32_bf16 v[34:37], v[142:145], v[174:177], v[34:37]
	v_mfma_f32_16x16x32_bf16 v[34:37], v[154:157], v[178:181], v[34:37]
	v_mfma_f32_16x16x32_bf16 v[38:41], v[130:133], v[178:181], v[38:41]
	v_mfma_f32_16x16x32_bf16 v[38:41], v[118:121], v[174:177], v[38:41]
	v_mfma_f32_16x16x32_bf16 v[42:45], v[94:97], v[174:177], v[42:45]
	v_mfma_f32_16x16x32_bf16 v[42:45], v[106:109], v[178:181], v[42:45]
	v_mfma_f32_16x16x32_bf16 v[46:49], v[82:85], v[178:181], v[46:49]
	v_mfma_f32_16x16x32_bf16 v[46:49], v[70:73], v[174:177], v[46:49]
	v_mfma_f32_16x16x32_bf16 v[30:33], v[70:73], v[182:185], v[30:33]
	v_mfma_f32_16x16x32_bf16 v[30:33], v[82:85], v[186:189], v[30:33]
	v_mfma_f32_16x16x32_bf16 v[26:29], v[106:109], v[186:189], v[26:29]
	v_mfma_f32_16x16x32_bf16 v[26:29], v[94:97], v[182:185], v[26:29]
	v_mfma_f32_16x16x32_bf16 v[22:25], v[118:121], v[182:185], v[22:25]
	v_mfma_f32_16x16x32_bf16 v[22:25], v[130:133], v[186:189], v[22:25]
	v_mfma_f32_16x16x32_bf16 v[18:21], v[154:157], v[186:189], v[18:21]
	v_mfma_f32_16x16x32_bf16 v[18:21], v[142:145], v[182:185], v[18:21]
	v_mfma_f32_16x16x32_bf16 v[2:5], v[142:145], v[210:213], v[2:5]
	v_mfma_f32_16x16x32_bf16 v[2:5], v[154:157], v[214:217], v[2:5]
	v_mfma_f32_16x16x32_bf16 v[6:9], v[130:133], v[214:217], v[6:9]
	v_mfma_f32_16x16x32_bf16 v[6:9], v[118:121], v[210:213], v[6:9]
	v_mfma_f32_16x16x32_bf16 v[10:13], v[94:97], v[210:213], v[10:13]
	v_mfma_f32_16x16x32_bf16 v[10:13], v[106:109], v[214:217], v[10:13]
	v_mfma_f32_16x16x32_bf16 v[14:17], v[82:85], v[214:217], v[14:17]
	v_mfma_f32_16x16x32_bf16 v[14:17], v[70:73], v[210:213], v[14:17]
	s_waitcnt vmcnt(8)
	s_barrier
	s_add_i32 s8, 0, 0x18000
	s_add_i32 s9, 0, 0x1c000
	v_add_u32_e32 v106, s8, v1
	v_add_u32_e32 v154, s9, v1
	ds_read_b128 v[70:73], v106
	ds_read_b128 v[82:85], v106 offset:1024
	ds_read_b128 v[94:97], v106 offset:2048
	ds_read_b128 v[106:109], v106 offset:3072
	ds_read_b128 v[118:121], v154
	ds_read_b128 v[130:133], v154 offset:1024
	ds_read_b128 v[142:145], v154 offset:2048
	ds_read_b128 v[154:157], v154 offset:3072
	s_add_u32 s0, s76, 0x160000
	s_addc_u32 s1, s77, 0
	s_mov_b32 m0, s33
	ds_read_b128 v[158:161], v237 offset:32768
	ds_read_b128 v[170:173], v237 offset:33792
	ds_read_b128 v[174:177], v237 offset:34816
	ds_read_b128 v[178:181], v237 offset:35840
	ds_read_b128 v[182:185], v237 offset:36864
	ds_read_b128 v[186:189], v237 offset:37888
	ds_read_b128 v[210:213], v237 offset:38912
	ds_read_b128 v[214:217], v237 offset:39936
	global_load_lds_dwordx4 v192, s[0:1]
	s_mov_b32 m0, s43
	s_nop 0
	global_load_lds_dwordx4 v190, s[0:1]
	s_waitcnt lgkmcnt(0)
	s_barrier
	s_waitcnt lgkmcnt(0)
	v_mfma_f32_16x16x32_bf16 v[166:169], v[70:73], v[158:161], v[166:169]
	v_mfma_f32_16x16x32_bf16 v[166:169], v[82:85], v[170:173], v[166:169]
	v_mfma_f32_16x16x32_bf16 v[162:165], v[106:109], v[170:173], v[162:165]
	v_mfma_f32_16x16x32_bf16 v[162:165], v[94:97], v[158:161], v[162:165]
	v_mfma_f32_16x16x32_bf16 v[150:153], v[118:121], v[158:161], v[150:153]
	v_mfma_f32_16x16x32_bf16 v[150:153], v[130:133], v[170:173], v[150:153]
	v_mfma_f32_16x16x32_bf16 v[146:149], v[154:157], v[170:173], v[146:149]
	v_mfma_f32_16x16x32_bf16 v[146:149], v[142:145], v[158:161], v[146:149]
	v_mfma_f32_16x16x32_bf16 v[122:125], v[142:145], v[174:177], v[122:125]
	v_mfma_f32_16x16x32_bf16 v[122:125], v[154:157], v[178:181], v[122:125]
	v_mfma_f32_16x16x32_bf16 v[126:129], v[130:133], v[178:181], v[126:129]
	v_mfma_f32_16x16x32_bf16 v[126:129], v[118:121], v[174:177], v[126:129]
	v_mfma_f32_16x16x32_bf16 v[134:137], v[94:97], v[174:177], v[134:137]
	v_mfma_f32_16x16x32_bf16 v[134:137], v[106:109], v[178:181], v[134:137]
	v_mfma_f32_16x16x32_bf16 v[138:141], v[82:85], v[178:181], v[138:141]
	v_mfma_f32_16x16x32_bf16 v[138:141], v[70:73], v[174:177], v[138:141]
	v_mfma_f32_16x16x32_bf16 v[114:117], v[70:73], v[182:185], v[114:117]
	v_mfma_f32_16x16x32_bf16 v[114:117], v[82:85], v[186:189], v[114:117]
	v_mfma_f32_16x16x32_bf16 v[110:113], v[106:109], v[186:189], v[110:113]
	v_mfma_f32_16x16x32_bf16 v[110:113], v[94:97], v[182:185], v[110:113]
	v_mfma_f32_16x16x32_bf16 v[102:105], v[118:121], v[182:185], v[102:105]
	v_mfma_f32_16x16x32_bf16 v[102:105], v[130:133], v[186:189], v[102:105]
	v_mfma_f32_16x16x32_bf16 v[98:101], v[154:157], v[186:189], v[98:101]
	v_mfma_f32_16x16x32_bf16 v[98:101], v[142:145], v[182:185], v[98:101]
	v_mfma_f32_16x16x32_bf16 v[74:77], v[142:145], v[210:213], v[74:77]
	v_mfma_f32_16x16x32_bf16 v[74:77], v[154:157], v[214:217], v[74:77]
	v_mfma_f32_16x16x32_bf16 v[78:81], v[130:133], v[214:217], v[78:81]
	v_mfma_f32_16x16x32_bf16 v[78:81], v[118:121], v[210:213], v[78:81]
	v_mfma_f32_16x16x32_bf16 v[86:89], v[94:97], v[210:213], v[86:89]
	v_mfma_f32_16x16x32_bf16 v[86:89], v[106:109], v[214:217], v[86:89]
	v_mfma_f32_16x16x32_bf16 v[90:93], v[82:85], v[214:217], v[90:93]
	v_mfma_f32_16x16x32_bf16 v[90:93], v[70:73], v[210:213], v[90:93]
	s_waitcnt vmcnt(8)
	s_barrier
	s_add_u32 s98, s70, 0x80
	s_addc_u32 s99, s71, 0
	s_add_u32 s100, s76, 0x80
	s_addc_u32 s101, s77, 0
	s_add_i32 s0, s8, s28
	s_mov_b32 m0, s0
	ds_read_b128 v[158:161], v237 offset:49152
	ds_read_b128 v[170:173], v237 offset:50176
	ds_read_b128 v[174:177], v237 offset:51200
	ds_read_b128 v[178:181], v237 offset:52224
	ds_read_b128 v[182:185], v237 offset:53248
	ds_read_b128 v[186:189], v237 offset:54272
	ds_read_b128 v[210:213], v237 offset:55296
	ds_read_b128 v[214:217], v237 offset:56320
	global_load_lds_dwordx4 v192, s[98:99]
	s_add_i32 m0, s0, 0x2000
	s_add_u32 s0, s70, 0x160080
	s_addc_u32 s1, s71, 0
	s_add_i32 s8, s9, s28
	global_load_lds_dwordx4 v190, s[98:99]
	s_mov_b32 m0, s8
	s_nop 0
	global_load_lds_dwordx4 v192, s[0:1]
	s_add_i32 m0, s8, 0x2000
	s_nop 0
	global_load_lds_dwordx4 v190, s[0:1]
	s_mov_b32 m0, s68
	s_nop 0
	global_load_lds_dwordx4 v192, s[100:101]
	s_mov_b32 m0, s79
	s_nop 0
	global_load_lds_dwordx4 v190, s[100:101]
	s_waitcnt lgkmcnt(0)
	s_barrier
	s_waitcnt lgkmcnt(0)
	v_mfma_f32_16x16x32_bf16 v[62:65], v[70:73], v[158:161], v[62:65]
	v_mfma_f32_16x16x32_bf16 v[62:65], v[82:85], v[170:173], v[62:65]
	v_mfma_f32_16x16x32_bf16 v[58:61], v[106:109], v[170:173], v[58:61]
	v_mfma_f32_16x16x32_bf16 v[58:61], v[94:97], v[158:161], v[58:61]
	v_mfma_f32_16x16x32_bf16 v[54:57], v[118:121], v[158:161], v[54:57]
	v_mfma_f32_16x16x32_bf16 v[54:57], v[130:133], v[170:173], v[54:57]
	v_mfma_f32_16x16x32_bf16 v[50:53], v[154:157], v[170:173], v[50:53]
	v_mfma_f32_16x16x32_bf16 v[50:53], v[142:145], v[158:161], v[50:53]
	v_mfma_f32_16x16x32_bf16 v[34:37], v[142:145], v[174:177], v[34:37]
	v_mfma_f32_16x16x32_bf16 v[34:37], v[154:157], v[178:181], v[34:37]
	v_mfma_f32_16x16x32_bf16 v[38:41], v[130:133], v[178:181], v[38:41]
	v_mfma_f32_16x16x32_bf16 v[38:41], v[118:121], v[174:177], v[38:41]
	v_mfma_f32_16x16x32_bf16 v[42:45], v[94:97], v[174:177], v[42:45]
	v_mfma_f32_16x16x32_bf16 v[42:45], v[106:109], v[178:181], v[42:45]
	v_mfma_f32_16x16x32_bf16 v[46:49], v[82:85], v[178:181], v[46:49]
	v_mfma_f32_16x16x32_bf16 v[46:49], v[70:73], v[174:177], v[46:49]
	v_mfma_f32_16x16x32_bf16 v[30:33], v[70:73], v[182:185], v[30:33]
	v_mfma_f32_16x16x32_bf16 v[30:33], v[82:85], v[186:189], v[30:33]
	v_mfma_f32_16x16x32_bf16 v[26:29], v[106:109], v[186:189], v[26:29]
	v_mfma_f32_16x16x32_bf16 v[26:29], v[94:97], v[182:185], v[26:29]
	v_mfma_f32_16x16x32_bf16 v[22:25], v[118:121], v[182:185], v[22:25]
	v_mfma_f32_16x16x32_bf16 v[22:25], v[130:133], v[186:189], v[22:25]
	v_mfma_f32_16x16x32_bf16 v[18:21], v[154:157], v[186:189], v[18:21]
	v_mfma_f32_16x16x32_bf16 v[18:21], v[142:145], v[182:185], v[18:21]
	v_mfma_f32_16x16x32_bf16 v[2:5], v[142:145], v[210:213], v[2:5]
	v_mfma_f32_16x16x32_bf16 v[2:5], v[154:157], v[214:217], v[2:5]
	v_mfma_f32_16x16x32_bf16 v[6:9], v[130:133], v[214:217], v[6:9]
	v_mfma_f32_16x16x32_bf16 v[6:9], v[118:121], v[210:213], v[6:9]
	v_mfma_f32_16x16x32_bf16 v[10:13], v[94:97], v[210:213], v[10:13]
	v_mfma_f32_16x16x32_bf16 v[10:13], v[106:109], v[214:217], v[10:13]
	v_mfma_f32_16x16x32_bf16 v[14:17], v[82:85], v[214:217], v[14:17]
	v_mfma_f32_16x16x32_bf16 v[14:17], v[70:73], v[210:213], v[14:17]
	s_waitcnt vmcnt(8)
	s_barrier
	s_add_i32 s41, s41, 2
	s_add_u32 s7, s7, 0x100
	s_addc_u32 s23, s23, 0
	s_cmpk_gt_u32 s41, 0x55
	s_mov_b64 s[8:9], s[64:65]
	s_cbranch_scc1 .LBB0_648
	s_branch .LBB0_646
